# GEMM K-loops: loop counter / tile-pointer SALU moved from behind the last MFMA burst into the DMA-only load section, so the MFMA wave reaches the loop-back barrier right after its last MFMA
# speedup vs baseline: 1.0046x; 1.0046x over previous
; #define PG8_STAGE(bufoff, gbase, voff) do { _Pragma("unroll") for (int _i = 0; _i < 2; ++_i) \
;         __builtin_amdgcn_global_load_lds((const unsigned*)((const char*)(gbase) + (voff)[_i]), (LAS unsigned*)(lds + (bufoff) + ldsw + _i * 8192), 16, 0, 0); } while (0)
; #define PG8_LDA(dst, b, h) do { _Pragma("unroll") for (int m = 0; m < 4; ++m) _Pragma("unroll") for (int k = 0; k < 2; ++k) dst[m][k] = *(const LAS bf16x8*)(lds + PG8_SA(b, h) + aoff + m * 2048 + k * 1024); } while (0)
; #define PG8_WAIT_V(n) asm volatile("s_waitcnt vmcnt(" #n ")" ::: "memory")
; #define PG8_WAIT_L(n) asm volatile("s_waitcnt lgkmcnt(" #n ")" ::: "memory")
; template <class Epi>
; __device__ __forceinline__ void gemm_phase(LAS unsigned char* lds, const Gemm g, const StaticOrder& S, const Epi& E) {
;     ...
;         for (int t = 0; t < nt; t += 2) {
;             const bool last = (t == nt - 2);
;             const char* a1 = cA + (size_t)(t + 1) * kstep;
;             const char* a2 = last ? nA : cA + (size_t)(t + 2) * kstep; const char* b2 = last ? nB : cB + (size_t)(t + 2) * kstep;
;             const char* a3 = a2 + kstep; const char* b3 = b2 + kstep;
;             PG8_LDB(B0, 0, 0); PG8_SCHED; PG8_LDA(At, 0, 0); PG8_STAGE(PG8_SA(1, 1), a1 + hstep, voffA);
;             PG8_WAIT_L(8); PG8_BAR; PG8_WAIT_L(0); PG8_MMA(0, 0, At, B0); PG8_BAR; PG8_SCHED;
;             PG8_LDB(B1, 0, 1); PG8_STAGE(PG8_SB(0, 0), b2, voffB);
;             PG8_BAR; PG8_WAIT_L(0); PG8_MMA(0, 1, At, B1); PG8_BAR;
;             PG8_LDA(At, 0, 1); PG8_STAGE(PG8_SA(0, 0), a2, voffA);
;             PG8_BAR; PG8_WAIT_L(0); PG8_MMA(1, 0, At, B0); PG8_BAR; PG8_SCHED;
;             PG8_STAGE(PG8_SB(0, 1), b2 + hstep, voffB);
;             PG8_WAIT_V(6); PG8_BAR; PG8_MMA(1, 1, At, B1); PG8_BAR;
;             PG8_LDB(B0, 1, 0); PG8_SCHED; PG8_LDA(At, 1, 0); PG8_STAGE(PG8_SA(0, 1), a2 + hstep, voffA);
;             PG8_WAIT_L(8); PG8_BAR; PG8_WAIT_L(0); PG8_MMA(0, 0, At, B0); PG8_BAR; PG8_SCHED;
;             PG8_LDB(B1, 1, 1); PG8_STAGE(PG8_SB(1, 0), b3, voffB);
;             PG8_BAR; PG8_WAIT_L(0); PG8_MMA(0, 1, At, B1); PG8_BAR;
;             PG8_LDA(At, 1, 1); PG8_STAGE(PG8_SA(1, 0), a3, voffA);
;             PG8_BAR; PG8_WAIT_L(0); PG8_MMA(1, 0, At, B0); PG8_BAR; PG8_SCHED;
;             PG8_STAGE(PG8_SB(1, 1), b3 + hstep, voffB);
;             PG8_WAIT_V(6); PG8_BAR; PG8_MMA(1, 1, At, B1); PG8_BAR;
.LBB0_203:
	ds_read_b128 v[144:147], v153
	ds_read_b128 v[160:163], v153 offset:1024
	ds_read_b128 v[164:167], v153 offset:2048
	ds_read_b128 v[168:171], v153 offset:3072
	s_add_u32 s44, s42, 0xfff80080
	s_addc_u32 s45, s43, -1
	s_cmp_eq_u32 s54, 28
	s_cselect_b32 s47, s25, s45
	s_cselect_b32 s46, s50, s44
	s_cselect_b32 s45, s23, s53
	s_cselect_b32 s44, s51, s52
	s_add_i32 m0, s11, 0xc000
	ds_read_b128 v[172:175], v154
	ds_read_b128 v[176:179], v154 offset:1024
	ds_read_b128 v[180:183], v154 offset:2048
	ds_read_b128 v[184:187], v154 offset:3072
	ds_read_b128 v[188:191], v154 offset:4096
	ds_read_b128 v[192:195], v154 offset:5120
	ds_read_b128 v[196:199], v154 offset:6144
	ds_read_b128 v[200:203], v154 offset:7168
	global_load_lds_dwordx4 v136, s[42:43]
	s_add_i32 m0, s11, 0xe000
	s_nop 0
	global_load_lds_dwordx4 v138, s[42:43]
	s_waitcnt lgkmcnt(8)
	s_barrier
	s_waitcnt lgkmcnt(0)
	v_mfma_f32_16x16x32_bf16 v[124:127], v[144:147], v[172:175], v[124:127]
	v_mfma_f32_16x16x32_bf16 v[120:123], v[164:167], v[172:175], v[120:123]
	v_mfma_f32_16x16x32_bf16 v[108:111], v[144:147], v[180:183], v[108:111]
	v_mfma_f32_16x16x32_bf16 v[104:107], v[164:167], v[180:183], v[104:107]
	v_mfma_f32_16x16x32_bf16 v[92:95], v[144:147], v[188:191], v[92:95]
	v_mfma_f32_16x16x32_bf16 v[88:91], v[164:167], v[188:191], v[88:91]
	v_mfma_f32_16x16x32_bf16 v[76:79], v[144:147], v[196:199], v[76:79]
	v_mfma_f32_16x16x32_bf16 v[72:75], v[164:167], v[196:199], v[72:75]
	v_mfma_f32_16x16x32_bf16 v[124:127], v[160:163], v[176:179], v[124:127]
	v_mfma_f32_16x16x32_bf16 v[120:123], v[168:171], v[176:179], v[120:123]
	v_mfma_f32_16x16x32_bf16 v[108:111], v[160:163], v[184:187], v[108:111]
	v_mfma_f32_16x16x32_bf16 v[104:107], v[168:171], v[184:187], v[104:107]
	v_mfma_f32_16x16x32_bf16 v[92:95], v[160:163], v[192:195], v[92:95]
	v_mfma_f32_16x16x32_bf16 v[88:91], v[168:171], v[192:195], v[88:91]
	v_mfma_f32_16x16x32_bf16 v[76:79], v[160:163], v[200:203], v[76:79]
	v_mfma_f32_16x16x32_bf16 v[72:75], v[168:171], v[200:203], v[72:75]
	s_barrier
	s_add_i32 s55, s41, s10
	s_add_u32 s98, s44, s8
	s_addc_u32 s99, s45, s9
	s_mov_b32 m0, s55
	ds_read_b128 v[204:207], v155
	ds_read_b128 v[208:211], v155 offset:1024
	ds_read_b128 v[212:215], v155 offset:2048
	ds_read_b128 v[216:219], v155 offset:3072
	global_load_lds_dwordx4 v132, s[44:45]
	s_add_i32 m0, s55, 0x2000
	s_nop 0
	global_load_lds_dwordx4 v128, s[44:45]
	s_barrier
	s_waitcnt lgkmcnt(0)
	v_mfma_f32_16x16x32_bf16 v[116:119], v[204:207], v[172:175], v[116:119]
	v_mfma_f32_16x16x32_bf16 v[112:115], v[212:215], v[172:175], v[112:115]
	v_mfma_f32_16x16x32_bf16 v[100:103], v[204:207], v[180:183], v[100:103]
	v_mfma_f32_16x16x32_bf16 v[96:99], v[212:215], v[180:183], v[96:99]
	v_mfma_f32_16x16x32_bf16 v[84:87], v[204:207], v[188:191], v[84:87]
	v_mfma_f32_16x16x32_bf16 v[80:83], v[212:215], v[188:191], v[80:83]
	v_mfma_f32_16x16x32_bf16 v[68:71], v[204:207], v[196:199], v[68:71]
	v_mfma_f32_16x16x32_bf16 v[64:67], v[212:215], v[196:199], v[64:67]
	v_mfma_f32_16x16x32_bf16 v[116:119], v[208:211], v[176:179], v[116:119]
	v_mfma_f32_16x16x32_bf16 v[112:115], v[216:219], v[176:179], v[112:115]
	v_mfma_f32_16x16x32_bf16 v[100:103], v[208:211], v[184:187], v[100:103]
	v_mfma_f32_16x16x32_bf16 v[96:99], v[216:219], v[184:187], v[96:99]
	v_mfma_f32_16x16x32_bf16 v[84:87], v[208:211], v[192:195], v[84:87]
	v_mfma_f32_16x16x32_bf16 v[80:83], v[216:219], v[192:195], v[80:83]
	v_mfma_f32_16x16x32_bf16 v[68:71], v[208:211], v[200:203], v[68:71]
	v_mfma_f32_16x16x32_bf16 v[64:67], v[216:219], v[200:203], v[64:67]
	s_mov_b32 m0, s11
	s_add_u32 s100, s46, s8
	s_addc_u32 s101, s47, s9
	s_barrier
	ds_read_b128 v[172:175], v154 offset:16384
	ds_read_b128 v[176:179], v154 offset:17408
	ds_read_b128 v[180:183], v154 offset:18432
	ds_read_b128 v[184:187], v154 offset:19456
	ds_read_b128 v[188:191], v154 offset:20480
	ds_read_b128 v[192:195], v154 offset:21504
	ds_read_b128 v[196:199], v154 offset:22528
	ds_read_b128 v[200:203], v154 offset:23552
	global_load_lds_dwordx4 v134, s[46:47]
	s_mov_b32 m0, s13
	s_nop 0
	global_load_lds_dwordx4 v130, s[46:47]
	s_barrier
	s_waitcnt lgkmcnt(0)
	v_mfma_f32_16x16x32_bf16 v[60:63], v[144:147], v[172:175], v[60:63]
	v_mfma_f32_16x16x32_bf16 v[56:59], v[164:167], v[172:175], v[56:59]
	v_mfma_f32_16x16x32_bf16 v[44:47], v[144:147], v[180:183], v[44:47]
	v_mfma_f32_16x16x32_bf16 v[40:43], v[164:167], v[180:183], v[40:43]
	v_mfma_f32_16x16x32_bf16 v[28:31], v[144:147], v[188:191], v[28:31]
	v_mfma_f32_16x16x32_bf16 v[24:27], v[164:167], v[188:191], v[24:27]
	v_mfma_f32_16x16x32_bf16 v[12:15], v[144:147], v[196:199], v[12:15]
	v_mfma_f32_16x16x32_bf16 v[8:11], v[164:167], v[196:199], v[8:11]
	v_mfma_f32_16x16x32_bf16 v[60:63], v[160:163], v[176:179], v[60:63]
	v_mfma_f32_16x16x32_bf16 v[56:59], v[168:171], v[176:179], v[56:59]
	v_mfma_f32_16x16x32_bf16 v[44:47], v[160:163], v[184:187], v[44:47]
	v_mfma_f32_16x16x32_bf16 v[40:43], v[168:171], v[184:187], v[40:43]
	v_mfma_f32_16x16x32_bf16 v[28:31], v[160:163], v[192:195], v[28:31]
	v_mfma_f32_16x16x32_bf16 v[24:27], v[168:171], v[192:195], v[24:27]
	v_mfma_f32_16x16x32_bf16 v[12:15], v[160:163], v[200:203], v[12:15]
	v_mfma_f32_16x16x32_bf16 v[8:11], v[168:171], v[200:203], v[8:11]
	s_barrier
	s_add_u32 s56, s44, 0x80000
	s_addc_u32 s57, s45, 0
	s_add_i32 s55, s48, s10
	s_mov_b32 m0, s55
	s_nop 0
	global_load_lds_dwordx4 v132, s[56:57]
	s_add_i32 m0, s55, 0x2000
	s_nop 0
	global_load_lds_dwordx4 v128, s[56:57]
	s_waitcnt vmcnt(6)
	s_barrier
; #define PG8_STAGE(bufoff, gbase, voff) do { _Pragma("unroll") for (int _i = 0; _i < 2; ++_i) \
;         __builtin_amdgcn_global_load_lds((const unsigned*)((const char*)(gbase) + (voff)[_i]), (LAS unsigned*)(lds + (bufoff) + ldsw + _i * 8192), 16, 0, 0); } while (0)
; #define PG8_LDA(dst, b, h) do { _Pragma("unroll") for (int m = 0; m < 4; ++m) _Pragma("unroll") for (int k = 0; k < 2; ++k) dst[m][k] = *(const LAS bf16x8*)(lds + PG8_SA(b, h) + aoff + m * 2048 + k * 1024); } while (0)
; #define PG8_LDB(dst, b, h) do { _Pragma("unroll") for (int n = 0; n < 2; ++n) _Pragma("unroll") for (int k = 0; k < 2; ++k) dst[n][k] = *(const LAS bf16x8*)(lds + PG8_SB(b, h) + boff + n * 2048 + k * 1024); } while (0)
; #define PG8_MMA(ai, bj, At, Bt) do { __builtin_amdgcn_s_setprio(1); _Pragma("unroll") for (int m = 0; m < 4; ++m) _Pragma("unroll") for (int n = 0; n < 2; ++n) _Pragma("unroll") for (int k = 0; k < 2; ++k) \
;         acc[ai][bj][m][n] = __builtin_amdgcn_mfma_f32_16x16x32_bf16(Bt[n][k], At[m][k], acc[ai][bj][m][n], 0, 0, 0); __builtin_amdgcn_s_setprio(0); } while (0)
; #define PG8_WAIT_V(n) asm volatile("s_waitcnt vmcnt(" #n ")" ::: "memory")
; #define PG8_WAIT_L(n) asm volatile("s_waitcnt lgkmcnt(" #n ")" ::: "memory")
; #define PG8_BAR __builtin_amdgcn_s_barrier()
; #define PG8_SCHED __builtin_amdgcn_sched_barrier(0)
; template <class Epi>
; __device__ __forceinline__ void gemm_phase(LAS unsigned char* lds, const Gemm g, const StaticOrder& S, const Epi& E) {
;     ...
;             PG8_WAIT_V(6); PG8_BAR; PG8_MMA(1, 1, At, B1); PG8_BAR;
;             PG8_LDB(B0, 1, 0); PG8_SCHED; PG8_LDA(At, 1, 0); PG8_STAGE(PG8_SA(0, 1), a2 + hstep, voffA);
;             PG8_WAIT_L(8); PG8_BAR; PG8_WAIT_L(0); PG8_MMA(0, 0, At, B0); PG8_BAR; PG8_SCHED;
;             PG8_LDB(B1, 1, 1); PG8_STAGE(PG8_SB(1, 0), b3, voffB);
;             PG8_BAR; PG8_WAIT_L(0); PG8_MMA(0, 1, At, B1); PG8_BAR;
;             PG8_LDA(At, 1, 1); PG8_STAGE(PG8_SA(1, 0), a3, voffA);
;             PG8_BAR; PG8_WAIT_L(0); PG8_MMA(1, 0, At, B0); PG8_BAR; PG8_SCHED;
;             PG8_STAGE(PG8_SB(1, 1), b3 + hstep, voffB);
;             PG8_WAIT_V(6); PG8_BAR; PG8_MMA(1, 1, At, B1); PG8_BAR;
	v_mfma_f32_16x16x32_bf16 v[52:55], v[204:207], v[172:175], v[52:55]
	v_mfma_f32_16x16x32_bf16 v[48:51], v[212:215], v[172:175], v[48:51]
	v_mfma_f32_16x16x32_bf16 v[36:39], v[204:207], v[180:183], v[36:39]
	v_mfma_f32_16x16x32_bf16 v[32:35], v[212:215], v[180:183], v[32:35]
	v_mfma_f32_16x16x32_bf16 v[20:23], v[204:207], v[188:191], v[20:23]
	v_mfma_f32_16x16x32_bf16 v[16:19], v[212:215], v[188:191], v[16:19]
	v_mfma_f32_16x16x32_bf16 v[4:7], v[204:207], v[196:199], v[4:7]
	v_mfma_f32_16x16x32_bf16 v[0:3], v[212:215], v[196:199], v[0:3]
	v_mfma_f32_16x16x32_bf16 v[52:55], v[208:211], v[176:179], v[52:55]
	v_mfma_f32_16x16x32_bf16 v[48:51], v[216:219], v[176:179], v[48:51]
	v_mfma_f32_16x16x32_bf16 v[36:39], v[208:211], v[184:187], v[36:39]
	v_mfma_f32_16x16x32_bf16 v[32:35], v[216:219], v[184:187], v[32:35]
	v_mfma_f32_16x16x32_bf16 v[20:23], v[208:211], v[192:195], v[20:23]
	v_mfma_f32_16x16x32_bf16 v[16:19], v[216:219], v[192:195], v[16:19]
	v_mfma_f32_16x16x32_bf16 v[4:7], v[208:211], v[200:203], v[4:7]
	v_mfma_f32_16x16x32_bf16 v[0:3], v[216:219], v[200:203], v[0:3]
	s_add_i32 s55, 0, 0x18000
	v_add_u32_e32 v168, s55, v151
	s_barrier
	ds_read_b128 v[144:147], v168
	ds_read_b128 v[160:163], v168 offset:1024
	ds_read_b128 v[164:167], v168 offset:2048
	ds_read_b128 v[168:171], v168 offset:3072
	s_add_u32 s46, s46, 0x80000
	s_addc_u32 s47, s47, 0
	s_mov_b32 m0, s30
	ds_read_b128 v[172:175], v154 offset:32768
	ds_read_b128 v[176:179], v154 offset:33792
	ds_read_b128 v[180:183], v154 offset:34816
	ds_read_b128 v[184:187], v154 offset:35840
	ds_read_b128 v[188:191], v154 offset:36864
	ds_read_b128 v[192:195], v154 offset:37888
	ds_read_b128 v[196:199], v154 offset:38912
	ds_read_b128 v[200:203], v154 offset:39936
	global_load_lds_dwordx4 v134, s[46:47]
	s_mov_b32 m0, s31
	s_nop 0
	global_load_lds_dwordx4 v130, s[46:47]
	s_waitcnt lgkmcnt(8)
	s_barrier
	s_waitcnt lgkmcnt(0)
	v_mfma_f32_16x16x32_bf16 v[124:127], v[144:147], v[172:175], v[124:127]
	v_mfma_f32_16x16x32_bf16 v[120:123], v[164:167], v[172:175], v[120:123]
	v_mfma_f32_16x16x32_bf16 v[108:111], v[144:147], v[180:183], v[108:111]
	v_mfma_f32_16x16x32_bf16 v[104:107], v[164:167], v[180:183], v[104:107]
	v_mfma_f32_16x16x32_bf16 v[92:95], v[144:147], v[188:191], v[92:95]
	v_mfma_f32_16x16x32_bf16 v[88:91], v[164:167], v[188:191], v[88:91]
	v_mfma_f32_16x16x32_bf16 v[76:79], v[144:147], v[196:199], v[76:79]
	v_mfma_f32_16x16x32_bf16 v[72:75], v[164:167], v[196:199], v[72:75]
	v_mfma_f32_16x16x32_bf16 v[124:127], v[160:163], v[176:179], v[124:127]
	v_mfma_f32_16x16x32_bf16 v[120:123], v[168:171], v[176:179], v[120:123]
	v_mfma_f32_16x16x32_bf16 v[108:111], v[160:163], v[184:187], v[108:111]
	v_mfma_f32_16x16x32_bf16 v[104:107], v[168:171], v[184:187], v[104:107]
	v_mfma_f32_16x16x32_bf16 v[92:95], v[160:163], v[192:195], v[92:95]
	v_mfma_f32_16x16x32_bf16 v[88:91], v[168:171], v[192:195], v[88:91]
	v_mfma_f32_16x16x32_bf16 v[76:79], v[160:163], v[200:203], v[76:79]
	v_mfma_f32_16x16x32_bf16 v[72:75], v[168:171], v[200:203], v[72:75]
	s_barrier
	s_add_i32 s46, 0, 0x1c000
	s_add_i32 s47, s55, s10
	v_add_u32_e32 v216, s46, v151
	s_mov_b32 m0, s47
	ds_read_b128 v[204:207], v216
	ds_read_b128 v[208:211], v216 offset:1024
	ds_read_b128 v[212:215], v216 offset:2048
	ds_read_b128 v[216:219], v216 offset:3072
	global_load_lds_dwordx4 v132, s[98:99]
	s_add_i32 m0, s47, 0x2000
	s_nop 0
	global_load_lds_dwordx4 v128, s[98:99]
	s_barrier
	s_waitcnt lgkmcnt(0)
	v_mfma_f32_16x16x32_bf16 v[116:119], v[204:207], v[172:175], v[116:119]
	v_mfma_f32_16x16x32_bf16 v[112:115], v[212:215], v[172:175], v[112:115]
	v_mfma_f32_16x16x32_bf16 v[100:103], v[204:207], v[180:183], v[100:103]
	v_mfma_f32_16x16x32_bf16 v[96:99], v[212:215], v[180:183], v[96:99]
	v_mfma_f32_16x16x32_bf16 v[84:87], v[204:207], v[188:191], v[84:87]
	v_mfma_f32_16x16x32_bf16 v[80:83], v[212:215], v[188:191], v[80:83]
	v_mfma_f32_16x16x32_bf16 v[68:71], v[204:207], v[196:199], v[68:71]
	v_mfma_f32_16x16x32_bf16 v[64:67], v[212:215], v[196:199], v[64:67]
	v_mfma_f32_16x16x32_bf16 v[116:119], v[208:211], v[176:179], v[116:119]
	v_mfma_f32_16x16x32_bf16 v[112:115], v[216:219], v[176:179], v[112:115]
	v_mfma_f32_16x16x32_bf16 v[100:103], v[208:211], v[184:187], v[100:103]
	v_mfma_f32_16x16x32_bf16 v[96:99], v[216:219], v[184:187], v[96:99]
	v_mfma_f32_16x16x32_bf16 v[84:87], v[208:211], v[192:195], v[84:87]
	v_mfma_f32_16x16x32_bf16 v[80:83], v[216:219], v[192:195], v[80:83]
	v_mfma_f32_16x16x32_bf16 v[68:71], v[208:211], v[200:203], v[68:71]
	v_mfma_f32_16x16x32_bf16 v[64:67], v[216:219], v[200:203], v[64:67]
	s_mov_b32 m0, s36
	s_barrier
	ds_read_b128 v[172:175], v154 offset:49152
	ds_read_b128 v[176:179], v154 offset:50176
	ds_read_b128 v[180:183], v154 offset:51200
	ds_read_b128 v[184:187], v154 offset:52224
	ds_read_b128 v[188:191], v154 offset:53248
	ds_read_b128 v[192:195], v154 offset:54272
	ds_read_b128 v[196:199], v154 offset:55296
	ds_read_b128 v[200:203], v154 offset:56320
	global_load_lds_dwordx4 v134, s[100:101]
	s_mov_b32 m0, s37
	s_nop 0
	global_load_lds_dwordx4 v130, s[100:101]
	s_barrier
; __device__ __forceinline__ float fast_rcp(float x) { return __builtin_amdgcn_rcpf(x); }
; __device__ __forceinline__ float fast_exp2(float x) { return __builtin_amdgcn_exp2f(x); }
; #define PG8_STAGE(bufoff, gbase, voff) do { _Pragma("unroll") for (int _i = 0; _i < 2; ++_i) \
;         __builtin_amdgcn_global_load_lds((const unsigned*)((const char*)(gbase) + (voff)[_i]), (LAS unsigned*)(lds + (bufoff) + ldsw + _i * 8192), 16, 0, 0); } while (0)
; #define PG8_MMA(ai, bj, At, Bt) do { __builtin_amdgcn_s_setprio(1); _Pragma("unroll") for (int m = 0; m < 4; ++m) _Pragma("unroll") for (int n = 0; n < 2; ++n) _Pragma("unroll") for (int k = 0; k < 2; ++k) \
;         acc[ai][bj][m][n] = __builtin_amdgcn_mfma_f32_16x16x32_bf16(Bt[n][k], At[m][k], acc[ai][bj][m][n], 0, 0, 0); __builtin_amdgcn_s_setprio(0); } while (0)
; #define PG8_WAIT_V(n) asm volatile("s_waitcnt vmcnt(" #n ")" ::: "memory")
; #define PG8_BAR __builtin_amdgcn_s_barrier()
; __device__ __forceinline__ u32x4 pack8(f32x4 v0, f32x4 v1) { u32x4 w; w.x = cvt_pk_bf16(v0[0], v0[1]); w.y = cvt_pk_bf16(v0[2], v0[3]); w.z = cvt_pk_bf16(v1[0], v1[1]); w.w = cvt_pk_bf16(v1[2], v1[3]); return w; }
; template <class Epi>
; __device__ __forceinline__ void gemm_phase(LAS unsigned char* lds, const Gemm g, const StaticOrder& S, const Epi& E) {
;     ...
;             PG8_STAGE(PG8_SB(1, 1), b3 + hstep, voffB);
;             PG8_WAIT_V(6); PG8_BAR; PG8_MMA(1, 1, At, B1); PG8_BAR;
;     __device__ __forceinline__ void operator()(const f32x4 (&acc)[2][2][4][2], const Unit& u, int wr, int wc, int fr, int fq) const {
;         const int row0 = u.pm * BM + wr * 64 + fr, col0 = u.pn * HALF + wc * 32 + 8 * fq;
; #pragma unroll
;         for (int ai = 0; ai < 2; ++ai)
; #pragma unroll
;             for (int m = 0; m < 4; ++m) { bf16_t* rowp = O + (size_t)(row0 + ai * HALF + m * 16) * DFF + col0;
;                 const float r = rs[row0 + ai * HALF + m * 16], r2 = r * r;
;                 f32x4 h0, h1;
; #pragma unroll
;                 for (int j = 0; j < 4; ++j) {
;                     const float g0 = acc[ai][0][m][0][j], g1 = acc[ai][0][m][1][j];
;                     h0[j] = g0 * r2 * fast_rcp(1.0f + fast_exp2(g0 * (-LOG2E * r))) * acc[ai][1][m][0][j];
;                     h1[j] = g1 * r2 * fast_rcp(1.0f + fast_exp2(g1 * (-LOG2E * r))) * acc[ai][1][m][1][j]; }
;                 *(u32x4*)rowp = pack8(h0, h1); }
	s_waitcnt lgkmcnt(0)
	v_mfma_f32_16x16x32_bf16 v[60:63], v[144:147], v[172:175], v[60:63]
	v_mfma_f32_16x16x32_bf16 v[56:59], v[164:167], v[172:175], v[56:59]
	v_mfma_f32_16x16x32_bf16 v[44:47], v[144:147], v[180:183], v[44:47]
	v_mfma_f32_16x16x32_bf16 v[40:43], v[164:167], v[180:183], v[40:43]
	v_mfma_f32_16x16x32_bf16 v[28:31], v[144:147], v[188:191], v[28:31]
	v_mfma_f32_16x16x32_bf16 v[24:27], v[164:167], v[188:191], v[24:27]
	v_mfma_f32_16x16x32_bf16 v[12:15], v[144:147], v[196:199], v[12:15]
	v_mfma_f32_16x16x32_bf16 v[8:11], v[164:167], v[196:199], v[8:11]
	v_mfma_f32_16x16x32_bf16 v[60:63], v[160:163], v[176:179], v[60:63]
	v_mfma_f32_16x16x32_bf16 v[56:59], v[168:171], v[176:179], v[56:59]
	v_mfma_f32_16x16x32_bf16 v[44:47], v[160:163], v[184:187], v[44:47]
	v_mfma_f32_16x16x32_bf16 v[40:43], v[168:171], v[184:187], v[40:43]
	v_mfma_f32_16x16x32_bf16 v[28:31], v[160:163], v[192:195], v[28:31]
	v_mfma_f32_16x16x32_bf16 v[24:27], v[168:171], v[192:195], v[24:27]
	v_mfma_f32_16x16x32_bf16 v[12:15], v[160:163], v[200:203], v[12:15]
	v_mfma_f32_16x16x32_bf16 v[8:11], v[168:171], v[200:203], v[8:11]
	s_barrier
	s_add_u32 s44, s44, 0x80080
	s_addc_u32 s45, s45, 0
	s_add_i32 s46, s46, s10
	s_mov_b32 m0, s46
	s_nop 0
	global_load_lds_dwordx4 v132, s[44:45]
	s_add_i32 m0, s46, 0x2000
	s_nop 0
	global_load_lds_dwordx4 v128, s[44:45]
	s_add_i32 s54, s54, 2
	s_add_u32 s42, s42, 0x100
	s_addc_u32 s43, s43, 0
	s_add_u32 s52, s52, 0x100
	s_addc_u32 s53, s53, 0
	s_cmp_gt_u32 s54, 29
	s_waitcnt vmcnt(6)
	s_barrier
	v_mfma_f32_16x16x32_bf16 v[52:55], v[204:207], v[172:175], v[52:55]
	v_mfma_f32_16x16x32_bf16 v[48:51], v[212:215], v[172:175], v[48:51]
	v_mfma_f32_16x16x32_bf16 v[36:39], v[204:207], v[180:183], v[36:39]
	v_mfma_f32_16x16x32_bf16 v[32:35], v[212:215], v[180:183], v[32:35]
	v_mfma_f32_16x16x32_bf16 v[20:23], v[204:207], v[188:191], v[20:23]
	v_mfma_f32_16x16x32_bf16 v[16:19], v[212:215], v[188:191], v[16:19]
	v_mfma_f32_16x16x32_bf16 v[4:7], v[204:207], v[196:199], v[4:7]
	v_mfma_f32_16x16x32_bf16 v[0:3], v[212:215], v[196:199], v[0:3]
	v_mfma_f32_16x16x32_bf16 v[52:55], v[208:211], v[176:179], v[52:55]
	v_mfma_f32_16x16x32_bf16 v[48:51], v[216:219], v[176:179], v[48:51]
	v_mfma_f32_16x16x32_bf16 v[36:39], v[208:211], v[184:187], v[36:39]
	v_mfma_f32_16x16x32_bf16 v[32:35], v[216:219], v[184:187], v[32:35]
	v_mfma_f32_16x16x32_bf16 v[20:23], v[208:211], v[192:195], v[20:23]
	v_mfma_f32_16x16x32_bf16 v[16:19], v[216:219], v[192:195], v[16:19]
	v_mfma_f32_16x16x32_bf16 v[4:7], v[208:211], v[200:203], v[4:7]
	v_mfma_f32_16x16x32_bf16 v[0:3], v[216:219], v[200:203], v[0:3]
	s_barrier
	s_cbranch_scc0 .LBB0_203
	v_lshl_add_u32 v144, s40, 8, v150
	v_ashrrev_i32_e32 v145, 31, v144
	v_lshl_add_u64 v[148:149], v[144:145], 2, s[14:15]
	v_mov_b32_e32 v145, v224
	v_mov_b32_e32 v204, v225
	v_mov_b32_e32 v205, v226
	v_mov_b32_e32 v206, v227
	v_mov_b32_e32 v207, v228
	v_mov_b32_e32 v208, v229
	v_mov_b32_e32 v209, v230
	v_mov_b32_e32 v210, v231
	v_lshl_or_b32 v156, s34, 7, v152
	v_ashrrev_i32_e32 v157, 31, v156
	v_mov_b64_e32 v[146:147], s[20:21]
	v_mad_i64_i32 v[160:161], s[42:43], v144, s49, v[146:147]
	s_and_b64 vcc, exec, s[4:5]
	s_mov_b32 s34, s22
	s_mov_b32 s40, s24
	s_mov_b64 s[44:45], s[28:29]
	v_mul_f32_e32 v162, v145, v145
	v_mul_f32_e32 v145, 0xbfb8aa3b, v145
	v_mul_f32_e32 v163, v124, v162
	v_mul_f32_e32 v124, v124, v145
	v_exp_f32_e32 v124, v124
	s_nop 0
	v_add_f32_e32 v124, 1.0, v124
	v_rcp_f32_e32 v124, v124
	s_nop 0
	v_mul_f32_e32 v124, v163, v124
	v_mul_f32_e32 v116, v116, v124
	v_mul_f32_e32 v124, v120, v162
	v_mul_f32_e32 v120, v120, v145
	v_exp_f32_e32 v120, v120
	s_nop 0
	v_add_f32_e32 v120, 1.0, v120
	v_rcp_f32_e32 v120, v120
	s_nop 0
	v_mul_f32_e32 v120, v124, v120
	v_mul_f32_e32 v124, v125, v145
	v_exp_f32_e32 v124, v124
	v_mul_f32_e32 v120, v112, v120
	v_mul_f32_e32 v112, v125, v162
	v_add_f32_e32 v124, 1.0, v124
	v_rcp_f32_e32 v124, v124
	s_nop 0
	v_mul_f32_e32 v112, v112, v124
	v_mul_f32_e32 v117, v117, v112
	v_mul_f32_e32 v112, v121, v162
	v_mul_f32_e32 v121, v121, v145
	v_exp_f32_e32 v121, v121
	s_nop 0
	v_add_f32_e32 v121, 1.0, v121
	v_rcp_f32_e32 v121, v121
	s_nop 0
	v_mul_f32_e32 v112, v112, v121
	v_mul_f32_e32 v121, v113, v112
	v_mul_f32_e32 v113, v126, v145
	v_exp_f32_e32 v113, v113
	v_mul_f32_e32 v112, v126, v162
	v_add_f32_e32 v113, 1.0, v113
	v_rcp_f32_e32 v113, v113
	s_nop 0
	v_mul_f32_e32 v112, v112, v113
	v_mul_f32_e32 v113, v122, v145
	v_exp_f32_e32 v113, v113
	v_mul_f32_e32 v124, v118, v112
	v_mul_f32_e32 v112, v122, v162
	v_add_f32_e32 v113, 1.0, v113
	v_rcp_f32_e32 v113, v113
	s_nop 0
	v_mul_f32_e32 v112, v112, v113
	v_mul_f32_e32 v113, v127, v145
	v_exp_f32_e32 v113, v113
	v_mul_f32_e32 v122, v114, v112
	v_mul_f32_e32 v112, v127, v162
	v_cvt_pk_bf16_f32 v114, v116, v117
	v_add_f32_e32 v113, 1.0, v113
	v_rcp_f32_e32 v113, v113
	s_nop 0
	v_mul_f32_e32 v112, v112, v113
	v_mul_f32_e32 v113, v123, v145
	v_exp_f32_e32 v113, v113
	v_mul_f32_e32 v125, v119, v112
	v_mul_f32_e32 v112, v123, v162
	v_add_f32_e32 v113, 1.0, v113
	v_rcp_f32_e32 v113, v113
	s_nop 0
	v_mul_f32_e32 v112, v112, v113
	v_mul_f32_e32 v123, v115, v112
	v_lshlrev_b64 v[112:113], 1, v[156:157]
	v_lshl_add_u64 v[118:119], v[160:161], 0, v[112:113]
	v_cvt_pk_bf16_f32 v115, v124, v125
	v_cvt_pk_bf16_f32 v116, v120, v121
	v_cvt_pk_bf16_f32 v117, v122, v123
	global_store_dwordx4 v[118:119], v[114:117], off
	s_nop 1
	v_mov_b32_e32 v116, v204
	s_nop 0
	v_or_b32_e32 v114, 16, v144
	v_mad_i64_i32 v[114:115], s[42:43], v114, s49, v[146:147]
	v_mul_f32_e32 v117, v116, v116
	v_mul_f32_e32 v116, 0xbfb8aa3b, v116
	v_mul_f32_e32 v118, v108, v117
; __device__ __forceinline__ float fast_rcp(float x) { return __builtin_amdgcn_rcpf(x); }
; __device__ __forceinline__ float fast_exp2(float x) { return __builtin_amdgcn_exp2f(x); }
; __device__ __forceinline__ u32x4 pack8(f32x4 v0, f32x4 v1) { u32x4 w; w.x = cvt_pk_bf16(v0[0], v0[1]); w.y = cvt_pk_bf16(v0[2], v0[3]); w.z = cvt_pk_bf16(v1[0], v1[1]); w.w = cvt_pk_bf16(v1[2], v1[3]); return w; }
;     __device__ __forceinline__ void operator()(const f32x4 (&acc)[2][2][4][2], const Unit& u, int wr, int wc, int fr, int fq) const {
;         const int row0 = u.pm * BM + wr * 64 + fr, col0 = u.pn * HALF + wc * 32 + 8 * fq;
; #pragma unroll
;         for (int ai = 0; ai < 2; ++ai)
; #pragma unroll
;             for (int m = 0; m < 4; ++m) { bf16_t* rowp = O + (size_t)(row0 + ai * HALF + m * 16) * DFF + col0;
;                 const float r = rs[row0 + ai * HALF + m * 16], r2 = r * r;
;                 f32x4 h0, h1;
; #pragma unroll
;                 for (int j = 0; j < 4; ++j) {
;                     const float g0 = acc[ai][0][m][0][j], g1 = acc[ai][0][m][1][j];
;                     h0[j] = g0 * r2 * fast_rcp(1.0f + fast_exp2(g0 * (-LOG2E * r))) * acc[ai][1][m][0][j];
;                     h1[j] = g1 * r2 * fast_rcp(1.0f + fast_exp2(g1 * (-LOG2E * r))) * acc[ai][1][m][1][j]; }
;                 *(u32x4*)rowp = pack8(h0, h1); }
	v_mul_f32_e32 v108, v108, v116
	v_exp_f32_e32 v108, v108
	s_nop 0
	v_add_f32_e32 v108, 1.0, v108
	v_rcp_f32_e32 v108, v108
	s_nop 0
	v_mul_f32_e32 v108, v118, v108
	v_mul_f32_e32 v108, v100, v108
	v_mul_f32_e32 v100, v104, v117
	v_mul_f32_e32 v104, v104, v116
	v_exp_f32_e32 v104, v104
	s_nop 0
	v_add_f32_e32 v104, 1.0, v104
	v_rcp_f32_e32 v104, v104
	s_nop 0
	v_mul_f32_e32 v100, v100, v104
	v_mul_f32_e32 v104, v96, v100
	v_mul_f32_e32 v100, v109, v116
	v_exp_f32_e32 v100, v100
	v_mul_f32_e32 v96, v109, v117
	v_add_f32_e32 v100, 1.0, v100
	v_rcp_f32_e32 v100, v100
	s_nop 0
	v_mul_f32_e32 v96, v96, v100
	v_mul_f32_e32 v96, v101, v96
	v_mul_f32_e32 v101, v105, v116
	v_exp_f32_e32 v101, v101
	v_mul_f32_e32 v100, v105, v117
	v_cvt_pk_bf16_f32 v96, v108, v96
	v_add_f32_e32 v101, 1.0, v101
	v_rcp_f32_e32 v101, v101
	s_nop 0
	v_mul_f32_e32 v100, v100, v101
	v_mul_f32_e32 v105, v97, v100
	v_mul_f32_e32 v100, v110, v116
	v_exp_f32_e32 v100, v100
	v_mul_f32_e32 v101, v106, v116
	v_exp_f32_e32 v101, v101
	v_mul_f32_e32 v97, v110, v117
	v_add_f32_e32 v100, 1.0, v100
	v_rcp_f32_e32 v100, v100
	v_add_f32_e32 v101, 1.0, v101
	v_rcp_f32_e32 v101, v101
	v_mul_f32_e32 v97, v97, v100
	v_mul_f32_e32 v100, v106, v117
	v_mul_f32_e32 v100, v100, v101
	v_mul_f32_e32 v97, v102, v97
	v_mul_f32_e32 v102, v98, v100
	v_mul_f32_e32 v100, v111, v116
	v_exp_f32_e32 v100, v100
	v_mul_f32_e32 v101, v107, v116
	v_exp_f32_e32 v101, v101
	v_mul_f32_e32 v98, v111, v117
	v_add_f32_e32 v100, 1.0, v100
	v_rcp_f32_e32 v100, v100
	v_add_f32_e32 v101, 1.0, v101
	v_rcp_f32_e32 v101, v101
	v_mul_f32_e32 v98, v98, v100
	v_mul_f32_e32 v100, v107, v117
	v_mul_f32_e32 v100, v100, v101
	v_mul_f32_e32 v98, v103, v98
	v_mul_f32_e32 v99, v99, v100
	v_lshl_add_u64 v[100:101], v[114:115], 0, v[112:113]
	v_cvt_pk_bf16_f32 v97, v97, v98
	v_cvt_pk_bf16_f32 v98, v104, v105
	v_cvt_pk_bf16_f32 v99, v102, v99
	global_store_dwordx4 v[100:101], v[96:99], off
	s_nop 1
	v_mov_b32_e32 v98, v205
	s_nop 0
	v_or_b32_e32 v96, 32, v144
	v_mad_i64_i32 v[96:97], s[42:43], v96, s49, v[146:147]
	v_mul_f32_e32 v99, v98, v98
	v_mul_f32_e32 v98, 0xbfb8aa3b, v98
	v_mul_f32_e32 v100, v92, v99
	v_mul_f32_e32 v92, v92, v98
	v_exp_f32_e32 v92, v92
	s_nop 0
	v_add_f32_e32 v92, 1.0, v92
	v_rcp_f32_e32 v92, v92
	s_nop 0
	v_mul_f32_e32 v92, v100, v92
	v_mul_f32_e32 v92, v84, v92
	v_mul_f32_e32 v84, v88, v99
	v_mul_f32_e32 v88, v88, v98
	v_exp_f32_e32 v88, v88
	s_nop 0
	v_add_f32_e32 v88, 1.0, v88
	v_rcp_f32_e32 v88, v88
	s_nop 0
	v_mul_f32_e32 v84, v84, v88
	v_mul_f32_e32 v88, v80, v84
	v_mul_f32_e32 v84, v93, v98
	v_exp_f32_e32 v84, v84
	v_mul_f32_e32 v80, v93, v99
	v_add_f32_e32 v84, 1.0, v84
	v_rcp_f32_e32 v84, v84
	s_nop 0
	v_mul_f32_e32 v80, v80, v84
	v_mul_f32_e32 v80, v85, v80
	v_mul_f32_e32 v85, v89, v98
	v_exp_f32_e32 v85, v85
	v_mul_f32_e32 v84, v89, v99
	v_cvt_pk_bf16_f32 v80, v92, v80
	v_add_f32_e32 v85, 1.0, v85
	v_rcp_f32_e32 v85, v85
	s_nop 0
	v_mul_f32_e32 v84, v84, v85
	v_mul_f32_e32 v89, v81, v84
	v_mul_f32_e32 v84, v94, v98
	v_exp_f32_e32 v84, v84
	v_mul_f32_e32 v85, v90, v98
	v_exp_f32_e32 v85, v85
	v_mul_f32_e32 v81, v94, v99
	v_add_f32_e32 v84, 1.0, v84
	v_rcp_f32_e32 v84, v84
	v_add_f32_e32 v85, 1.0, v85
	v_rcp_f32_e32 v85, v85
	v_mul_f32_e32 v81, v81, v84
	v_mul_f32_e32 v84, v90, v99
	v_mul_f32_e32 v84, v84, v85
	v_mul_f32_e32 v81, v86, v81
	v_mul_f32_e32 v86, v82, v84
	v_mul_f32_e32 v84, v95, v98
	v_exp_f32_e32 v84, v84
	v_mul_f32_e32 v85, v91, v98
	v_exp_f32_e32 v85, v85
	v_mul_f32_e32 v82, v95, v99
	v_add_f32_e32 v84, 1.0, v84
	v_rcp_f32_e32 v84, v84
	v_add_f32_e32 v85, 1.0, v85
	v_rcp_f32_e32 v85, v85
	v_mul_f32_e32 v82, v82, v84
	v_mul_f32_e32 v84, v91, v99
	v_mul_f32_e32 v84, v84, v85
	v_mul_f32_e32 v82, v87, v82
	v_mul_f32_e32 v83, v83, v84
	v_lshl_add_u64 v[84:85], v[96:97], 0, v[112:113]
	v_cvt_pk_bf16_f32 v81, v81, v82
	v_cvt_pk_bf16_f32 v82, v88, v89
	v_cvt_pk_bf16_f32 v83, v86, v83
	global_store_dwordx4 v[84:85], v[80:83], off
	s_nop 1
	v_mov_b32_e32 v82, v206
	s_nop 0
	v_or_b32_e32 v80, 48, v144
	v_mad_i64_i32 v[80:81], s[42:43], v80, s49, v[146:147]
	v_mul_f32_e32 v83, v82, v82
	v_mul_f32_e32 v82, 0xbfb8aa3b, v82
	v_mul_f32_e32 v84, v76, v83
	v_mul_f32_e32 v76, v76, v82
	v_exp_f32_e32 v76, v76
	s_nop 0
	v_add_f32_e32 v76, 1.0, v76
	v_rcp_f32_e32 v76, v76
	s_nop 0
	v_mul_f32_e32 v76, v84, v76
	v_mul_f32_e32 v76, v68, v76
	v_mul_f32_e32 v68, v72, v83
	v_mul_f32_e32 v72, v72, v82
	v_exp_f32_e32 v72, v72
	s_nop 0
	v_add_f32_e32 v72, 1.0, v72
	v_rcp_f32_e32 v72, v72
	s_nop 0
	v_mul_f32_e32 v68, v68, v72
	v_mul_f32_e32 v72, v64, v68
	v_mul_f32_e32 v68, v77, v82
	v_exp_f32_e32 v68, v68
	v_mul_f32_e32 v64, v77, v83
	v_add_f32_e32 v68, 1.0, v68
	v_rcp_f32_e32 v68, v68
	s_nop 0
	v_mul_f32_e32 v64, v64, v68
	v_mul_f32_e32 v64, v69, v64
	v_mul_f32_e32 v69, v73, v82
	v_exp_f32_e32 v69, v69
	v_mul_f32_e32 v68, v73, v83
	v_cvt_pk_bf16_f32 v64, v76, v64
	v_add_f32_e32 v69, 1.0, v69
	v_rcp_f32_e32 v69, v69
	s_nop 0
	v_mul_f32_e32 v68, v68, v69
	v_mul_f32_e32 v73, v65, v68
	v_mul_f32_e32 v68, v78, v82
	v_exp_f32_e32 v68, v68
	v_mul_f32_e32 v69, v74, v82
	v_exp_f32_e32 v69, v69
	v_mul_f32_e32 v65, v78, v83
	v_add_f32_e32 v68, 1.0, v68
	v_rcp_f32_e32 v68, v68
	v_add_f32_e32 v69, 1.0, v69
	v_rcp_f32_e32 v69, v69
	v_mul_f32_e32 v65, v65, v68
	v_mul_f32_e32 v68, v74, v83
	v_mul_f32_e32 v68, v68, v69
	v_mul_f32_e32 v65, v70, v65
	v_mul_f32_e32 v70, v66, v68
	v_mul_f32_e32 v68, v79, v82
	v_exp_f32_e32 v68, v68
	v_mul_f32_e32 v69, v75, v82
	v_exp_f32_e32 v69, v69
	v_mul_f32_e32 v66, v79, v83
	v_add_f32_e32 v68, 1.0, v68
	v_rcp_f32_e32 v68, v68
	v_add_f32_e32 v69, 1.0, v69
	v_rcp_f32_e32 v69, v69
; __device__ __forceinline__ float fast_rcp(float x) { return __builtin_amdgcn_rcpf(x); }
; __device__ __forceinline__ float fast_exp2(float x) { return __builtin_amdgcn_exp2f(x); }
; __device__ __forceinline__ u32x4 pack8(f32x4 v0, f32x4 v1) { u32x4 w; w.x = cvt_pk_bf16(v0[0], v0[1]); w.y = cvt_pk_bf16(v0[2], v0[3]); w.z = cvt_pk_bf16(v1[0], v1[1]); w.w = cvt_pk_bf16(v1[2], v1[3]); return w; }
;     __device__ __forceinline__ void operator()(const f32x4 (&acc)[2][2][4][2], const Unit& u, int wr, int wc, int fr, int fq) const {
;         const int row0 = u.pm * BM + wr * 64 + fr, col0 = u.pn * HALF + wc * 32 + 8 * fq;
; #pragma unroll
;         for (int ai = 0; ai < 2; ++ai)
; #pragma unroll
;             for (int m = 0; m < 4; ++m) { bf16_t* rowp = O + (size_t)(row0 + ai * HALF + m * 16) * DFF + col0;
;                 const float r = rs[row0 + ai * HALF + m * 16], r2 = r * r;
;                 f32x4 h0, h1;
; #pragma unroll
;                 for (int j = 0; j < 4; ++j) {
;                     const float g0 = acc[ai][0][m][0][j], g1 = acc[ai][0][m][1][j];
;                     h0[j] = g0 * r2 * fast_rcp(1.0f + fast_exp2(g0 * (-LOG2E * r))) * acc[ai][1][m][0][j];
;                     h1[j] = g1 * r2 * fast_rcp(1.0f + fast_exp2(g1 * (-LOG2E * r))) * acc[ai][1][m][1][j]; }
;                 *(u32x4*)rowp = pack8(h0, h1); }
	v_mul_f32_e32 v66, v66, v68
	v_mul_f32_e32 v68, v75, v83
	v_mul_f32_e32 v68, v68, v69
	v_mul_f32_e32 v66, v71, v66
	v_mul_f32_e32 v67, v67, v68
	v_lshl_add_u64 v[68:69], v[80:81], 0, v[112:113]
	v_cvt_pk_bf16_f32 v65, v65, v66
	v_cvt_pk_bf16_f32 v66, v72, v73
	v_cvt_pk_bf16_f32 v67, v70, v67
	global_store_dwordx4 v[68:69], v[64:67], off
	s_nop 1
	v_mov_b32_e32 v66, v207
	s_nop 0
	v_add_u32_e32 v64, 0x80, v144
	v_mad_i64_i32 v[64:65], s[42:43], v64, s49, v[146:147]
	v_mul_f32_e32 v67, v66, v66
	v_mul_f32_e32 v66, 0xbfb8aa3b, v66
	v_mul_f32_e32 v68, v60, v67
	v_mul_f32_e32 v60, v60, v66
	v_exp_f32_e32 v60, v60
	s_nop 0
	v_add_f32_e32 v60, 1.0, v60
	v_rcp_f32_e32 v60, v60
	s_nop 0
	v_mul_f32_e32 v60, v68, v60
	v_mul_f32_e32 v60, v52, v60
	v_mul_f32_e32 v52, v56, v67
	v_mul_f32_e32 v56, v56, v66
	v_exp_f32_e32 v56, v56
	s_nop 0
	v_add_f32_e32 v56, 1.0, v56
	v_rcp_f32_e32 v56, v56
	s_nop 0
	v_mul_f32_e32 v52, v52, v56
	v_mul_f32_e32 v56, v48, v52
	v_mul_f32_e32 v52, v61, v66
	v_exp_f32_e32 v52, v52
	v_mul_f32_e32 v48, v61, v67
	v_add_f32_e32 v52, 1.0, v52
	v_rcp_f32_e32 v52, v52
	s_nop 0
	v_mul_f32_e32 v48, v48, v52
	v_mul_f32_e32 v48, v53, v48
	v_mul_f32_e32 v53, v57, v66
	v_exp_f32_e32 v53, v53
	v_mul_f32_e32 v52, v57, v67
	v_cvt_pk_bf16_f32 v48, v60, v48
	v_add_f32_e32 v53, 1.0, v53
	v_rcp_f32_e32 v53, v53
	s_nop 0
	v_mul_f32_e32 v52, v52, v53
	v_mul_f32_e32 v57, v49, v52
	v_mul_f32_e32 v52, v62, v66
	v_exp_f32_e32 v52, v52
	v_mul_f32_e32 v53, v58, v66
	v_exp_f32_e32 v53, v53
	v_mul_f32_e32 v49, v62, v67
	v_add_f32_e32 v52, 1.0, v52
	v_rcp_f32_e32 v52, v52
	v_add_f32_e32 v53, 1.0, v53
	v_rcp_f32_e32 v53, v53
	v_mul_f32_e32 v49, v49, v52
	v_mul_f32_e32 v52, v58, v67
	v_mul_f32_e32 v52, v52, v53
	v_mul_f32_e32 v49, v54, v49
	v_mul_f32_e32 v54, v50, v52
	v_mul_f32_e32 v52, v63, v66
	v_exp_f32_e32 v52, v52
	v_mul_f32_e32 v53, v59, v66
	v_exp_f32_e32 v53, v53
	v_mul_f32_e32 v50, v63, v67
	v_add_f32_e32 v52, 1.0, v52
	v_rcp_f32_e32 v52, v52
	v_add_f32_e32 v53, 1.0, v53
	v_rcp_f32_e32 v53, v53
	v_mul_f32_e32 v50, v50, v52
	v_mul_f32_e32 v52, v59, v67
	v_mul_f32_e32 v52, v52, v53
	v_mul_f32_e32 v50, v55, v50
	v_mul_f32_e32 v51, v51, v52
	v_lshl_add_u64 v[52:53], v[64:65], 0, v[112:113]
	v_cvt_pk_bf16_f32 v49, v49, v50
	v_cvt_pk_bf16_f32 v50, v56, v57
	v_cvt_pk_bf16_f32 v51, v54, v51
	global_store_dwordx4 v[52:53], v[48:51], off
	s_nop 1
	v_mov_b32_e32 v50, v208
	s_nop 0
	v_add_u32_e32 v48, 0x90, v144
	v_mad_i64_i32 v[48:49], s[42:43], v48, s49, v[146:147]
	v_mul_f32_e32 v51, v50, v50
	v_mul_f32_e32 v50, 0xbfb8aa3b, v50
	v_mul_f32_e32 v52, v44, v51
	v_mul_f32_e32 v44, v44, v50
	v_exp_f32_e32 v44, v44
	s_nop 0
	v_add_f32_e32 v44, 1.0, v44
	v_rcp_f32_e32 v44, v44
	s_nop 0
	v_mul_f32_e32 v44, v52, v44
	v_mul_f32_e32 v44, v36, v44
	v_mul_f32_e32 v36, v40, v51
	v_mul_f32_e32 v40, v40, v50
	v_exp_f32_e32 v40, v40
	s_nop 0
	v_add_f32_e32 v40, 1.0, v40
	v_rcp_f32_e32 v40, v40
	s_nop 0
	v_mul_f32_e32 v36, v36, v40
	v_mul_f32_e32 v40, v32, v36
	v_mul_f32_e32 v36, v45, v50
	v_exp_f32_e32 v36, v36
	v_mul_f32_e32 v32, v45, v51
	v_add_f32_e32 v36, 1.0, v36
	v_rcp_f32_e32 v36, v36
	s_nop 0
	v_mul_f32_e32 v32, v32, v36
	v_mul_f32_e32 v32, v37, v32
	v_mul_f32_e32 v37, v41, v50
	v_exp_f32_e32 v37, v37
	v_mul_f32_e32 v36, v41, v51
	v_cvt_pk_bf16_f32 v32, v44, v32
	v_add_f32_e32 v37, 1.0, v37
	v_rcp_f32_e32 v37, v37
	s_nop 0
	v_mul_f32_e32 v36, v36, v37
	v_mul_f32_e32 v41, v33, v36
	v_mul_f32_e32 v36, v46, v50
	v_exp_f32_e32 v36, v36
	v_mul_f32_e32 v37, v42, v50
	v_exp_f32_e32 v37, v37
	v_mul_f32_e32 v33, v46, v51
	v_add_f32_e32 v36, 1.0, v36
	v_rcp_f32_e32 v36, v36
	v_add_f32_e32 v37, 1.0, v37
	v_rcp_f32_e32 v37, v37
	v_mul_f32_e32 v33, v33, v36
	v_mul_f32_e32 v36, v42, v51
	v_mul_f32_e32 v36, v36, v37
	v_mul_f32_e32 v33, v38, v33
	v_mul_f32_e32 v38, v34, v36
	v_mul_f32_e32 v36, v47, v50
	v_exp_f32_e32 v36, v36
	v_mul_f32_e32 v37, v43, v50
	v_exp_f32_e32 v37, v37
	v_mul_f32_e32 v34, v47, v51
	v_add_f32_e32 v36, 1.0, v36
	v_rcp_f32_e32 v36, v36
	v_add_f32_e32 v37, 1.0, v37
	v_rcp_f32_e32 v37, v37
	v_mul_f32_e32 v34, v34, v36
	v_mul_f32_e32 v36, v43, v51
	v_mul_f32_e32 v36, v36, v37
	v_mul_f32_e32 v34, v39, v34
	v_mul_f32_e32 v35, v35, v36
	v_lshl_add_u64 v[36:37], v[48:49], 0, v[112:113]
; __device__ __forceinline__ float fast_rcp(float x) { return __builtin_amdgcn_rcpf(x); }
; __device__ __forceinline__ float fast_exp2(float x) { return __builtin_amdgcn_exp2f(x); }
; __device__ __forceinline__ u32x4 pack8(f32x4 v0, f32x4 v1) { u32x4 w; w.x = cvt_pk_bf16(v0[0], v0[1]); w.y = cvt_pk_bf16(v0[2], v0[3]); w.z = cvt_pk_bf16(v1[0], v1[1]); w.w = cvt_pk_bf16(v1[2], v1[3]); return w; }
;     __device__ __forceinline__ void operator()(const f32x4 (&acc)[2][2][4][2], const Unit& u, int wr, int wc, int fr, int fq) const {
;         const int row0 = u.pm * BM + wr * 64 + fr, col0 = u.pn * HALF + wc * 32 + 8 * fq;
; #pragma unroll
;         for (int ai = 0; ai < 2; ++ai)
; #pragma unroll
;             for (int m = 0; m < 4; ++m) { bf16_t* rowp = O + (size_t)(row0 + ai * HALF + m * 16) * DFF + col0;
;                 const float r = rs[row0 + ai * HALF + m * 16], r2 = r * r;
;                 f32x4 h0, h1;
; #pragma unroll
;                 for (int j = 0; j < 4; ++j) {
;                     const float g0 = acc[ai][0][m][0][j], g1 = acc[ai][0][m][1][j];
;                     h0[j] = g0 * r2 * fast_rcp(1.0f + fast_exp2(g0 * (-LOG2E * r))) * acc[ai][1][m][0][j];
;                     h1[j] = g1 * r2 * fast_rcp(1.0f + fast_exp2(g1 * (-LOG2E * r))) * acc[ai][1][m][1][j]; }
;                 *(u32x4*)rowp = pack8(h0, h1); }
	v_cvt_pk_bf16_f32 v33, v33, v34
	v_cvt_pk_bf16_f32 v34, v40, v41
	v_cvt_pk_bf16_f32 v35, v38, v35
	global_store_dwordx4 v[36:37], v[32:35], off
	s_nop 1
	v_mov_b32_e32 v34, v209
	s_nop 0
	v_add_u32_e32 v32, 0xa0, v144
	v_mad_i64_i32 v[32:33], s[42:43], v32, s49, v[146:147]
	v_mul_f32_e32 v35, v34, v34
	v_mul_f32_e32 v34, 0xbfb8aa3b, v34
	v_mul_f32_e32 v36, v28, v35
	v_mul_f32_e32 v28, v28, v34
	v_exp_f32_e32 v28, v28
	s_nop 0
	v_add_f32_e32 v28, 1.0, v28
	v_rcp_f32_e32 v28, v28
	s_nop 0
	v_mul_f32_e32 v28, v36, v28
	v_mul_f32_e32 v28, v20, v28
	v_mul_f32_e32 v20, v24, v35
	v_mul_f32_e32 v24, v24, v34
	v_exp_f32_e32 v24, v24
	s_nop 0
	v_add_f32_e32 v24, 1.0, v24
	v_rcp_f32_e32 v24, v24
	s_nop 0
	v_mul_f32_e32 v20, v20, v24
	v_mul_f32_e32 v24, v16, v20
	v_mul_f32_e32 v20, v29, v34
	v_exp_f32_e32 v20, v20
	v_mul_f32_e32 v16, v29, v35
	v_add_f32_e32 v20, 1.0, v20
	v_rcp_f32_e32 v20, v20
	s_nop 0
	v_mul_f32_e32 v16, v16, v20
	v_mul_f32_e32 v16, v21, v16
	v_mul_f32_e32 v21, v25, v34
	v_exp_f32_e32 v21, v21
	v_mul_f32_e32 v20, v25, v35
	v_cvt_pk_bf16_f32 v16, v28, v16
	v_add_f32_e32 v21, 1.0, v21
	v_rcp_f32_e32 v21, v21
	s_nop 0
	v_mul_f32_e32 v20, v20, v21
	v_mul_f32_e32 v25, v17, v20
	v_mul_f32_e32 v20, v30, v34
	v_exp_f32_e32 v20, v20
	v_mul_f32_e32 v21, v26, v34
	v_exp_f32_e32 v21, v21
	v_mul_f32_e32 v17, v30, v35
	v_add_f32_e32 v20, 1.0, v20
	v_rcp_f32_e32 v20, v20
	v_add_f32_e32 v21, 1.0, v21
	v_rcp_f32_e32 v21, v21
	v_mul_f32_e32 v17, v17, v20
	v_mul_f32_e32 v20, v26, v35
	v_mul_f32_e32 v20, v20, v21
	v_mul_f32_e32 v17, v22, v17
	v_mul_f32_e32 v22, v18, v20
	v_mul_f32_e32 v20, v31, v34
	v_exp_f32_e32 v20, v20
	v_mul_f32_e32 v21, v27, v34
	v_exp_f32_e32 v21, v21
	v_mul_f32_e32 v18, v31, v35
	v_add_f32_e32 v20, 1.0, v20
	v_rcp_f32_e32 v20, v20
	v_add_f32_e32 v21, 1.0, v21
	v_rcp_f32_e32 v21, v21
	v_mul_f32_e32 v18, v18, v20
	v_mul_f32_e32 v20, v27, v35
	v_mul_f32_e32 v20, v20, v21
	v_mul_f32_e32 v18, v23, v18
	v_mul_f32_e32 v19, v19, v20
	v_lshl_add_u64 v[20:21], v[32:33], 0, v[112:113]
	v_cvt_pk_bf16_f32 v17, v17, v18
	v_cvt_pk_bf16_f32 v18, v24, v25
	v_cvt_pk_bf16_f32 v19, v22, v19
	global_store_dwordx4 v[20:21], v[16:19], off
	s_nop 1
	v_mov_b32_e32 v18, v210
	s_nop 0
	v_add_u32_e32 v16, 0xb0, v144
	v_mad_i64_i32 v[16:17], s[42:43], v16, s49, v[146:147]
	s_mov_b64 s[42:43], s[26:27]
	v_mul_f32_e32 v19, v18, v18
	v_mul_f32_e32 v18, 0xbfb8aa3b, v18
	v_mul_f32_e32 v20, v12, v19
	v_mul_f32_e32 v12, v12, v18
	v_exp_f32_e32 v12, v12
	s_nop 0
	v_add_f32_e32 v12, 1.0, v12
	v_rcp_f32_e32 v12, v12
	s_nop 0
	v_mul_f32_e32 v12, v20, v12
	v_mul_f32_e32 v12, v4, v12
	v_mul_f32_e32 v4, v8, v19
	v_mul_f32_e32 v8, v8, v18
	v_exp_f32_e32 v8, v8
	s_nop 0
	v_add_f32_e32 v8, 1.0, v8
	v_rcp_f32_e32 v8, v8
	s_nop 0
	v_mul_f32_e32 v4, v4, v8
	v_mul_f32_e32 v8, v0, v4
	v_mul_f32_e32 v4, v13, v18
	v_exp_f32_e32 v4, v4
	v_mul_f32_e32 v0, v13, v19
	v_add_f32_e32 v4, 1.0, v4
	v_rcp_f32_e32 v4, v4
	s_nop 0
	v_mul_f32_e32 v0, v0, v4
	v_mul_f32_e32 v0, v5, v0
	v_mul_f32_e32 v5, v9, v18
	v_exp_f32_e32 v5, v5
	v_mul_f32_e32 v4, v9, v19
	v_cvt_pk_bf16_f32 v0, v12, v0
	v_add_f32_e32 v5, 1.0, v5
	v_rcp_f32_e32 v5, v5
	s_nop 0
	v_mul_f32_e32 v4, v4, v5
	v_mul_f32_e32 v9, v1, v4
	v_mul_f32_e32 v4, v14, v18
	v_exp_f32_e32 v4, v4
	v_mul_f32_e32 v5, v10, v18
	v_exp_f32_e32 v5, v5
	v_mul_f32_e32 v1, v14, v19
	v_add_f32_e32 v4, 1.0, v4
	v_rcp_f32_e32 v4, v4
	v_add_f32_e32 v5, 1.0, v5
	v_rcp_f32_e32 v5, v5
	v_mul_f32_e32 v1, v1, v4
	v_mul_f32_e32 v4, v10, v19
	v_mul_f32_e32 v4, v4, v5
	v_mul_f32_e32 v1, v6, v1
	v_mul_f32_e32 v6, v2, v4
	v_mul_f32_e32 v4, v15, v18
	v_exp_f32_e32 v4, v4
	v_mul_f32_e32 v5, v11, v18
	v_exp_f32_e32 v5, v5
	v_mul_f32_e32 v2, v15, v19
	v_add_f32_e32 v4, 1.0, v4
	v_rcp_f32_e32 v4, v4
	v_add_f32_e32 v5, 1.0, v5
	v_rcp_f32_e32 v5, v5
	v_mul_f32_e32 v2, v2, v4
	v_mul_f32_e32 v4, v11, v19
	v_mul_f32_e32 v4, v4, v5
	v_mul_f32_e32 v2, v7, v2
	v_mul_f32_e32 v3, v3, v4
	v_lshl_add_u64 v[4:5], v[16:17], 0, v[112:113]
	v_cvt_pk_bf16_f32 v1, v1, v2
	v_cvt_pk_bf16_f32 v2, v8, v9
	v_cvt_pk_bf16_f32 v3, v6, v3
	global_store_dwordx4 v[4:5], v[0:3], off
	s_cbranch_vccz .LBB0_200
	s_waitcnt vmcnt(0)
	s_cmpk_gt_u32 s3, 0xff
	s_cbranch_scc1 .LBB0_207
	s_barrier

; #define PG8_STAGE(bufoff, gbase, voff) do { _Pragma("unroll") for (int _i = 0; _i < 2; ++_i) \
;         __builtin_amdgcn_global_load_lds((const unsigned*)((const char*)(gbase) + (voff)[_i]), (LAS unsigned*)(lds + (bufoff) + ldsw + _i * 8192), 16, 0, 0); } while (0)
; #define PG8_LDA(dst, b, h) do { _Pragma("unroll") for (int m = 0; m < 4; ++m) _Pragma("unroll") for (int k = 0; k < 2; ++k) dst[m][k] = *(const LAS bf16x8*)(lds + PG8_SA(b, h) + aoff + m * 2048 + k * 1024); } while (0)
; #define PG8_WAIT_V(n) asm volatile("s_waitcnt vmcnt(" #n ")" ::: "memory")
; #define PG8_WAIT_L(n) asm volatile("s_waitcnt lgkmcnt(" #n ")" ::: "memory")
; template <class Epi>
; __device__ __forceinline__ void gemm_phase(LAS unsigned char* lds, const Gemm g, const StaticOrder& S, const Epi& E) {
;     ...
;         for (int t = 0; t < nt; t += 2) {
;             const bool last = (t == nt - 2);
;             const char* a1 = cA + (size_t)(t + 1) * kstep;
;             const char* a2 = last ? nA : cA + (size_t)(t + 2) * kstep; const char* b2 = last ? nB : cB + (size_t)(t + 2) * kstep;
;             const char* a3 = a2 + kstep; const char* b3 = b2 + kstep;
;             PG8_LDB(B0, 0, 0); PG8_SCHED; PG8_LDA(At, 0, 0); PG8_STAGE(PG8_SA(1, 1), a1 + hstep, voffA);
;             PG8_WAIT_L(8); PG8_BAR; PG8_WAIT_L(0); PG8_MMA(0, 0, At, B0); PG8_BAR; PG8_SCHED;
;             PG8_LDB(B1, 0, 1); PG8_STAGE(PG8_SB(0, 0), b2, voffB);
;             PG8_BAR; PG8_WAIT_L(0); PG8_MMA(0, 1, At, B1); PG8_BAR;
;             PG8_LDA(At, 0, 1); PG8_STAGE(PG8_SA(0, 0), a2, voffA);
;             PG8_BAR; PG8_WAIT_L(0); PG8_MMA(1, 0, At, B0); PG8_BAR; PG8_SCHED;
;             PG8_STAGE(PG8_SB(0, 1), b2 + hstep, voffB);
;             PG8_WAIT_V(6); PG8_BAR; PG8_MMA(1, 1, At, B1); PG8_BAR;
;             PG8_LDB(B0, 1, 0); PG8_SCHED; PG8_LDA(At, 1, 0); PG8_STAGE(PG8_SA(0, 1), a2 + hstep, voffA);
;             PG8_WAIT_L(8); PG8_BAR; PG8_WAIT_L(0); PG8_MMA(0, 0, At, B0); PG8_BAR; PG8_SCHED;
;             PG8_LDB(B1, 1, 1); PG8_STAGE(PG8_SB(1, 0), b3, voffB);
;             PG8_BAR; PG8_WAIT_L(0); PG8_MMA(0, 1, At, B1); PG8_BAR;
;             PG8_LDA(At, 1, 1); PG8_STAGE(PG8_SA(1, 0), a3, voffA);
;             PG8_BAR; PG8_WAIT_L(0); PG8_MMA(1, 0, At, B0); PG8_BAR; PG8_SCHED;
;             PG8_STAGE(PG8_SB(1, 1), b3 + hstep, voffB);
;             PG8_WAIT_V(6); PG8_BAR; PG8_MMA(1, 1, At, B1); PG8_BAR;
.LBB0_283:
	ds_read_b128 v[148:151], v145
	ds_read_b128 v[152:155], v145 offset:1024
	ds_read_b128 v[160:163], v145 offset:2048
	ds_read_b128 v[164:167], v145 offset:3072
	s_add_u32 s50, s48, 0x100
	s_addc_u32 s51, s49, 0
	s_cmpk_eq_i32 s65, 0x54
	s_cselect_b32 s55, s47, s51
	s_cselect_b32 s54, s46, s50
	s_cselect_b32 s53, s5, s64
	s_cselect_b32 s52, s4, s63
	s_add_i32 m0, s23, 0xc000
	ds_read_b128 v[168:171], v146
	ds_read_b128 v[172:175], v146 offset:1024
	ds_read_b128 v[176:179], v146 offset:2048
	ds_read_b128 v[180:183], v146 offset:3072
	ds_read_b128 v[184:187], v146 offset:4096
	ds_read_b128 v[188:191], v146 offset:5120
	ds_read_b128 v[192:195], v146 offset:6144
	ds_read_b128 v[196:199], v146 offset:7168
	global_load_lds_dwordx4 v136, s[48:49]
	s_add_i32 m0, s23, 0xe000
	s_nop 0
	global_load_lds_dwordx4 v138, s[48:49]
	s_waitcnt lgkmcnt(8)
	s_barrier
	s_waitcnt lgkmcnt(0)
	v_mfma_f32_16x16x32_bf16 v[124:127], v[148:151], v[168:171], v[124:127]
	v_mfma_f32_16x16x32_bf16 v[120:123], v[160:163], v[168:171], v[120:123]
	v_mfma_f32_16x16x32_bf16 v[112:115], v[148:151], v[176:179], v[112:115]
	v_mfma_f32_16x16x32_bf16 v[104:107], v[160:163], v[176:179], v[104:107]
	v_mfma_f32_16x16x32_bf16 v[96:99], v[148:151], v[184:187], v[96:99]
	v_mfma_f32_16x16x32_bf16 v[88:91], v[160:163], v[184:187], v[88:91]
	v_mfma_f32_16x16x32_bf16 v[80:83], v[148:151], v[192:195], v[80:83]
	v_mfma_f32_16x16x32_bf16 v[72:75], v[160:163], v[192:195], v[72:75]
	v_mfma_f32_16x16x32_bf16 v[124:127], v[152:155], v[172:175], v[124:127]
	v_mfma_f32_16x16x32_bf16 v[120:123], v[164:167], v[172:175], v[120:123]
	v_mfma_f32_16x16x32_bf16 v[112:115], v[152:155], v[180:183], v[112:115]
	v_mfma_f32_16x16x32_bf16 v[104:107], v[164:167], v[180:183], v[104:107]
	v_mfma_f32_16x16x32_bf16 v[96:99], v[152:155], v[188:191], v[96:99]
	v_mfma_f32_16x16x32_bf16 v[88:91], v[164:167], v[188:191], v[88:91]
	v_mfma_f32_16x16x32_bf16 v[80:83], v[152:155], v[196:199], v[80:83]
	v_mfma_f32_16x16x32_bf16 v[72:75], v[164:167], v[196:199], v[72:75]
	s_barrier
	s_add_i32 s48, s39, s13
	s_add_u32 s98, s52, s6
	s_addc_u32 s99, s53, s7
	s_mov_b32 m0, s48
	ds_read_b128 v[200:203], v147
	ds_read_b128 v[204:207], v147 offset:1024
	ds_read_b128 v[208:211], v147 offset:2048
	ds_read_b128 v[212:215], v147 offset:3072
	global_load_lds_dwordx4 v132, s[52:53]
	s_add_i32 m0, s48, 0x2000
	s_nop 0
	global_load_lds_dwordx4 v128, s[52:53]
	s_barrier
	s_waitcnt lgkmcnt(0)
	v_mfma_f32_16x16x32_bf16 v[116:119], v[200:203], v[168:171], v[116:119]
	v_mfma_f32_16x16x32_bf16 v[108:111], v[208:211], v[168:171], v[108:111]
	v_mfma_f32_16x16x32_bf16 v[100:103], v[200:203], v[176:179], v[100:103]
	v_mfma_f32_16x16x32_bf16 v[92:95], v[208:211], v[176:179], v[92:95]
	v_mfma_f32_16x16x32_bf16 v[84:87], v[200:203], v[184:187], v[84:87]
	v_mfma_f32_16x16x32_bf16 v[76:79], v[208:211], v[184:187], v[76:79]
	v_mfma_f32_16x16x32_bf16 v[68:71], v[200:203], v[192:195], v[68:71]
	v_mfma_f32_16x16x32_bf16 v[64:67], v[208:211], v[192:195], v[64:67]
	v_mfma_f32_16x16x32_bf16 v[116:119], v[204:207], v[172:175], v[116:119]
	v_mfma_f32_16x16x32_bf16 v[108:111], v[212:215], v[172:175], v[108:111]
	v_mfma_f32_16x16x32_bf16 v[100:103], v[204:207], v[180:183], v[100:103]
	v_mfma_f32_16x16x32_bf16 v[92:95], v[212:215], v[180:183], v[92:95]
	v_mfma_f32_16x16x32_bf16 v[84:87], v[204:207], v[188:191], v[84:87]
	v_mfma_f32_16x16x32_bf16 v[76:79], v[212:215], v[188:191], v[76:79]
	v_mfma_f32_16x16x32_bf16 v[68:71], v[204:207], v[196:199], v[68:71]
	v_mfma_f32_16x16x32_bf16 v[64:67], v[212:215], v[196:199], v[64:67]
	s_mov_b32 m0, s23
	s_add_u32 s100, s54, s6
	s_addc_u32 s101, s55, s7
	s_barrier
	ds_read_b128 v[168:171], v146 offset:16384
	ds_read_b128 v[172:175], v146 offset:17408
	ds_read_b128 v[176:179], v146 offset:18432
	ds_read_b128 v[180:183], v146 offset:19456
	ds_read_b128 v[184:187], v146 offset:20480
	ds_read_b128 v[188:191], v146 offset:21504
	ds_read_b128 v[192:195], v146 offset:22528
	ds_read_b128 v[196:199], v146 offset:23552
	global_load_lds_dwordx4 v134, s[54:55]
	s_mov_b32 m0, s30
	s_nop 0
	global_load_lds_dwordx4 v130, s[54:55]
	s_barrier
	s_waitcnt lgkmcnt(0)
	v_mfma_f32_16x16x32_bf16 v[60:63], v[148:151], v[168:171], v[60:63]
	v_mfma_f32_16x16x32_bf16 v[56:59], v[160:163], v[168:171], v[56:59]
	v_mfma_f32_16x16x32_bf16 v[52:55], v[148:151], v[176:179], v[52:55]
	v_mfma_f32_16x16x32_bf16 v[44:47], v[160:163], v[176:179], v[44:47]
	v_mfma_f32_16x16x32_bf16 v[36:39], v[148:151], v[184:187], v[36:39]
	v_mfma_f32_16x16x32_bf16 v[28:31], v[160:163], v[184:187], v[28:31]
	v_mfma_f32_16x16x32_bf16 v[20:23], v[148:151], v[192:195], v[20:23]
	v_mfma_f32_16x16x32_bf16 v[12:15], v[160:163], v[192:195], v[12:15]
	v_mfma_f32_16x16x32_bf16 v[60:63], v[152:155], v[172:175], v[60:63]
	v_mfma_f32_16x16x32_bf16 v[56:59], v[164:167], v[172:175], v[56:59]
	v_mfma_f32_16x16x32_bf16 v[52:55], v[152:155], v[180:183], v[52:55]
	v_mfma_f32_16x16x32_bf16 v[44:47], v[164:167], v[180:183], v[44:47]
	v_mfma_f32_16x16x32_bf16 v[36:39], v[152:155], v[188:191], v[36:39]
	v_mfma_f32_16x16x32_bf16 v[28:31], v[164:167], v[188:191], v[28:31]
	v_mfma_f32_16x16x32_bf16 v[20:23], v[152:155], v[196:199], v[20:23]
	v_mfma_f32_16x16x32_bf16 v[12:15], v[164:167], v[196:199], v[12:15]
	s_barrier
	s_add_u32 s48, s52, 0x160000
	s_addc_u32 s49, s53, 0
	s_add_i32 s66, s40, s13
	s_mov_b32 m0, s66
	s_nop 0
	global_load_lds_dwordx4 v132, s[48:49]
	s_add_i32 m0, s66, 0x2000
	s_nop 0
	global_load_lds_dwordx4 v128, s[48:49]
	s_waitcnt vmcnt(6)
	s_barrier
; #define PG8_STAGE(bufoff, gbase, voff) do { _Pragma("unroll") for (int _i = 0; _i < 2; ++_i) \
;         __builtin_amdgcn_global_load_lds((const unsigned*)((const char*)(gbase) + (voff)[_i]), (LAS unsigned*)(lds + (bufoff) + ldsw + _i * 8192), 16, 0, 0); } while (0)
; #define PG8_LDA(dst, b, h) do { _Pragma("unroll") for (int m = 0; m < 4; ++m) _Pragma("unroll") for (int k = 0; k < 2; ++k) dst[m][k] = *(const LAS bf16x8*)(lds + PG8_SA(b, h) + aoff + m * 2048 + k * 1024); } while (0)
; #define PG8_LDB(dst, b, h) do { _Pragma("unroll") for (int n = 0; n < 2; ++n) _Pragma("unroll") for (int k = 0; k < 2; ++k) dst[n][k] = *(const LAS bf16x8*)(lds + PG8_SB(b, h) + boff + n * 2048 + k * 1024); } while (0)
; #define PG8_MMA(ai, bj, At, Bt) do { __builtin_amdgcn_s_setprio(1); _Pragma("unroll") for (int m = 0; m < 4; ++m) _Pragma("unroll") for (int n = 0; n < 2; ++n) _Pragma("unroll") for (int k = 0; k < 2; ++k) \
;         acc[ai][bj][m][n] = __builtin_amdgcn_mfma_f32_16x16x32_bf16(Bt[n][k], At[m][k], acc[ai][bj][m][n], 0, 0, 0); __builtin_amdgcn_s_setprio(0); } while (0)
; #define PG8_WAIT_V(n) asm volatile("s_waitcnt vmcnt(" #n ")" ::: "memory")
; #define PG8_WAIT_L(n) asm volatile("s_waitcnt lgkmcnt(" #n ")" ::: "memory")
; #define PG8_BAR __builtin_amdgcn_s_barrier()
; #define PG8_SCHED __builtin_amdgcn_sched_barrier(0)
; template <class Epi>
; __device__ __forceinline__ void gemm_phase(LAS unsigned char* lds, const Gemm g, const StaticOrder& S, const Epi& E) {
;     ...
;             PG8_WAIT_V(6); PG8_BAR; PG8_MMA(1, 1, At, B1); PG8_BAR;
;             PG8_LDB(B0, 1, 0); PG8_SCHED; PG8_LDA(At, 1, 0); PG8_STAGE(PG8_SA(0, 1), a2 + hstep, voffA);
;             PG8_WAIT_L(8); PG8_BAR; PG8_WAIT_L(0); PG8_MMA(0, 0, At, B0); PG8_BAR; PG8_SCHED;
;             PG8_LDB(B1, 1, 1); PG8_STAGE(PG8_SB(1, 0), b3, voffB);
;             PG8_BAR; PG8_WAIT_L(0); PG8_MMA(0, 1, At, B1); PG8_BAR;
;             PG8_LDA(At, 1, 1); PG8_STAGE(PG8_SA(1, 0), a3, voffA);
;             PG8_BAR; PG8_WAIT_L(0); PG8_MMA(1, 0, At, B0); PG8_BAR; PG8_SCHED;
;             PG8_STAGE(PG8_SB(1, 1), b3 + hstep, voffB);
;             PG8_WAIT_V(6); PG8_BAR; PG8_MMA(1, 1, At, B1); PG8_BAR;
	v_mfma_f32_16x16x32_bf16 v[48:51], v[200:203], v[168:171], v[48:51]
	v_mfma_f32_16x16x32_bf16 v[40:43], v[208:211], v[168:171], v[40:43]
	v_mfma_f32_16x16x32_bf16 v[32:35], v[200:203], v[176:179], v[32:35]
	v_mfma_f32_16x16x32_bf16 v[24:27], v[208:211], v[176:179], v[24:27]
	v_mfma_f32_16x16x32_bf16 v[16:19], v[200:203], v[184:187], v[16:19]
	v_mfma_f32_16x16x32_bf16 v[8:11], v[208:211], v[184:187], v[8:11]
	v_mfma_f32_16x16x32_bf16 v[4:7], v[200:203], v[192:195], v[4:7]
	v_mfma_f32_16x16x32_bf16 v[0:3], v[208:211], v[192:195], v[0:3]
	v_mfma_f32_16x16x32_bf16 v[48:51], v[204:207], v[172:175], v[48:51]
	v_mfma_f32_16x16x32_bf16 v[40:43], v[212:215], v[172:175], v[40:43]
	v_mfma_f32_16x16x32_bf16 v[32:35], v[204:207], v[180:183], v[32:35]
	v_mfma_f32_16x16x32_bf16 v[24:27], v[212:215], v[180:183], v[24:27]
	v_mfma_f32_16x16x32_bf16 v[16:19], v[204:207], v[188:191], v[16:19]
	v_mfma_f32_16x16x32_bf16 v[8:11], v[212:215], v[188:191], v[8:11]
	v_mfma_f32_16x16x32_bf16 v[4:7], v[204:207], v[196:199], v[4:7]
	v_mfma_f32_16x16x32_bf16 v[0:3], v[212:215], v[196:199], v[0:3]
	s_add_i32 s66, 0, 0x18000
	v_add_u32_e32 v164, s66, v143
	s_barrier
	ds_read_b128 v[148:151], v164
	ds_read_b128 v[152:155], v164 offset:1024
	ds_read_b128 v[160:163], v164 offset:2048
	ds_read_b128 v[164:167], v164 offset:3072
	s_add_u32 s48, s54, 0x160000
	s_addc_u32 s49, s55, 0
	s_mov_b32 m0, s31
	ds_read_b128 v[168:171], v146 offset:32768
	ds_read_b128 v[172:175], v146 offset:33792
	ds_read_b128 v[176:179], v146 offset:34816
	ds_read_b128 v[180:183], v146 offset:35840
	ds_read_b128 v[184:187], v146 offset:36864
	ds_read_b128 v[188:191], v146 offset:37888
	ds_read_b128 v[192:195], v146 offset:38912
	ds_read_b128 v[196:199], v146 offset:39936
	global_load_lds_dwordx4 v134, s[48:49]
	s_mov_b32 m0, s33
	s_nop 0
	global_load_lds_dwordx4 v130, s[48:49]
	s_waitcnt lgkmcnt(8)
	s_barrier
	s_waitcnt lgkmcnt(0)
	v_mfma_f32_16x16x32_bf16 v[124:127], v[148:151], v[168:171], v[124:127]
	v_mfma_f32_16x16x32_bf16 v[120:123], v[160:163], v[168:171], v[120:123]
	v_mfma_f32_16x16x32_bf16 v[112:115], v[148:151], v[176:179], v[112:115]
	v_mfma_f32_16x16x32_bf16 v[104:107], v[160:163], v[176:179], v[104:107]
	v_mfma_f32_16x16x32_bf16 v[96:99], v[148:151], v[184:187], v[96:99]
	v_mfma_f32_16x16x32_bf16 v[88:91], v[160:163], v[184:187], v[88:91]
	v_mfma_f32_16x16x32_bf16 v[80:83], v[148:151], v[192:195], v[80:83]
	v_mfma_f32_16x16x32_bf16 v[72:75], v[160:163], v[192:195], v[72:75]
	v_mfma_f32_16x16x32_bf16 v[124:127], v[152:155], v[172:175], v[124:127]
	v_mfma_f32_16x16x32_bf16 v[120:123], v[164:167], v[172:175], v[120:123]
	v_mfma_f32_16x16x32_bf16 v[112:115], v[152:155], v[180:183], v[112:115]
	v_mfma_f32_16x16x32_bf16 v[104:107], v[164:167], v[180:183], v[104:107]
	v_mfma_f32_16x16x32_bf16 v[96:99], v[152:155], v[188:191], v[96:99]
	v_mfma_f32_16x16x32_bf16 v[88:91], v[164:167], v[188:191], v[88:91]
	v_mfma_f32_16x16x32_bf16 v[80:83], v[152:155], v[196:199], v[80:83]
	v_mfma_f32_16x16x32_bf16 v[72:75], v[164:167], v[196:199], v[72:75]
	s_barrier
	s_add_i32 s54, 0, 0x1c000
	s_add_i32 s48, s66, s13
	v_add_u32_e32 v212, s54, v143
	s_mov_b32 m0, s48
	ds_read_b128 v[200:203], v212
	ds_read_b128 v[204:207], v212 offset:1024
	ds_read_b128 v[208:211], v212 offset:2048
	ds_read_b128 v[212:215], v212 offset:3072
	global_load_lds_dwordx4 v132, s[98:99]
	s_add_i32 m0, s48, 0x2000
	s_nop 0
	global_load_lds_dwordx4 v128, s[98:99]
	s_barrier
	s_waitcnt lgkmcnt(0)
	v_mfma_f32_16x16x32_bf16 v[116:119], v[200:203], v[168:171], v[116:119]
	v_mfma_f32_16x16x32_bf16 v[108:111], v[208:211], v[168:171], v[108:111]
	v_mfma_f32_16x16x32_bf16 v[100:103], v[200:203], v[176:179], v[100:103]
	v_mfma_f32_16x16x32_bf16 v[92:95], v[208:211], v[176:179], v[92:95]
	v_mfma_f32_16x16x32_bf16 v[84:87], v[200:203], v[184:187], v[84:87]
	v_mfma_f32_16x16x32_bf16 v[76:79], v[208:211], v[184:187], v[76:79]
	v_mfma_f32_16x16x32_bf16 v[68:71], v[200:203], v[192:195], v[68:71]
	v_mfma_f32_16x16x32_bf16 v[64:67], v[208:211], v[192:195], v[64:67]
	v_mfma_f32_16x16x32_bf16 v[116:119], v[204:207], v[172:175], v[116:119]
	v_mfma_f32_16x16x32_bf16 v[108:111], v[212:215], v[172:175], v[108:111]
	v_mfma_f32_16x16x32_bf16 v[100:103], v[204:207], v[180:183], v[100:103]
	v_mfma_f32_16x16x32_bf16 v[92:95], v[212:215], v[180:183], v[92:95]
	v_mfma_f32_16x16x32_bf16 v[84:87], v[204:207], v[188:191], v[84:87]
	v_mfma_f32_16x16x32_bf16 v[76:79], v[212:215], v[188:191], v[76:79]
	v_mfma_f32_16x16x32_bf16 v[68:71], v[204:207], v[196:199], v[68:71]
	v_mfma_f32_16x16x32_bf16 v[64:67], v[212:215], v[196:199], v[64:67]
	s_mov_b32 m0, s34
	s_barrier
	ds_read_b128 v[168:171], v146 offset:49152
	ds_read_b128 v[172:175], v146 offset:50176
	ds_read_b128 v[176:179], v146 offset:51200
	ds_read_b128 v[180:183], v146 offset:52224
	ds_read_b128 v[184:187], v146 offset:53248
	ds_read_b128 v[188:191], v146 offset:54272
	ds_read_b128 v[192:195], v146 offset:55296
	ds_read_b128 v[196:199], v146 offset:56320
	global_load_lds_dwordx4 v134, s[100:101]
	s_mov_b32 m0, s36
	s_nop 0
	global_load_lds_dwordx4 v130, s[100:101]
	s_barrier
; #define PG8_STAGE(bufoff, gbase, voff) do { _Pragma("unroll") for (int _i = 0; _i < 2; ++_i) \
;         __builtin_amdgcn_global_load_lds((const unsigned*)((const char*)(gbase) + (voff)[_i]), (LAS unsigned*)(lds + (bufoff) + ldsw + _i * 8192), 16, 0, 0); } while (0)
; #define PG8_MMA(ai, bj, At, Bt) do { __builtin_amdgcn_s_setprio(1); _Pragma("unroll") for (int m = 0; m < 4; ++m) _Pragma("unroll") for (int n = 0; n < 2; ++n) _Pragma("unroll") for (int k = 0; k < 2; ++k) \
;         acc[ai][bj][m][n] = __builtin_amdgcn_mfma_f32_16x16x32_bf16(Bt[n][k], At[m][k], acc[ai][bj][m][n], 0, 0, 0); __builtin_amdgcn_s_setprio(0); } while (0)
; #define PG8_WAIT_V(n) asm volatile("s_waitcnt vmcnt(" #n ")" ::: "memory")
; #define PG8_WAIT_L(n) asm volatile("s_waitcnt lgkmcnt(" #n ")" ::: "memory")
; #define PG8_BAR __builtin_amdgcn_s_barrier()
; #define PG8_SCHED __builtin_amdgcn_sched_barrier(0)
; template <class Epi>
; __device__ __forceinline__ void gemm_phase(LAS unsigned char* lds, const Gemm g, const StaticOrder& S, const Epi& E) {
;     ...
;             PG8_BAR; PG8_WAIT_L(0); PG8_MMA(1, 0, At, B0); PG8_BAR; PG8_SCHED;
;             PG8_STAGE(PG8_SB(1, 1), b3 + hstep, voffB);
;             PG8_WAIT_V(6); PG8_BAR; PG8_MMA(1, 1, At, B1); PG8_BAR;
;         }
;         E(acc, cur, wr, wc, fr, fq);
;         if (!has_next) break;
	s_waitcnt lgkmcnt(0)
	v_mfma_f32_16x16x32_bf16 v[60:63], v[148:151], v[168:171], v[60:63]
	v_mfma_f32_16x16x32_bf16 v[56:59], v[160:163], v[168:171], v[56:59]
	v_mfma_f32_16x16x32_bf16 v[52:55], v[148:151], v[176:179], v[52:55]
	v_mfma_f32_16x16x32_bf16 v[44:47], v[160:163], v[176:179], v[44:47]
	v_mfma_f32_16x16x32_bf16 v[36:39], v[148:151], v[184:187], v[36:39]
	v_mfma_f32_16x16x32_bf16 v[28:31], v[160:163], v[184:187], v[28:31]
	v_mfma_f32_16x16x32_bf16 v[20:23], v[148:151], v[192:195], v[20:23]
	v_mfma_f32_16x16x32_bf16 v[12:15], v[160:163], v[192:195], v[12:15]
	v_mfma_f32_16x16x32_bf16 v[60:63], v[152:155], v[172:175], v[60:63]
	v_mfma_f32_16x16x32_bf16 v[56:59], v[164:167], v[172:175], v[56:59]
	v_mfma_f32_16x16x32_bf16 v[52:55], v[152:155], v[180:183], v[52:55]
	v_mfma_f32_16x16x32_bf16 v[44:47], v[164:167], v[180:183], v[44:47]
	v_mfma_f32_16x16x32_bf16 v[36:39], v[152:155], v[188:191], v[36:39]
	v_mfma_f32_16x16x32_bf16 v[28:31], v[164:167], v[188:191], v[28:31]
	v_mfma_f32_16x16x32_bf16 v[20:23], v[152:155], v[196:199], v[20:23]
	v_mfma_f32_16x16x32_bf16 v[12:15], v[164:167], v[196:199], v[12:15]
	s_barrier
	s_add_u32 s48, s52, 0x160080
	s_addc_u32 s49, s53, 0
	s_add_i32 s52, s54, s13
	s_mov_b32 m0, s52
	s_nop 0
	global_load_lds_dwordx4 v132, s[48:49]
	s_add_i32 m0, s52, 0x2000
	s_nop 0
	global_load_lds_dwordx4 v128, s[48:49]
	s_add_i32 s65, s65, 2
	s_add_u32 s63, s63, 0x100
	s_addc_u32 s64, s64, 0
	s_cmpk_gt_u32 s65, 0x55
	s_mov_b64 s[48:49], s[50:51]
	s_waitcnt vmcnt(6)
	s_barrier
	v_mfma_f32_16x16x32_bf16 v[48:51], v[200:203], v[168:171], v[48:51]
	v_mfma_f32_16x16x32_bf16 v[40:43], v[208:211], v[168:171], v[40:43]
	v_mfma_f32_16x16x32_bf16 v[32:35], v[200:203], v[176:179], v[32:35]
	v_mfma_f32_16x16x32_bf16 v[24:27], v[208:211], v[176:179], v[24:27]
	v_mfma_f32_16x16x32_bf16 v[16:19], v[200:203], v[184:187], v[16:19]
	v_mfma_f32_16x16x32_bf16 v[8:11], v[208:211], v[184:187], v[8:11]
	v_mfma_f32_16x16x32_bf16 v[4:7], v[200:203], v[192:195], v[4:7]
	v_mfma_f32_16x16x32_bf16 v[0:3], v[208:211], v[192:195], v[0:3]
	v_mfma_f32_16x16x32_bf16 v[48:51], v[204:207], v[172:175], v[48:51]
	v_mfma_f32_16x16x32_bf16 v[40:43], v[212:215], v[172:175], v[40:43]
	v_mfma_f32_16x16x32_bf16 v[32:35], v[204:207], v[180:183], v[32:35]
	v_mfma_f32_16x16x32_bf16 v[24:27], v[212:215], v[180:183], v[24:27]
	v_mfma_f32_16x16x32_bf16 v[16:19], v[204:207], v[188:191], v[16:19]
	v_mfma_f32_16x16x32_bf16 v[8:11], v[212:215], v[188:191], v[8:11]
	v_mfma_f32_16x16x32_bf16 v[4:7], v[204:207], v[196:199], v[4:7]
	v_mfma_f32_16x16x32_bf16 v[0:3], v[212:215], v[196:199], v[0:3]
	s_barrier
	s_cbranch_scc0 .LBB0_283
; __device__ __forceinline__ u32x4 pack8(f32x4 v0, f32x4 v1) { u32x4 w; w.x = cvt_pk_bf16(v0[0], v0[1]); w.y = cvt_pk_bf16(v0[2], v0[3]); w.z = cvt_pk_bf16(v1[0], v1[1]); w.w = cvt_pk_bf16(v1[2], v1[3]); return w; }
;     __device__ __forceinline__ void operator()(const f32x4 (&acc)[2][2][4][2], const Unit& u, int wr, int wc, int fr, int fq) const {
;         const int row0 = u.pm * BM + wr * 64 + fr, col0 = u.pn * BM + wc * 32 + 8 * fq;
; #pragma unroll
;         for (int ai = 0; ai < 2; ++ai)
; #pragma unroll
;             for (int m = 0; m < 4; ++m) { bf16_t* rowp = O + (size_t)(row0 + ai * HALF + m * 16) * ldc + col0;
; #pragma unroll
;                 for (int bj = 0; bj < 2; ++bj) *(u32x4*)(rowp + bj * HALF) = pack8(acc[ai][bj][m][0], acc[ai][bj][m][1]); }
	v_lshl_add_u32 v148, s61, 8, v142
	v_lshl_or_b32 v140, s62, 8, v144
	v_ashrrev_i32_e32 v149, 31, v148
	v_ashrrev_i32_e32 v141, 31, v140
	v_lshlrev_b64 v[150:151], 12, v[148:149]
	v_lshl_add_u64 v[150:151], s[24:25], 0, v[150:151]
	v_lshlrev_b64 v[152:153], 1, v[140:141]
	v_lshl_add_u64 v[140:141], v[150:151], 0, v[152:153]
	v_cvt_pk_bf16_f32 v124, v124, v125
	v_cvt_pk_bf16_f32 v125, v126, v127
	v_cvt_pk_bf16_f32 v126, v120, v121
	v_cvt_pk_bf16_f32 v127, v122, v123
	global_store_dwordx4 v[140:141], v[124:127], off
	v_cvt_pk_bf16_f32 v116, v116, v117
	v_cvt_pk_bf16_f32 v117, v118, v119
	v_cvt_pk_bf16_f32 v118, v108, v109
	v_or_b32_e32 v108, 16, v148
	v_ashrrev_i32_e32 v109, 31, v108
	v_lshlrev_b64 v[108:109], 12, v[108:109]
	v_lshl_add_u64 v[108:109], s[24:25], 0, v[108:109]
	v_cvt_pk_bf16_f32 v119, v110, v111
	global_store_dwordx4 v[140:141], v[116:119], off offset:256
	s_mov_b32 s62, s59
	s_mov_b32 s61, s60
	v_lshl_add_u64 v[116:117], v[108:109], 0, v[152:153]
	v_cvt_pk_bf16_f32 v108, v112, v113
	v_cvt_pk_bf16_f32 v109, v114, v115
	v_cvt_pk_bf16_f32 v110, v104, v105
	v_cvt_pk_bf16_f32 v111, v106, v107
	global_store_dwordx4 v[116:117], v[108:111], off
	v_cvt_pk_bf16_f32 v100, v100, v101
	v_cvt_pk_bf16_f32 v101, v102, v103
	v_cvt_pk_bf16_f32 v102, v92, v93
	v_or_b32_e32 v92, 32, v148
	v_ashrrev_i32_e32 v93, 31, v92
	v_lshlrev_b64 v[92:93], 12, v[92:93]
	v_lshl_add_u64 v[92:93], s[24:25], 0, v[92:93]
	v_cvt_pk_bf16_f32 v103, v94, v95
	global_store_dwordx4 v[116:117], v[100:103], off offset:256
	s_mov_b64 s[50:51], s[4:5]
	s_mov_b64 s[48:49], s[46:47]
	v_lshl_add_u64 v[100:101], v[92:93], 0, v[152:153]
	v_cvt_pk_bf16_f32 v92, v96, v97
	v_cvt_pk_bf16_f32 v93, v98, v99
	v_cvt_pk_bf16_f32 v94, v88, v89
	v_cvt_pk_bf16_f32 v95, v90, v91
	global_store_dwordx4 v[100:101], v[92:95], off
	v_cvt_pk_bf16_f32 v84, v84, v85
	v_cvt_pk_bf16_f32 v85, v86, v87
	v_cvt_pk_bf16_f32 v86, v76, v77
	v_or_b32_e32 v76, 48, v148
	v_ashrrev_i32_e32 v77, 31, v76
	v_lshlrev_b64 v[76:77], 12, v[76:77]
	v_lshl_add_u64 v[76:77], s[24:25], 0, v[76:77]
	v_cvt_pk_bf16_f32 v87, v78, v79
	global_store_dwordx4 v[100:101], v[84:87], off offset:256
	s_nop 1
	v_lshl_add_u64 v[84:85], v[76:77], 0, v[152:153]
	v_cvt_pk_bf16_f32 v76, v80, v81
	v_cvt_pk_bf16_f32 v77, v82, v83
	v_cvt_pk_bf16_f32 v78, v72, v73
	v_cvt_pk_bf16_f32 v79, v74, v75
	global_store_dwordx4 v[84:85], v[76:79], off
	v_cvt_pk_bf16_f32 v68, v68, v69
	v_cvt_pk_bf16_f32 v69, v70, v71
	v_cvt_pk_bf16_f32 v70, v64, v65
	v_cvt_pk_bf16_f32 v71, v66, v67
	global_store_dwordx4 v[84:85], v[68:71], off offset:256
	v_cvt_pk_bf16_f32 v60, v60, v61
	v_cvt_pk_bf16_f32 v61, v62, v63
	v_cvt_pk_bf16_f32 v62, v56, v57
	v_add_co_u32_e32 v56, vcc, s41, v140
	v_lshl_add_u64 v[64:65], v[140:141], 0, s[8:9]
	s_nop 0
	v_addc_co_u32_e32 v57, vcc, 0, v141, vcc
	v_cvt_pk_bf16_f32 v63, v58, v59
	global_store_dwordx4 v[56:57], v[60:63], off
	v_cvt_pk_bf16_f32 v48, v48, v49
	v_cvt_pk_bf16_f32 v49, v50, v51
	v_cvt_pk_bf16_f32 v50, v40, v41
	v_cvt_pk_bf16_f32 v51, v42, v43
	global_store_dwordx4 v[64:65], v[48:51], off offset:256
	v_cvt_pk_bf16_f32 v40, v52, v53
	v_cvt_pk_bf16_f32 v41, v54, v55
	v_cvt_pk_bf16_f32 v42, v44, v45
	v_add_co_u32_e32 v44, vcc, s56, v140
	s_nop 0
	v_lshl_add_u64 v[48:49], v[140:141], 0, s[26:27]
	v_addc_co_u32_e32 v45, vcc, 0, v141, vcc
	v_cvt_pk_bf16_f32 v43, v46, v47
	global_store_dwordx4 v[44:45], v[40:43], off
	v_cvt_pk_bf16_f32 v32, v32, v33
	v_cvt_pk_bf16_f32 v33, v34, v35
	v_cvt_pk_bf16_f32 v34, v24, v25
	v_cvt_pk_bf16_f32 v35, v26, v27
	global_store_dwordx4 v[48:49], v[32:35], off offset:256
	v_cvt_pk_bf16_f32 v24, v36, v37
	v_cvt_pk_bf16_f32 v25, v38, v39
	v_cvt_pk_bf16_f32 v26, v28, v29
	v_add_co_u32_e32 v28, vcc, s57, v140
	s_nop 0
	v_lshl_add_u64 v[32:33], v[140:141], 0, s[28:29]
	v_addc_co_u32_e32 v29, vcc, 0, v141, vcc
	v_cvt_pk_bf16_f32 v27, v30, v31
	global_store_dwordx4 v[28:29], v[24:27], off
	v_cvt_pk_bf16_f32 v16, v16, v17
	v_cvt_pk_bf16_f32 v17, v18, v19
	v_cvt_pk_bf16_f32 v18, v8, v9
	v_cvt_pk_bf16_f32 v19, v10, v11
	global_store_dwordx4 v[32:33], v[16:19], off offset:256
	v_cvt_pk_bf16_f32 v8, v20, v21
	v_cvt_pk_bf16_f32 v9, v22, v23
	v_cvt_pk_bf16_f32 v10, v12, v13
	v_add_co_u32_e32 v12, vcc, s58, v140
	s_nop 0
	v_lshl_add_u64 v[16:17], v[140:141], 0, s[42:43]
	v_addc_co_u32_e32 v13, vcc, 0, v141, vcc
	s_and_b64 vcc, exec, s[44:45]
	v_cvt_pk_bf16_f32 v11, v14, v15
	global_store_dwordx4 v[12:13], v[8:11], off
	v_cvt_pk_bf16_f32 v4, v4, v5
	v_cvt_pk_bf16_f32 v5, v6, v7
	v_cvt_pk_bf16_f32 v6, v0, v1
	v_cvt_pk_bf16_f32 v7, v2, v3
	global_store_dwordx4 v[16:17], v[4:7], off offset:256
	s_cbranch_vccz .LBB0_276
	s_waitcnt vmcnt(0)
	s_cmpk_gt_u32 s3, 0xff
	v_readlane_b32 s62, v232, 20
	s_cbranch_scc1 .LBB0_287
	s_barrier

; #define PG8_STAGE(bufoff, gbase, voff) do { _Pragma("unroll") for (int _i = 0; _i < 2; ++_i) \
;         __builtin_amdgcn_global_load_lds((const unsigned*)((const char*)(gbase) + (voff)[_i]), (LAS unsigned*)(lds + (bufoff) + ldsw + _i * 8192), 16, 0, 0); } while (0)
; #define PG8_LDA(dst, b, h) do { _Pragma("unroll") for (int m = 0; m < 4; ++m) _Pragma("unroll") for (int k = 0; k < 2; ++k) dst[m][k] = *(const LAS bf16x8*)(lds + PG8_SA(b, h) + aoff + m * 2048 + k * 1024); } while (0)
; #define PG8_WAIT_V(n) asm volatile("s_waitcnt vmcnt(" #n ")" ::: "memory")
; #define PG8_WAIT_L(n) asm volatile("s_waitcnt lgkmcnt(" #n ")" ::: "memory")
; template <class Epi>
; __device__ __forceinline__ void gemm_phase(LAS unsigned char* lds, const Gemm g, const StaticOrder& S, const Epi& E) {
;     ...
;         for (int t = 0; t < nt; t += 2) {
;             const bool last = (t == nt - 2);
;             const char* a1 = cA + (size_t)(t + 1) * kstep;
;             const char* a2 = last ? nA : cA + (size_t)(t + 2) * kstep; const char* b2 = last ? nB : cB + (size_t)(t + 2) * kstep;
;             const char* a3 = a2 + kstep; const char* b3 = b2 + kstep;
;             PG8_LDB(B0, 0, 0); PG8_SCHED; PG8_LDA(At, 0, 0); PG8_STAGE(PG8_SA(1, 1), a1 + hstep, voffA);
;             PG8_WAIT_L(8); PG8_BAR; PG8_WAIT_L(0); PG8_MMA(0, 0, At, B0); PG8_BAR; PG8_SCHED;
;             PG8_LDB(B1, 0, 1); PG8_STAGE(PG8_SB(0, 0), b2, voffB);
;             PG8_BAR; PG8_WAIT_L(0); PG8_MMA(0, 1, At, B1); PG8_BAR;
;             PG8_LDA(At, 0, 1); PG8_STAGE(PG8_SA(0, 0), a2, voffA);
;             PG8_BAR; PG8_WAIT_L(0); PG8_MMA(1, 0, At, B0); PG8_BAR; PG8_SCHED;
;             PG8_STAGE(PG8_SB(0, 1), b2 + hstep, voffB);
;             PG8_WAIT_V(6); PG8_BAR; PG8_MMA(1, 1, At, B1); PG8_BAR;
;             PG8_LDB(B0, 1, 0); PG8_SCHED; PG8_LDA(At, 1, 0); PG8_STAGE(PG8_SA(0, 1), a2 + hstep, voffA);
;             PG8_WAIT_L(8); PG8_BAR; PG8_WAIT_L(0); PG8_MMA(0, 0, At, B0); PG8_BAR; PG8_SCHED;
;             PG8_LDB(B1, 1, 1); PG8_STAGE(PG8_SB(1, 0), b3, voffB);
;             PG8_BAR; PG8_WAIT_L(0); PG8_MMA(0, 1, At, B1); PG8_BAR;
;             PG8_LDA(At, 1, 1); PG8_STAGE(PG8_SA(1, 0), a3, voffA);
;             PG8_BAR; PG8_WAIT_L(0); PG8_MMA(1, 0, At, B0); PG8_BAR; PG8_SCHED;
;             PG8_STAGE(PG8_SB(1, 1), b3 + hstep, voffB);
;             PG8_WAIT_V(6); PG8_BAR; PG8_MMA(1, 1, At, B1); PG8_BAR;
.LBB0_407:
	ds_read_b128 v[150:153], v164
	ds_read_b128 v[154:157], v164 offset:1024
	ds_read_b128 v[168:171], v164 offset:2048
	ds_read_b128 v[172:175], v164 offset:3072
	s_add_u32 s48, s46, 0xfff80080
	s_addc_u32 s49, s47, -1
	s_cmp_eq_u32 s57, 28
	s_cselect_b32 s51, s9, s49
	s_cselect_b32 s50, s45, s48
	s_cselect_b32 s49, s7, s56
	s_cselect_b32 s48, s54, s55
	s_add_i32 m0, s27, 0xc000
	ds_read_b128 v[176:179], v165
	ds_read_b128 v[180:183], v165 offset:1024
	ds_read_b128 v[184:187], v165 offset:2048
	ds_read_b128 v[188:191], v165 offset:3072
	ds_read_b128 v[192:195], v165 offset:4096
	ds_read_b128 v[196:199], v165 offset:5120
	ds_read_b128 v[200:203], v165 offset:6144
	ds_read_b128 v[204:207], v165 offset:7168
	global_load_lds_dwordx4 v142, s[46:47]
	s_add_i32 m0, s27, 0xe000
	s_nop 0
	global_load_lds_dwordx4 v144, s[46:47]
	s_waitcnt lgkmcnt(8)
	s_barrier
	s_waitcnt lgkmcnt(0)
	v_mfma_f32_16x16x32_bf16 v[124:127], v[150:153], v[176:179], v[124:127]
	v_mfma_f32_16x16x32_bf16 v[120:123], v[168:171], v[176:179], v[120:123]
	v_mfma_f32_16x16x32_bf16 v[108:111], v[150:153], v[184:187], v[108:111]
	v_mfma_f32_16x16x32_bf16 v[104:107], v[168:171], v[184:187], v[104:107]
	v_mfma_f32_16x16x32_bf16 v[92:95], v[150:153], v[192:195], v[92:95]
	v_mfma_f32_16x16x32_bf16 v[88:91], v[168:171], v[192:195], v[88:91]
	v_mfma_f32_16x16x32_bf16 v[76:79], v[150:153], v[200:203], v[76:79]
	v_mfma_f32_16x16x32_bf16 v[72:75], v[168:171], v[200:203], v[72:75]
	v_mfma_f32_16x16x32_bf16 v[124:127], v[154:157], v[180:183], v[124:127]
	v_mfma_f32_16x16x32_bf16 v[120:123], v[172:175], v[180:183], v[120:123]
	v_mfma_f32_16x16x32_bf16 v[108:111], v[154:157], v[188:191], v[108:111]
	v_mfma_f32_16x16x32_bf16 v[104:107], v[172:175], v[188:191], v[104:107]
	v_mfma_f32_16x16x32_bf16 v[92:95], v[154:157], v[196:199], v[92:95]
	v_mfma_f32_16x16x32_bf16 v[88:91], v[172:175], v[196:199], v[88:91]
	v_mfma_f32_16x16x32_bf16 v[76:79], v[154:157], v[204:207], v[76:79]
	v_mfma_f32_16x16x32_bf16 v[72:75], v[172:175], v[204:207], v[72:75]
	s_barrier
	s_add_i32 s58, s41, s23
	s_add_u32 s98, s48, s2
	s_addc_u32 s99, s49, s3
	s_mov_b32 m0, s58
	ds_read_b128 v[208:211], v166
	ds_read_b128 v[212:215], v166 offset:1024
	ds_read_b128 v[216:219], v166 offset:2048
	ds_read_b128 v[220:223], v166 offset:3072
	global_load_lds_dwordx4 v132, s[48:49]
	s_add_i32 m0, s58, 0x2000
	s_nop 0
	global_load_lds_dwordx4 v128, s[48:49]
	s_barrier
	s_waitcnt lgkmcnt(0)
	v_mfma_f32_16x16x32_bf16 v[116:119], v[208:211], v[176:179], v[116:119]
	v_mfma_f32_16x16x32_bf16 v[112:115], v[216:219], v[176:179], v[112:115]
	v_mfma_f32_16x16x32_bf16 v[100:103], v[208:211], v[184:187], v[100:103]
	v_mfma_f32_16x16x32_bf16 v[96:99], v[216:219], v[184:187], v[96:99]
	v_mfma_f32_16x16x32_bf16 v[84:87], v[208:211], v[192:195], v[84:87]
	v_mfma_f32_16x16x32_bf16 v[80:83], v[216:219], v[192:195], v[80:83]
	v_mfma_f32_16x16x32_bf16 v[68:71], v[208:211], v[200:203], v[68:71]
	v_mfma_f32_16x16x32_bf16 v[64:67], v[216:219], v[200:203], v[64:67]
	v_mfma_f32_16x16x32_bf16 v[116:119], v[212:215], v[180:183], v[116:119]
	v_mfma_f32_16x16x32_bf16 v[112:115], v[220:223], v[180:183], v[112:115]
	v_mfma_f32_16x16x32_bf16 v[100:103], v[212:215], v[188:191], v[100:103]
	v_mfma_f32_16x16x32_bf16 v[96:99], v[220:223], v[188:191], v[96:99]
	v_mfma_f32_16x16x32_bf16 v[84:87], v[212:215], v[196:199], v[84:87]
	v_mfma_f32_16x16x32_bf16 v[80:83], v[220:223], v[196:199], v[80:83]
	v_mfma_f32_16x16x32_bf16 v[68:71], v[212:215], v[204:207], v[68:71]
	v_mfma_f32_16x16x32_bf16 v[64:67], v[220:223], v[204:207], v[64:67]
	s_mov_b32 m0, s27
	s_add_u32 s100, s50, s2
	s_addc_u32 s101, s51, s3
	s_barrier
	ds_read_b128 v[176:179], v165 offset:16384
	ds_read_b128 v[180:183], v165 offset:17408
	ds_read_b128 v[184:187], v165 offset:18432
	ds_read_b128 v[188:191], v165 offset:19456
	ds_read_b128 v[192:195], v165 offset:20480
	ds_read_b128 v[196:199], v165 offset:21504
	ds_read_b128 v[200:203], v165 offset:22528
	ds_read_b128 v[204:207], v165 offset:23552
	global_load_lds_dwordx4 v134, s[50:51]
	s_mov_b32 m0, s30
	s_nop 0
	global_load_lds_dwordx4 v130, s[50:51]
	s_barrier
	s_waitcnt lgkmcnt(0)
	v_mfma_f32_16x16x32_bf16 v[60:63], v[150:153], v[176:179], v[60:63]
	v_mfma_f32_16x16x32_bf16 v[56:59], v[168:171], v[176:179], v[56:59]
	v_mfma_f32_16x16x32_bf16 v[44:47], v[150:153], v[184:187], v[44:47]
	v_mfma_f32_16x16x32_bf16 v[40:43], v[168:171], v[184:187], v[40:43]
	v_mfma_f32_16x16x32_bf16 v[28:31], v[150:153], v[192:195], v[28:31]
	v_mfma_f32_16x16x32_bf16 v[24:27], v[168:171], v[192:195], v[24:27]
	v_mfma_f32_16x16x32_bf16 v[12:15], v[150:153], v[200:203], v[12:15]
	v_mfma_f32_16x16x32_bf16 v[8:11], v[168:171], v[200:203], v[8:11]
	v_mfma_f32_16x16x32_bf16 v[60:63], v[154:157], v[180:183], v[60:63]
	v_mfma_f32_16x16x32_bf16 v[56:59], v[172:175], v[180:183], v[56:59]
	v_mfma_f32_16x16x32_bf16 v[44:47], v[154:157], v[188:191], v[44:47]
	v_mfma_f32_16x16x32_bf16 v[40:43], v[172:175], v[188:191], v[40:43]
	v_mfma_f32_16x16x32_bf16 v[28:31], v[154:157], v[196:199], v[28:31]
	v_mfma_f32_16x16x32_bf16 v[24:27], v[172:175], v[196:199], v[24:27]
	v_mfma_f32_16x16x32_bf16 v[12:15], v[154:157], v[204:207], v[12:15]
	v_mfma_f32_16x16x32_bf16 v[8:11], v[172:175], v[204:207], v[8:11]
	s_barrier
	s_add_u32 s58, s48, 0x80000
	s_addc_u32 s59, s49, 0
	s_add_i32 s60, s52, s23
	s_mov_b32 m0, s60
	s_nop 0
	global_load_lds_dwordx4 v132, s[58:59]
	s_add_i32 m0, s60, 0x2000
	s_nop 0
	global_load_lds_dwordx4 v128, s[58:59]
	s_waitcnt vmcnt(6)
	s_barrier
; #define PG8_STAGE(bufoff, gbase, voff) do { _Pragma("unroll") for (int _i = 0; _i < 2; ++_i) \
;         __builtin_amdgcn_global_load_lds((const unsigned*)((const char*)(gbase) + (voff)[_i]), (LAS unsigned*)(lds + (bufoff) + ldsw + _i * 8192), 16, 0, 0); } while (0)
; #define PG8_LDA(dst, b, h) do { _Pragma("unroll") for (int m = 0; m < 4; ++m) _Pragma("unroll") for (int k = 0; k < 2; ++k) dst[m][k] = *(const LAS bf16x8*)(lds + PG8_SA(b, h) + aoff + m * 2048 + k * 1024); } while (0)
; #define PG8_LDB(dst, b, h) do { _Pragma("unroll") for (int n = 0; n < 2; ++n) _Pragma("unroll") for (int k = 0; k < 2; ++k) dst[n][k] = *(const LAS bf16x8*)(lds + PG8_SB(b, h) + boff + n * 2048 + k * 1024); } while (0)
; #define PG8_MMA(ai, bj, At, Bt) do { __builtin_amdgcn_s_setprio(1); _Pragma("unroll") for (int m = 0; m < 4; ++m) _Pragma("unroll") for (int n = 0; n < 2; ++n) _Pragma("unroll") for (int k = 0; k < 2; ++k) \
;         acc[ai][bj][m][n] = __builtin_amdgcn_mfma_f32_16x16x32_bf16(Bt[n][k], At[m][k], acc[ai][bj][m][n], 0, 0, 0); __builtin_amdgcn_s_setprio(0); } while (0)
; #define PG8_WAIT_V(n) asm volatile("s_waitcnt vmcnt(" #n ")" ::: "memory")
; #define PG8_WAIT_L(n) asm volatile("s_waitcnt lgkmcnt(" #n ")" ::: "memory")
; #define PG8_BAR __builtin_amdgcn_s_barrier()
; #define PG8_SCHED __builtin_amdgcn_sched_barrier(0)
; template <class Epi>
; __device__ __forceinline__ void gemm_phase(LAS unsigned char* lds, const Gemm g, const StaticOrder& S, const Epi& E) {
;     ...
;             PG8_WAIT_V(6); PG8_BAR; PG8_MMA(1, 1, At, B1); PG8_BAR;
;             PG8_LDB(B0, 1, 0); PG8_SCHED; PG8_LDA(At, 1, 0); PG8_STAGE(PG8_SA(0, 1), a2 + hstep, voffA);
;             PG8_WAIT_L(8); PG8_BAR; PG8_WAIT_L(0); PG8_MMA(0, 0, At, B0); PG8_BAR; PG8_SCHED;
;             PG8_LDB(B1, 1, 1); PG8_STAGE(PG8_SB(1, 0), b3, voffB);
;             PG8_BAR; PG8_WAIT_L(0); PG8_MMA(0, 1, At, B1); PG8_BAR;
;             PG8_LDA(At, 1, 1); PG8_STAGE(PG8_SA(1, 0), a3, voffA);
;             PG8_BAR; PG8_WAIT_L(0); PG8_MMA(1, 0, At, B0); PG8_BAR; PG8_SCHED;
;             PG8_STAGE(PG8_SB(1, 1), b3 + hstep, voffB);
;             PG8_WAIT_V(6); PG8_BAR; PG8_MMA(1, 1, At, B1); PG8_BAR;
	v_mfma_f32_16x16x32_bf16 v[52:55], v[208:211], v[176:179], v[52:55]
	v_mfma_f32_16x16x32_bf16 v[48:51], v[216:219], v[176:179], v[48:51]
	v_mfma_f32_16x16x32_bf16 v[36:39], v[208:211], v[184:187], v[36:39]
	v_mfma_f32_16x16x32_bf16 v[32:35], v[216:219], v[184:187], v[32:35]
	v_mfma_f32_16x16x32_bf16 v[20:23], v[208:211], v[192:195], v[20:23]
	v_mfma_f32_16x16x32_bf16 v[16:19], v[216:219], v[192:195], v[16:19]
	v_mfma_f32_16x16x32_bf16 v[4:7], v[208:211], v[200:203], v[4:7]
	v_mfma_f32_16x16x32_bf16 v[0:3], v[216:219], v[200:203], v[0:3]
	v_mfma_f32_16x16x32_bf16 v[52:55], v[212:215], v[180:183], v[52:55]
	v_mfma_f32_16x16x32_bf16 v[48:51], v[220:223], v[180:183], v[48:51]
	v_mfma_f32_16x16x32_bf16 v[36:39], v[212:215], v[188:191], v[36:39]
	v_mfma_f32_16x16x32_bf16 v[32:35], v[220:223], v[188:191], v[32:35]
	v_mfma_f32_16x16x32_bf16 v[20:23], v[212:215], v[196:199], v[20:23]
	v_mfma_f32_16x16x32_bf16 v[16:19], v[220:223], v[196:199], v[16:19]
	v_mfma_f32_16x16x32_bf16 v[4:7], v[212:215], v[204:207], v[4:7]
	v_mfma_f32_16x16x32_bf16 v[0:3], v[220:223], v[204:207], v[0:3]
	s_add_i32 s58, 0, 0x18000
	v_add_u32_e32 v136, s58, v161
	s_barrier
	ds_read_b128 v[150:153], v136
	ds_read_b128 v[154:157], v136 offset:1024
	ds_read_b128 v[168:171], v136 offset:2048
	ds_read_b128 v[172:175], v136 offset:3072
	s_add_u32 s50, s50, 0x80000
	s_addc_u32 s51, s51, 0
	s_mov_b32 m0, s31
	ds_read_b128 v[176:179], v165 offset:32768
	ds_read_b128 v[180:183], v165 offset:33792
	ds_read_b128 v[184:187], v165 offset:34816
	ds_read_b128 v[188:191], v165 offset:35840
	ds_read_b128 v[192:195], v165 offset:36864
	ds_read_b128 v[196:199], v165 offset:37888
	ds_read_b128 v[200:203], v165 offset:38912
	ds_read_b128 v[204:207], v165 offset:39936
	global_load_lds_dwordx4 v134, s[50:51]
	s_mov_b32 m0, s33
	s_nop 0
	global_load_lds_dwordx4 v130, s[50:51]
	s_waitcnt lgkmcnt(8)
	s_barrier
	s_waitcnt lgkmcnt(0)
	v_mfma_f32_16x16x32_bf16 v[124:127], v[150:153], v[176:179], v[124:127]
	v_mfma_f32_16x16x32_bf16 v[120:123], v[168:171], v[176:179], v[120:123]
	v_mfma_f32_16x16x32_bf16 v[108:111], v[150:153], v[184:187], v[108:111]
	v_mfma_f32_16x16x32_bf16 v[104:107], v[168:171], v[184:187], v[104:107]
	v_mfma_f32_16x16x32_bf16 v[92:95], v[150:153], v[192:195], v[92:95]
	v_mfma_f32_16x16x32_bf16 v[88:91], v[168:171], v[192:195], v[88:91]
	v_mfma_f32_16x16x32_bf16 v[76:79], v[150:153], v[200:203], v[76:79]
	v_mfma_f32_16x16x32_bf16 v[72:75], v[168:171], v[200:203], v[72:75]
	v_mfma_f32_16x16x32_bf16 v[124:127], v[154:157], v[180:183], v[124:127]
	v_mfma_f32_16x16x32_bf16 v[120:123], v[172:175], v[180:183], v[120:123]
	v_mfma_f32_16x16x32_bf16 v[108:111], v[154:157], v[188:191], v[108:111]
	v_mfma_f32_16x16x32_bf16 v[104:107], v[172:175], v[188:191], v[104:107]
	v_mfma_f32_16x16x32_bf16 v[92:95], v[154:157], v[196:199], v[92:95]
	v_mfma_f32_16x16x32_bf16 v[88:91], v[172:175], v[196:199], v[88:91]
	v_mfma_f32_16x16x32_bf16 v[76:79], v[154:157], v[204:207], v[76:79]
	v_mfma_f32_16x16x32_bf16 v[72:75], v[172:175], v[204:207], v[72:75]
	s_barrier
	s_add_i32 s50, 0, 0x1c000
	s_add_i32 s51, s58, s23
	v_add_u32_e32 v136, s50, v161
	s_mov_b32 m0, s51
	ds_read_b128 v[208:211], v136
	ds_read_b128 v[212:215], v136 offset:1024
	ds_read_b128 v[216:219], v136 offset:2048
	ds_read_b128 v[220:223], v136 offset:3072
	global_load_lds_dwordx4 v132, s[98:99]
	s_add_i32 m0, s51, 0x2000
	s_nop 0
	global_load_lds_dwordx4 v128, s[98:99]
	s_barrier
	s_waitcnt lgkmcnt(0)
	v_mfma_f32_16x16x32_bf16 v[116:119], v[208:211], v[176:179], v[116:119]
	v_mfma_f32_16x16x32_bf16 v[112:115], v[216:219], v[176:179], v[112:115]
	v_mfma_f32_16x16x32_bf16 v[100:103], v[208:211], v[184:187], v[100:103]
	v_mfma_f32_16x16x32_bf16 v[96:99], v[216:219], v[184:187], v[96:99]
	v_mfma_f32_16x16x32_bf16 v[84:87], v[208:211], v[192:195], v[84:87]
	v_mfma_f32_16x16x32_bf16 v[80:83], v[216:219], v[192:195], v[80:83]
	v_mfma_f32_16x16x32_bf16 v[68:71], v[208:211], v[200:203], v[68:71]
	v_mfma_f32_16x16x32_bf16 v[64:67], v[216:219], v[200:203], v[64:67]
	v_mfma_f32_16x16x32_bf16 v[116:119], v[212:215], v[180:183], v[116:119]
	v_mfma_f32_16x16x32_bf16 v[112:115], v[220:223], v[180:183], v[112:115]
	v_mfma_f32_16x16x32_bf16 v[100:103], v[212:215], v[188:191], v[100:103]
	v_mfma_f32_16x16x32_bf16 v[96:99], v[220:223], v[188:191], v[96:99]
	v_mfma_f32_16x16x32_bf16 v[84:87], v[212:215], v[196:199], v[84:87]
	v_mfma_f32_16x16x32_bf16 v[80:83], v[220:223], v[196:199], v[80:83]
	v_mfma_f32_16x16x32_bf16 v[68:71], v[212:215], v[204:207], v[68:71]
	v_mfma_f32_16x16x32_bf16 v[64:67], v[220:223], v[204:207], v[64:67]
	s_mov_b32 m0, s37
	s_barrier
	ds_read_b128 v[176:179], v165 offset:49152
	ds_read_b128 v[180:183], v165 offset:50176
	ds_read_b128 v[184:187], v165 offset:51200
	ds_read_b128 v[188:191], v165 offset:52224
	ds_read_b128 v[192:195], v165 offset:53248
	ds_read_b128 v[196:199], v165 offset:54272
	ds_read_b128 v[200:203], v165 offset:55296
	ds_read_b128 v[204:207], v165 offset:56320
	global_load_lds_dwordx4 v134, s[100:101]
	s_mov_b32 m0, s38
	s_nop 0
	global_load_lds_dwordx4 v130, s[100:101]
	s_barrier
; #define PG8_STAGE(bufoff, gbase, voff) do { _Pragma("unroll") for (int _i = 0; _i < 2; ++_i) \
;         __builtin_amdgcn_global_load_lds((const unsigned*)((const char*)(gbase) + (voff)[_i]), (LAS unsigned*)(lds + (bufoff) + ldsw + _i * 8192), 16, 0, 0); } while (0)
; #define PG8_MMA(ai, bj, At, Bt) do { __builtin_amdgcn_s_setprio(1); _Pragma("unroll") for (int m = 0; m < 4; ++m) _Pragma("unroll") for (int n = 0; n < 2; ++n) _Pragma("unroll") for (int k = 0; k < 2; ++k) \
;         acc[ai][bj][m][n] = __builtin_amdgcn_mfma_f32_16x16x32_bf16(Bt[n][k], At[m][k], acc[ai][bj][m][n], 0, 0, 0); __builtin_amdgcn_s_setprio(0); } while (0)
; #define PG8_WAIT_V(n) asm volatile("s_waitcnt vmcnt(" #n ")" ::: "memory")
; #define PG8_BAR __builtin_amdgcn_s_barrier()
; __device__ __forceinline__ u32x4 pack8(f32x4 v0, f32x4 v1) { u32x4 w; w.x = cvt_pk_bf16(v0[0], v0[1]); w.y = cvt_pk_bf16(v0[2], v0[3]); w.z = cvt_pk_bf16(v1[0], v1[1]); w.w = cvt_pk_bf16(v1[2], v1[3]); return w; }
; template <class Epi>
; __device__ __forceinline__ void gemm_phase(LAS unsigned char* lds, const Gemm g, const StaticOrder& S, const Epi& E) {
;     ...
;             PG8_STAGE(PG8_SB(1, 1), b3 + hstep, voffB);
;             PG8_WAIT_V(6); PG8_BAR; PG8_MMA(1, 1, At, B1); PG8_BAR;
;     __device__ __forceinline__ void operator()(const f32x4 (&acc)[2][2][4][2], const Unit& u, int wr, int wc, int fr, int fq) const {
;     ...
;         } else {
;             const int col0 = u.pn * BM + wc * 32 + 8 * fq; const float sc = (u.pn < 2) ? QSCALE : 1.0f;
; #pragma unroll
;             for (int ai = 0; ai < 2; ++ai)
; #pragma unroll
;                 for (int m = 0; m < 4; ++m) { bf16_t* rowp = O + (size_t)(row0 + ai * HALF + m * 16) * NQKV + col0; const float scr_ = sc * rowsc[row0 + ai * HALF + m * 16];
; #pragma unroll
;                     for (int bj = 0; bj < 2; ++bj) *(u32x4*)(rowp + bj * HALF) = pack8(acc[ai][bj][m][0] * scr_, acc[ai][bj][m][1] * scr_); }
	s_waitcnt lgkmcnt(0)
	v_mfma_f32_16x16x32_bf16 v[60:63], v[150:153], v[176:179], v[60:63]
	v_mfma_f32_16x16x32_bf16 v[56:59], v[168:171], v[176:179], v[56:59]
	v_mfma_f32_16x16x32_bf16 v[44:47], v[150:153], v[184:187], v[44:47]
	v_mfma_f32_16x16x32_bf16 v[40:43], v[168:171], v[184:187], v[40:43]
	v_mfma_f32_16x16x32_bf16 v[28:31], v[150:153], v[192:195], v[28:31]
	v_mfma_f32_16x16x32_bf16 v[24:27], v[168:171], v[192:195], v[24:27]
	v_mfma_f32_16x16x32_bf16 v[12:15], v[150:153], v[200:203], v[12:15]
	v_mfma_f32_16x16x32_bf16 v[8:11], v[168:171], v[200:203], v[8:11]
	v_mfma_f32_16x16x32_bf16 v[60:63], v[154:157], v[180:183], v[60:63]
	v_mfma_f32_16x16x32_bf16 v[56:59], v[172:175], v[180:183], v[56:59]
	v_mfma_f32_16x16x32_bf16 v[44:47], v[154:157], v[188:191], v[44:47]
	v_mfma_f32_16x16x32_bf16 v[40:43], v[172:175], v[188:191], v[40:43]
	v_mfma_f32_16x16x32_bf16 v[28:31], v[154:157], v[196:199], v[28:31]
	v_mfma_f32_16x16x32_bf16 v[24:27], v[172:175], v[196:199], v[24:27]
	v_mfma_f32_16x16x32_bf16 v[12:15], v[154:157], v[204:207], v[12:15]
	v_mfma_f32_16x16x32_bf16 v[8:11], v[172:175], v[204:207], v[8:11]
	s_barrier
	s_add_u32 s48, s48, 0x80080
	s_addc_u32 s49, s49, 0
	s_add_i32 s50, s50, s23
	s_mov_b32 m0, s50
	s_nop 0
	global_load_lds_dwordx4 v132, s[48:49]
	s_add_i32 m0, s50, 0x2000
	s_nop 0
	global_load_lds_dwordx4 v128, s[48:49]
	s_add_i32 s57, s57, 2
	s_add_u32 s46, s46, 0x100
	s_addc_u32 s47, s47, 0
	s_add_u32 s55, s55, 0x100
	s_addc_u32 s56, s56, 0
	s_cmp_gt_u32 s57, 29
	s_waitcnt vmcnt(6)
	s_barrier
	v_mfma_f32_16x16x32_bf16 v[52:55], v[208:211], v[176:179], v[52:55]
	v_mfma_f32_16x16x32_bf16 v[48:51], v[216:219], v[176:179], v[48:51]
	v_mfma_f32_16x16x32_bf16 v[36:39], v[208:211], v[184:187], v[36:39]
	v_mfma_f32_16x16x32_bf16 v[32:35], v[216:219], v[184:187], v[32:35]
	v_mfma_f32_16x16x32_bf16 v[20:23], v[208:211], v[192:195], v[20:23]
	v_mfma_f32_16x16x32_bf16 v[16:19], v[216:219], v[192:195], v[16:19]
	v_mfma_f32_16x16x32_bf16 v[4:7], v[208:211], v[200:203], v[4:7]
	v_mfma_f32_16x16x32_bf16 v[0:3], v[216:219], v[200:203], v[0:3]
	v_mfma_f32_16x16x32_bf16 v[52:55], v[212:215], v[180:183], v[52:55]
	v_mfma_f32_16x16x32_bf16 v[48:51], v[220:223], v[180:183], v[48:51]
	v_mfma_f32_16x16x32_bf16 v[36:39], v[212:215], v[188:191], v[36:39]
	v_mfma_f32_16x16x32_bf16 v[32:35], v[220:223], v[188:191], v[32:35]
	v_mfma_f32_16x16x32_bf16 v[20:23], v[212:215], v[196:199], v[20:23]
	v_mfma_f32_16x16x32_bf16 v[16:19], v[220:223], v[196:199], v[16:19]
	v_mfma_f32_16x16x32_bf16 v[4:7], v[212:215], v[204:207], v[4:7]
	v_mfma_f32_16x16x32_bf16 v[0:3], v[220:223], v[204:207], v[0:3]
	s_barrier
	s_cbranch_scc0 .LBB0_407
	v_lshl_add_u32 v154, s44, 8, v160
	s_add_i32 s9, s34, -6
	s_lshl_b32 s7, s34, 8
	s_cmp_gt_u32 s9, 11
	s_mov_b64 s[44:45], -1
	v_ashrrev_i32_e32 v155, 31, v154
	v_or_b32_e32 v174, 16, v154
	v_or_b32_e32 v173, 32, v154
	v_or_b32_e32 v172, 48, v154
	v_add_u32_e32 v171, 0x80, v154
	v_add_u32_e32 v170, 0x90, v154
	v_add_u32_e32 v169, 0xa0, v154
	v_add_u32_e32 v168, 0xb0, v154
	s_cbranch_scc0 .LBB0_410
	v_lshl_add_u64 v[150:151], v[154:155], 2, s[14:15]
	global_load_dword v136, v[150:151], off
	global_load_dword v204, v[150:151], off offset:64
	global_load_dword v205, v[150:151], off offset:128
	global_load_dword v206, v[150:151], off offset:192
	global_load_dword v207, v[150:151], off offset:512
	global_load_dword v208, v[150:151], off offset:576
	global_load_dword v209, v[150:151], off offset:640
	global_load_dword v210, v[150:151], off offset:704
	s_cmp_lt_i32 s34, 2
	v_or_b32_e32 v156, s7, v162
	s_cselect_b64 vcc, -1, 0
	v_mov_b64_e32 v[152:153], s[20:21]
	v_cndmask_b32_e32 v175, 1.0, v167, vcc
	v_ashrrev_i32_e32 v157, 31, v156
	v_mad_i64_i32 v[176:177], s[44:45], v154, s53, v[152:153]
	v_lshlrev_b64 v[156:157], 1, v[156:157]
	v_lshl_add_u64 v[180:181], v[176:177], 0, v[156:157]
	s_waitcnt vmcnt(0)
	v_mul_f32_e32 v136, v175, v136
	v_pk_mul_f32 v[178:179], v[126:127], v[136:137] op_sel_hi:[1,0]
	v_pk_mul_f32 v[176:177], v[124:125], v[136:137] op_sel_hi:[1,0]
	v_pk_mul_f32 v[182:183], v[122:123], v[136:137] op_sel_hi:[1,0]
	v_pk_mul_f32 v[184:185], v[120:121], v[136:137] op_sel_hi:[1,0]
	v_cvt_pk_bf16_f32 v176, v176, v177
	v_cvt_pk_bf16_f32 v177, v178, v179
	v_pk_mul_f32 v[186:187], v[118:119], v[136:137] op_sel_hi:[1,0]
	v_cvt_pk_bf16_f32 v178, v184, v185
	v_cvt_pk_bf16_f32 v179, v182, v183
	v_pk_mul_f32 v[188:189], v[116:117], v[136:137] op_sel_hi:[1,0]
	v_pk_mul_f32 v[190:191], v[114:115], v[136:137] op_sel_hi:[1,0]
	v_pk_mul_f32 v[192:193], v[112:113], v[136:137] op_sel_hi:[1,0]
	global_store_dwordx4 v[180:181], v[176:179], off
	s_nop 1
	v_cvt_pk_bf16_f32 v176, v188, v189
	v_cvt_pk_bf16_f32 v177, v186, v187
	v_cvt_pk_bf16_f32 v178, v192, v193
	v_cvt_pk_bf16_f32 v179, v190, v191
	global_store_dwordx4 v[180:181], v[176:179], off offset:256
	s_nop 1
	v_mov_b32_e32 v136, v204
	v_mul_f32_e32 v136, v175, v136
	v_mad_i64_i32 v[176:177], s[44:45], v174, s53, v[152:153]
	v_lshl_add_u64 v[180:181], v[176:177], 0, v[156:157]
	v_pk_mul_f32 v[178:179], v[110:111], v[136:137] op_sel_hi:[1,0]
	v_pk_mul_f32 v[176:177], v[108:109], v[136:137] op_sel_hi:[1,0]
	v_pk_mul_f32 v[182:183], v[106:107], v[136:137] op_sel_hi:[1,0]
	v_pk_mul_f32 v[184:185], v[104:105], v[136:137] op_sel_hi:[1,0]
	v_cvt_pk_bf16_f32 v176, v176, v177
	v_cvt_pk_bf16_f32 v177, v178, v179
	v_pk_mul_f32 v[186:187], v[102:103], v[136:137] op_sel_hi:[1,0]
	v_cvt_pk_bf16_f32 v178, v184, v185
	v_cvt_pk_bf16_f32 v179, v182, v183
	v_pk_mul_f32 v[188:189], v[100:101], v[136:137] op_sel_hi:[1,0]
	v_pk_mul_f32 v[190:191], v[98:99], v[136:137] op_sel_hi:[1,0]
; __device__ __forceinline__ u32x4 pack8(f32x4 v0, f32x4 v1) { u32x4 w; w.x = cvt_pk_bf16(v0[0], v0[1]); w.y = cvt_pk_bf16(v0[2], v0[3]); w.z = cvt_pk_bf16(v1[0], v1[1]); w.w = cvt_pk_bf16(v1[2], v1[3]); return w; }
;     __device__ __forceinline__ void operator()(const f32x4 (&acc)[2][2][4][2], const Unit& u, int wr, int wc, int fr, int fq) const {
;     ...
;         } else {
;             const int col0 = u.pn * BM + wc * 32 + 8 * fq; const float sc = (u.pn < 2) ? QSCALE : 1.0f;
; #pragma unroll
;             for (int ai = 0; ai < 2; ++ai)
; #pragma unroll
;                 for (int m = 0; m < 4; ++m) { bf16_t* rowp = O + (size_t)(row0 + ai * HALF + m * 16) * NQKV + col0; const float scr_ = sc * rowsc[row0 + ai * HALF + m * 16];
; #pragma unroll
;                     for (int bj = 0; bj < 2; ++bj) *(u32x4*)(rowp + bj * HALF) = pack8(acc[ai][bj][m][0] * scr_, acc[ai][bj][m][1] * scr_); }
	v_pk_mul_f32 v[192:193], v[96:97], v[136:137] op_sel_hi:[1,0]
	global_store_dwordx4 v[180:181], v[176:179], off
	s_nop 1
	v_cvt_pk_bf16_f32 v176, v188, v189
	v_cvt_pk_bf16_f32 v177, v186, v187
	v_cvt_pk_bf16_f32 v178, v192, v193
	v_cvt_pk_bf16_f32 v179, v190, v191
	global_store_dwordx4 v[180:181], v[176:179], off offset:256
	s_nop 1
	v_mov_b32_e32 v136, v205
	v_mul_f32_e32 v136, v175, v136
	v_mad_i64_i32 v[176:177], s[44:45], v173, s53, v[152:153]
	v_lshl_add_u64 v[180:181], v[176:177], 0, v[156:157]
	v_pk_mul_f32 v[178:179], v[94:95], v[136:137] op_sel_hi:[1,0]
	v_pk_mul_f32 v[176:177], v[92:93], v[136:137] op_sel_hi:[1,0]
	v_pk_mul_f32 v[182:183], v[90:91], v[136:137] op_sel_hi:[1,0]
	v_pk_mul_f32 v[184:185], v[88:89], v[136:137] op_sel_hi:[1,0]
	v_cvt_pk_bf16_f32 v176, v176, v177
	v_cvt_pk_bf16_f32 v177, v178, v179
	v_pk_mul_f32 v[186:187], v[86:87], v[136:137] op_sel_hi:[1,0]
	v_cvt_pk_bf16_f32 v178, v184, v185
	v_cvt_pk_bf16_f32 v179, v182, v183
	v_pk_mul_f32 v[188:189], v[84:85], v[136:137] op_sel_hi:[1,0]
	v_pk_mul_f32 v[190:191], v[82:83], v[136:137] op_sel_hi:[1,0]
	v_pk_mul_f32 v[192:193], v[80:81], v[136:137] op_sel_hi:[1,0]
	global_store_dwordx4 v[180:181], v[176:179], off
	s_nop 1
	v_cvt_pk_bf16_f32 v176, v188, v189
	v_cvt_pk_bf16_f32 v177, v186, v187
	v_cvt_pk_bf16_f32 v178, v192, v193
	v_cvt_pk_bf16_f32 v179, v190, v191
	global_store_dwordx4 v[180:181], v[176:179], off offset:256
	s_nop 1
	v_mov_b32_e32 v136, v206
	v_mul_f32_e32 v136, v175, v136
	v_mad_i64_i32 v[176:177], s[44:45], v172, s53, v[152:153]
	v_lshl_add_u64 v[180:181], v[176:177], 0, v[156:157]
	v_pk_mul_f32 v[178:179], v[78:79], v[136:137] op_sel_hi:[1,0]
	v_pk_mul_f32 v[176:177], v[76:77], v[136:137] op_sel_hi:[1,0]
	v_pk_mul_f32 v[182:183], v[74:75], v[136:137] op_sel_hi:[1,0]
	v_pk_mul_f32 v[184:185], v[72:73], v[136:137] op_sel_hi:[1,0]
	v_cvt_pk_bf16_f32 v176, v176, v177
	v_cvt_pk_bf16_f32 v177, v178, v179
	v_pk_mul_f32 v[186:187], v[70:71], v[136:137] op_sel_hi:[1,0]
	v_cvt_pk_bf16_f32 v178, v184, v185
	v_cvt_pk_bf16_f32 v179, v182, v183
	v_pk_mul_f32 v[188:189], v[68:69], v[136:137] op_sel_hi:[1,0]
	v_pk_mul_f32 v[190:191], v[66:67], v[136:137] op_sel_hi:[1,0]
	v_pk_mul_f32 v[192:193], v[64:65], v[136:137] op_sel_hi:[1,0]
	global_store_dwordx4 v[180:181], v[176:179], off
	s_nop 1
	v_cvt_pk_bf16_f32 v176, v188, v189
	v_cvt_pk_bf16_f32 v177, v186, v187
	v_cvt_pk_bf16_f32 v178, v192, v193
	v_cvt_pk_bf16_f32 v179, v190, v191
	global_store_dwordx4 v[180:181], v[176:179], off offset:256
	s_nop 1
	v_mov_b32_e32 v136, v207
	v_mul_f32_e32 v136, v175, v136
	v_mad_i64_i32 v[176:177], s[44:45], v171, s53, v[152:153]
	v_lshl_add_u64 v[180:181], v[176:177], 0, v[156:157]
	v_pk_mul_f32 v[178:179], v[62:63], v[136:137] op_sel_hi:[1,0]
	v_pk_mul_f32 v[176:177], v[60:61], v[136:137] op_sel_hi:[1,0]
	v_pk_mul_f32 v[182:183], v[58:59], v[136:137] op_sel_hi:[1,0]
	v_pk_mul_f32 v[184:185], v[56:57], v[136:137] op_sel_hi:[1,0]
	v_cvt_pk_bf16_f32 v176, v176, v177
	v_cvt_pk_bf16_f32 v177, v178, v179
	v_pk_mul_f32 v[186:187], v[54:55], v[136:137] op_sel_hi:[1,0]
	v_cvt_pk_bf16_f32 v178, v184, v185
	v_cvt_pk_bf16_f32 v179, v182, v183
	v_pk_mul_f32 v[188:189], v[52:53], v[136:137] op_sel_hi:[1,0]
	v_pk_mul_f32 v[190:191], v[50:51], v[136:137] op_sel_hi:[1,0]
	v_pk_mul_f32 v[192:193], v[48:49], v[136:137] op_sel_hi:[1,0]
	global_store_dwordx4 v[180:181], v[176:179], off
	s_nop 1
	v_cvt_pk_bf16_f32 v176, v188, v189
	v_cvt_pk_bf16_f32 v177, v186, v187
	v_cvt_pk_bf16_f32 v178, v192, v193
	v_cvt_pk_bf16_f32 v179, v190, v191
	global_store_dwordx4 v[180:181], v[176:179], off offset:256
	s_nop 1
	v_mov_b32_e32 v136, v208
	v_mul_f32_e32 v136, v175, v136
	v_mad_i64_i32 v[176:177], s[44:45], v170, s53, v[152:153]
	v_lshl_add_u64 v[180:181], v[176:177], 0, v[156:157]
	v_pk_mul_f32 v[178:179], v[46:47], v[136:137] op_sel_hi:[1,0]
	v_pk_mul_f32 v[176:177], v[44:45], v[136:137] op_sel_hi:[1,0]
	v_pk_mul_f32 v[182:183], v[42:43], v[136:137] op_sel_hi:[1,0]
	v_pk_mul_f32 v[184:185], v[40:41], v[136:137] op_sel_hi:[1,0]
	v_cvt_pk_bf16_f32 v176, v176, v177
	v_cvt_pk_bf16_f32 v177, v178, v179
	v_pk_mul_f32 v[186:187], v[38:39], v[136:137] op_sel_hi:[1,0]
	v_cvt_pk_bf16_f32 v178, v184, v185
	v_cvt_pk_bf16_f32 v179, v182, v183
	v_pk_mul_f32 v[188:189], v[36:37], v[136:137] op_sel_hi:[1,0]
	v_pk_mul_f32 v[190:191], v[34:35], v[136:137] op_sel_hi:[1,0]
	v_pk_mul_f32 v[192:193], v[32:33], v[136:137] op_sel_hi:[1,0]
	global_store_dwordx4 v[180:181], v[176:179], off
	s_nop 1
	v_cvt_pk_bf16_f32 v176, v188, v189
	v_cvt_pk_bf16_f32 v177, v186, v187
	v_cvt_pk_bf16_f32 v178, v192, v193
	v_cvt_pk_bf16_f32 v179, v190, v191
	global_store_dwordx4 v[180:181], v[176:179], off offset:256
	s_nop 1
	v_mov_b32_e32 v136, v209
	v_mul_f32_e32 v136, v175, v136
	v_mad_i64_i32 v[176:177], s[44:45], v169, s53, v[152:153]
	v_lshl_add_u64 v[180:181], v[176:177], 0, v[156:157]
	v_pk_mul_f32 v[178:179], v[30:31], v[136:137] op_sel_hi:[1,0]
	v_pk_mul_f32 v[176:177], v[28:29], v[136:137] op_sel_hi:[1,0]
	v_pk_mul_f32 v[182:183], v[26:27], v[136:137] op_sel_hi:[1,0]
	v_pk_mul_f32 v[184:185], v[24:25], v[136:137] op_sel_hi:[1,0]
	v_cvt_pk_bf16_f32 v176, v176, v177
	v_cvt_pk_bf16_f32 v177, v178, v179
	v_pk_mul_f32 v[186:187], v[22:23], v[136:137] op_sel_hi:[1,0]
	v_cvt_pk_bf16_f32 v178, v184, v185
	v_cvt_pk_bf16_f32 v179, v182, v183
	v_pk_mul_f32 v[188:189], v[20:21], v[136:137] op_sel_hi:[1,0]
	v_pk_mul_f32 v[190:191], v[18:19], v[136:137] op_sel_hi:[1,0]
	v_pk_mul_f32 v[192:193], v[16:17], v[136:137] op_sel_hi:[1,0]
	global_store_dwordx4 v[180:181], v[176:179], off
	s_nop 1
	v_cvt_pk_bf16_f32 v176, v188, v189
	v_cvt_pk_bf16_f32 v177, v186, v187
	v_cvt_pk_bf16_f32 v178, v192, v193
	v_cvt_pk_bf16_f32 v179, v190, v191
	global_store_dwordx4 v[180:181], v[176:179], off offset:256
	s_nop 1
	v_mov_b32_e32 v136, v210
	v_mad_i64_i32 v[150:151], s[44:45], v168, s53, v[152:153]
	v_lshl_add_u64 v[156:157], v[150:151], 0, v[156:157]
	s_mov_b64 s[44:45], 0
	v_mul_f32_e32 v136, v175, v136
	v_pk_mul_f32 v[152:153], v[14:15], v[136:137] op_sel_hi:[1,0]
	v_pk_mul_f32 v[150:151], v[12:13], v[136:137] op_sel_hi:[1,0]
	v_pk_mul_f32 v[176:177], v[10:11], v[136:137] op_sel_hi:[1,0]
	v_pk_mul_f32 v[178:179], v[8:9], v[136:137] op_sel_hi:[1,0]
	v_cvt_pk_bf16_f32 v150, v150, v151
	v_cvt_pk_bf16_f32 v151, v152, v153
	v_pk_mul_f32 v[180:181], v[6:7], v[136:137] op_sel_hi:[1,0]
	v_cvt_pk_bf16_f32 v152, v178, v179
	v_cvt_pk_bf16_f32 v153, v176, v177
	v_pk_mul_f32 v[182:183], v[4:5], v[136:137] op_sel_hi:[1,0]
	v_pk_mul_f32 v[184:185], v[2:3], v[136:137] op_sel_hi:[1,0]
	v_pk_mul_f32 v[186:187], v[0:1], v[136:137] op_sel_hi:[1,0]
	global_store_dwordx4 v[156:157], v[150:153], off
	s_nop 1
	v_cvt_pk_bf16_f32 v150, v182, v183
	v_cvt_pk_bf16_f32 v151, v180, v181
	v_cvt_pk_bf16_f32 v152, v186, v187
	v_cvt_pk_bf16_f32 v153, v184, v185
	global_store_dwordx4 v[156:157], v[150:153], off offset:256

; #define PG8_STAGE(bufoff, gbase, voff) do { _Pragma("unroll") for (int _i = 0; _i < 2; ++_i) \
;         __builtin_amdgcn_global_load_lds((const unsigned*)((const char*)(gbase) + (voff)[_i]), (LAS unsigned*)(lds + (bufoff) + ldsw + _i * 8192), 16, 0, 0); } while (0)
; #define PG8_LDA(dst, b, h) do { _Pragma("unroll") for (int m = 0; m < 4; ++m) _Pragma("unroll") for (int k = 0; k < 2; ++k) dst[m][k] = *(const LAS bf16x8*)(lds + PG8_SA(b, h) + aoff + m * 2048 + k * 1024); } while (0)
; #define PG8_WAIT_V(n) asm volatile("s_waitcnt vmcnt(" #n ")" ::: "memory")
; #define PG8_WAIT_L(n) asm volatile("s_waitcnt lgkmcnt(" #n ")" ::: "memory")
; template <class Epi>
; __device__ __forceinline__ void gemm_phase(LAS unsigned char* lds, const Gemm g, const StaticOrder& S, const Epi& E) {
;     ...
;         for (int t = 0; t < nt; t += 2) {
;             const bool last = (t == nt - 2);
;             const char* a1 = cA + (size_t)(t + 1) * kstep;
;             const char* a2 = last ? nA : cA + (size_t)(t + 2) * kstep; const char* b2 = last ? nB : cB + (size_t)(t + 2) * kstep;
;             const char* a3 = a2 + kstep; const char* b3 = b2 + kstep;
;             PG8_LDB(B0, 0, 0); PG8_SCHED; PG8_LDA(At, 0, 0); PG8_STAGE(PG8_SA(1, 1), a1 + hstep, voffA);
;             PG8_WAIT_L(8); PG8_BAR; PG8_WAIT_L(0); PG8_MMA(0, 0, At, B0); PG8_BAR; PG8_SCHED;
;             PG8_LDB(B1, 0, 1); PG8_STAGE(PG8_SB(0, 0), b2, voffB);
;             PG8_BAR; PG8_WAIT_L(0); PG8_MMA(0, 1, At, B1); PG8_BAR;
;             PG8_LDA(At, 0, 1); PG8_STAGE(PG8_SA(0, 0), a2, voffA);
;             PG8_BAR; PG8_WAIT_L(0); PG8_MMA(1, 0, At, B0); PG8_BAR; PG8_SCHED;
;             PG8_STAGE(PG8_SB(0, 1), b2 + hstep, voffB);
;             PG8_WAIT_V(6); PG8_BAR; PG8_MMA(1, 1, At, B1); PG8_BAR;
;             PG8_LDB(B0, 1, 0); PG8_SCHED; PG8_LDA(At, 1, 0); PG8_STAGE(PG8_SA(0, 1), a2 + hstep, voffA);
;             PG8_WAIT_L(8); PG8_BAR; PG8_WAIT_L(0); PG8_MMA(0, 0, At, B0); PG8_BAR; PG8_SCHED;
;             PG8_LDB(B1, 1, 1); PG8_STAGE(PG8_SB(1, 0), b3, voffB);
;             PG8_BAR; PG8_WAIT_L(0); PG8_MMA(0, 1, At, B1); PG8_BAR;
;             PG8_LDA(At, 1, 1); PG8_STAGE(PG8_SA(1, 0), a3, voffA);
;             PG8_BAR; PG8_WAIT_L(0); PG8_MMA(1, 0, At, B0); PG8_BAR; PG8_SCHED;
;             PG8_STAGE(PG8_SB(1, 1), b3 + hstep, voffB);
;             PG8_WAIT_V(6); PG8_BAR; PG8_MMA(1, 1, At, B1); PG8_BAR;
.LBB0_673:
	ds_read_b128 v[148:151], v145
	ds_read_b128 v[152:155], v145 offset:1024
	ds_read_b128 v[160:163], v145 offset:2048
	ds_read_b128 v[164:167], v145 offset:3072
	s_add_u32 s52, s50, 0xfff80080
	s_addc_u32 s53, s51, -1
	s_cmp_eq_u32 s69, 28
	s_cselect_b32 s55, s43, s53
	s_cselect_b32 s54, s65, s52
	s_cselect_b32 s53, s41, s68
	s_cselect_b32 s52, s66, s67
	s_add_i32 m0, s28, 0xc000
	ds_read_b128 v[168:171], v146
	ds_read_b128 v[172:175], v146 offset:1024
	ds_read_b128 v[176:179], v146 offset:2048
	ds_read_b128 v[180:183], v146 offset:3072
	ds_read_b128 v[184:187], v146 offset:4096
	ds_read_b128 v[188:191], v146 offset:5120
	ds_read_b128 v[192:195], v146 offset:6144
	ds_read_b128 v[196:199], v146 offset:7168
	global_load_lds_dwordx4 v136, s[50:51]
	s_add_i32 m0, s28, 0xe000
	s_nop 0
	global_load_lds_dwordx4 v138, s[50:51]
	s_waitcnt lgkmcnt(8)
	s_barrier
	s_waitcnt lgkmcnt(0)
	v_mfma_f32_16x16x32_bf16 v[124:127], v[148:151], v[168:171], v[124:127]
	v_mfma_f32_16x16x32_bf16 v[120:123], v[160:163], v[168:171], v[120:123]
	v_mfma_f32_16x16x32_bf16 v[112:115], v[148:151], v[176:179], v[112:115]
	v_mfma_f32_16x16x32_bf16 v[104:107], v[160:163], v[176:179], v[104:107]
	v_mfma_f32_16x16x32_bf16 v[96:99], v[148:151], v[184:187], v[96:99]
	v_mfma_f32_16x16x32_bf16 v[88:91], v[160:163], v[184:187], v[88:91]
	v_mfma_f32_16x16x32_bf16 v[80:83], v[148:151], v[192:195], v[80:83]
	v_mfma_f32_16x16x32_bf16 v[72:75], v[160:163], v[192:195], v[72:75]
	v_mfma_f32_16x16x32_bf16 v[124:127], v[152:155], v[172:175], v[124:127]
	v_mfma_f32_16x16x32_bf16 v[120:123], v[164:167], v[172:175], v[120:123]
	v_mfma_f32_16x16x32_bf16 v[112:115], v[152:155], v[180:183], v[112:115]
	v_mfma_f32_16x16x32_bf16 v[104:107], v[164:167], v[180:183], v[104:107]
	v_mfma_f32_16x16x32_bf16 v[96:99], v[152:155], v[188:191], v[96:99]
	v_mfma_f32_16x16x32_bf16 v[88:91], v[164:167], v[188:191], v[88:91]
	v_mfma_f32_16x16x32_bf16 v[80:83], v[152:155], v[196:199], v[80:83]
	v_mfma_f32_16x16x32_bf16 v[72:75], v[164:167], v[196:199], v[72:75]
	s_barrier
	s_add_i32 s70, s58, s23
	s_add_u32 s98, s52, s6
	s_addc_u32 s99, s53, s7
	s_mov_b32 m0, s70
	ds_read_b128 v[200:203], v147
	ds_read_b128 v[204:207], v147 offset:1024
	ds_read_b128 v[208:211], v147 offset:2048
	ds_read_b128 v[212:215], v147 offset:3072
	global_load_lds_dwordx4 v132, s[52:53]
	s_add_i32 m0, s70, 0x2000
	s_nop 0
	global_load_lds_dwordx4 v128, s[52:53]
	s_barrier
	s_waitcnt lgkmcnt(0)
	v_mfma_f32_16x16x32_bf16 v[116:119], v[200:203], v[168:171], v[116:119]
	v_mfma_f32_16x16x32_bf16 v[108:111], v[208:211], v[168:171], v[108:111]
	v_mfma_f32_16x16x32_bf16 v[100:103], v[200:203], v[176:179], v[100:103]
	v_mfma_f32_16x16x32_bf16 v[92:95], v[208:211], v[176:179], v[92:95]
	v_mfma_f32_16x16x32_bf16 v[84:87], v[200:203], v[184:187], v[84:87]
	v_mfma_f32_16x16x32_bf16 v[76:79], v[208:211], v[184:187], v[76:79]
	v_mfma_f32_16x16x32_bf16 v[68:71], v[200:203], v[192:195], v[68:71]
	v_mfma_f32_16x16x32_bf16 v[64:67], v[208:211], v[192:195], v[64:67]
	v_mfma_f32_16x16x32_bf16 v[116:119], v[204:207], v[172:175], v[116:119]
	v_mfma_f32_16x16x32_bf16 v[108:111], v[212:215], v[172:175], v[108:111]
	v_mfma_f32_16x16x32_bf16 v[100:103], v[204:207], v[180:183], v[100:103]
	v_mfma_f32_16x16x32_bf16 v[92:95], v[212:215], v[180:183], v[92:95]
	v_mfma_f32_16x16x32_bf16 v[84:87], v[204:207], v[188:191], v[84:87]
	v_mfma_f32_16x16x32_bf16 v[76:79], v[212:215], v[188:191], v[76:79]
	v_mfma_f32_16x16x32_bf16 v[68:71], v[204:207], v[196:199], v[68:71]
	v_mfma_f32_16x16x32_bf16 v[64:67], v[212:215], v[196:199], v[64:67]
	s_mov_b32 m0, s28
	s_add_u32 s100, s54, s6
	s_addc_u32 s101, s55, s7
	s_barrier
	ds_read_b128 v[168:171], v146 offset:16384
	ds_read_b128 v[172:175], v146 offset:17408
	ds_read_b128 v[176:179], v146 offset:18432
	ds_read_b128 v[180:183], v146 offset:19456
	ds_read_b128 v[184:187], v146 offset:20480
	ds_read_b128 v[188:191], v146 offset:21504
	ds_read_b128 v[192:195], v146 offset:22528
	ds_read_b128 v[196:199], v146 offset:23552
	global_load_lds_dwordx4 v134, s[54:55]
	s_mov_b32 m0, s29
	s_nop 0
	global_load_lds_dwordx4 v130, s[54:55]
	s_barrier
	s_waitcnt lgkmcnt(0)
	v_mfma_f32_16x16x32_bf16 v[60:63], v[148:151], v[168:171], v[60:63]
	v_mfma_f32_16x16x32_bf16 v[56:59], v[160:163], v[168:171], v[56:59]
	v_mfma_f32_16x16x32_bf16 v[52:55], v[148:151], v[176:179], v[52:55]
	v_mfma_f32_16x16x32_bf16 v[44:47], v[160:163], v[176:179], v[44:47]
	v_mfma_f32_16x16x32_bf16 v[36:39], v[148:151], v[184:187], v[36:39]
	v_mfma_f32_16x16x32_bf16 v[28:31], v[160:163], v[184:187], v[28:31]
	v_mfma_f32_16x16x32_bf16 v[20:23], v[148:151], v[192:195], v[20:23]
	v_mfma_f32_16x16x32_bf16 v[12:15], v[160:163], v[192:195], v[12:15]
	v_mfma_f32_16x16x32_bf16 v[60:63], v[152:155], v[172:175], v[60:63]
	v_mfma_f32_16x16x32_bf16 v[56:59], v[164:167], v[172:175], v[56:59]
	v_mfma_f32_16x16x32_bf16 v[52:55], v[152:155], v[180:183], v[52:55]
	v_mfma_f32_16x16x32_bf16 v[44:47], v[164:167], v[180:183], v[44:47]
	v_mfma_f32_16x16x32_bf16 v[36:39], v[152:155], v[188:191], v[36:39]
	v_mfma_f32_16x16x32_bf16 v[28:31], v[164:167], v[188:191], v[28:31]
	v_mfma_f32_16x16x32_bf16 v[20:23], v[152:155], v[196:199], v[20:23]
	v_mfma_f32_16x16x32_bf16 v[12:15], v[164:167], v[196:199], v[12:15]
	s_barrier
	s_add_u32 s70, s52, 0x80000
	s_addc_u32 s71, s53, 0
	s_add_i32 s72, s59, s23
	s_mov_b32 m0, s72
	s_nop 0
	global_load_lds_dwordx4 v132, s[70:71]
	s_add_i32 m0, s72, 0x2000
	s_nop 0
	global_load_lds_dwordx4 v128, s[70:71]
	s_waitcnt vmcnt(6)
	s_barrier
; #define PG8_STAGE(bufoff, gbase, voff) do { _Pragma("unroll") for (int _i = 0; _i < 2; ++_i) \
;         __builtin_amdgcn_global_load_lds((const unsigned*)((const char*)(gbase) + (voff)[_i]), (LAS unsigned*)(lds + (bufoff) + ldsw + _i * 8192), 16, 0, 0); } while (0)
; #define PG8_LDA(dst, b, h) do { _Pragma("unroll") for (int m = 0; m < 4; ++m) _Pragma("unroll") for (int k = 0; k < 2; ++k) dst[m][k] = *(const LAS bf16x8*)(lds + PG8_SA(b, h) + aoff + m * 2048 + k * 1024); } while (0)
; #define PG8_LDB(dst, b, h) do { _Pragma("unroll") for (int n = 0; n < 2; ++n) _Pragma("unroll") for (int k = 0; k < 2; ++k) dst[n][k] = *(const LAS bf16x8*)(lds + PG8_SB(b, h) + boff + n * 2048 + k * 1024); } while (0)
; #define PG8_MMA(ai, bj, At, Bt) do { __builtin_amdgcn_s_setprio(1); _Pragma("unroll") for (int m = 0; m < 4; ++m) _Pragma("unroll") for (int n = 0; n < 2; ++n) _Pragma("unroll") for (int k = 0; k < 2; ++k) \
;         acc[ai][bj][m][n] = __builtin_amdgcn_mfma_f32_16x16x32_bf16(Bt[n][k], At[m][k], acc[ai][bj][m][n], 0, 0, 0); __builtin_amdgcn_s_setprio(0); } while (0)
; #define PG8_WAIT_V(n) asm volatile("s_waitcnt vmcnt(" #n ")" ::: "memory")
; #define PG8_WAIT_L(n) asm volatile("s_waitcnt lgkmcnt(" #n ")" ::: "memory")
; #define PG8_BAR __builtin_amdgcn_s_barrier()
; #define PG8_SCHED __builtin_amdgcn_sched_barrier(0)
; template <class Epi>
; __device__ __forceinline__ void gemm_phase(LAS unsigned char* lds, const Gemm g, const StaticOrder& S, const Epi& E) {
;     ...
;             PG8_WAIT_V(6); PG8_BAR; PG8_MMA(1, 1, At, B1); PG8_BAR;
;             PG8_LDB(B0, 1, 0); PG8_SCHED; PG8_LDA(At, 1, 0); PG8_STAGE(PG8_SA(0, 1), a2 + hstep, voffA);
;             PG8_WAIT_L(8); PG8_BAR; PG8_WAIT_L(0); PG8_MMA(0, 0, At, B0); PG8_BAR; PG8_SCHED;
;             PG8_LDB(B1, 1, 1); PG8_STAGE(PG8_SB(1, 0), b3, voffB);
;             PG8_BAR; PG8_WAIT_L(0); PG8_MMA(0, 1, At, B1); PG8_BAR;
;             PG8_LDA(At, 1, 1); PG8_STAGE(PG8_SA(1, 0), a3, voffA);
;             PG8_BAR; PG8_WAIT_L(0); PG8_MMA(1, 0, At, B0); PG8_BAR; PG8_SCHED;
;             PG8_STAGE(PG8_SB(1, 1), b3 + hstep, voffB);
;             PG8_WAIT_V(6); PG8_BAR; PG8_MMA(1, 1, At, B1); PG8_BAR;
	v_mfma_f32_16x16x32_bf16 v[48:51], v[200:203], v[168:171], v[48:51]
	v_mfma_f32_16x16x32_bf16 v[40:43], v[208:211], v[168:171], v[40:43]
	v_mfma_f32_16x16x32_bf16 v[32:35], v[200:203], v[176:179], v[32:35]
	v_mfma_f32_16x16x32_bf16 v[24:27], v[208:211], v[176:179], v[24:27]
	v_mfma_f32_16x16x32_bf16 v[16:19], v[200:203], v[184:187], v[16:19]
	v_mfma_f32_16x16x32_bf16 v[8:11], v[208:211], v[184:187], v[8:11]
	v_mfma_f32_16x16x32_bf16 v[4:7], v[200:203], v[192:195], v[4:7]
	v_mfma_f32_16x16x32_bf16 v[0:3], v[208:211], v[192:195], v[0:3]
	v_mfma_f32_16x16x32_bf16 v[48:51], v[204:207], v[172:175], v[48:51]
	v_mfma_f32_16x16x32_bf16 v[40:43], v[212:215], v[172:175], v[40:43]
	v_mfma_f32_16x16x32_bf16 v[32:35], v[204:207], v[180:183], v[32:35]
	v_mfma_f32_16x16x32_bf16 v[24:27], v[212:215], v[180:183], v[24:27]
	v_mfma_f32_16x16x32_bf16 v[16:19], v[204:207], v[188:191], v[16:19]
	v_mfma_f32_16x16x32_bf16 v[8:11], v[212:215], v[188:191], v[8:11]
	v_mfma_f32_16x16x32_bf16 v[4:7], v[204:207], v[196:199], v[4:7]
	v_mfma_f32_16x16x32_bf16 v[0:3], v[212:215], v[196:199], v[0:3]
	s_add_i32 s70, 0, 0x18000
	v_add_u32_e32 v164, s70, v143
	s_barrier
	ds_read_b128 v[148:151], v164
	ds_read_b128 v[152:155], v164 offset:1024
	ds_read_b128 v[160:163], v164 offset:2048
	ds_read_b128 v[164:167], v164 offset:3072
	s_add_u32 s54, s54, 0x80000
	s_addc_u32 s55, s55, 0
	s_mov_b32 m0, s33
	ds_read_b128 v[168:171], v146 offset:32768
	ds_read_b128 v[172:175], v146 offset:33792
	ds_read_b128 v[176:179], v146 offset:34816
	ds_read_b128 v[180:183], v146 offset:35840
	ds_read_b128 v[184:187], v146 offset:36864
	ds_read_b128 v[188:191], v146 offset:37888
	ds_read_b128 v[192:195], v146 offset:38912
	ds_read_b128 v[196:199], v146 offset:39936
	global_load_lds_dwordx4 v134, s[54:55]
	s_mov_b32 m0, s36
	s_nop 0
	global_load_lds_dwordx4 v130, s[54:55]
	s_waitcnt lgkmcnt(8)
	s_barrier
	s_waitcnt lgkmcnt(0)
	v_mfma_f32_16x16x32_bf16 v[124:127], v[148:151], v[168:171], v[124:127]
	v_mfma_f32_16x16x32_bf16 v[120:123], v[160:163], v[168:171], v[120:123]
	v_mfma_f32_16x16x32_bf16 v[112:115], v[148:151], v[176:179], v[112:115]
	v_mfma_f32_16x16x32_bf16 v[104:107], v[160:163], v[176:179], v[104:107]
	v_mfma_f32_16x16x32_bf16 v[96:99], v[148:151], v[184:187], v[96:99]
	v_mfma_f32_16x16x32_bf16 v[88:91], v[160:163], v[184:187], v[88:91]
	v_mfma_f32_16x16x32_bf16 v[80:83], v[148:151], v[192:195], v[80:83]
	v_mfma_f32_16x16x32_bf16 v[72:75], v[160:163], v[192:195], v[72:75]
	v_mfma_f32_16x16x32_bf16 v[124:127], v[152:155], v[172:175], v[124:127]
	v_mfma_f32_16x16x32_bf16 v[120:123], v[164:167], v[172:175], v[120:123]
	v_mfma_f32_16x16x32_bf16 v[112:115], v[152:155], v[180:183], v[112:115]
	v_mfma_f32_16x16x32_bf16 v[104:107], v[164:167], v[180:183], v[104:107]
	v_mfma_f32_16x16x32_bf16 v[96:99], v[152:155], v[188:191], v[96:99]
	v_mfma_f32_16x16x32_bf16 v[88:91], v[164:167], v[188:191], v[88:91]
	v_mfma_f32_16x16x32_bf16 v[80:83], v[152:155], v[196:199], v[80:83]
	v_mfma_f32_16x16x32_bf16 v[72:75], v[164:167], v[196:199], v[72:75]
	s_barrier
	s_add_i32 s54, 0, 0x1c000
	s_add_i32 s55, s70, s23
	v_add_u32_e32 v212, s54, v143
	s_mov_b32 m0, s55
	ds_read_b128 v[200:203], v212
	ds_read_b128 v[204:207], v212 offset:1024
	ds_read_b128 v[208:211], v212 offset:2048
	ds_read_b128 v[212:215], v212 offset:3072
	global_load_lds_dwordx4 v132, s[98:99]
	s_add_i32 m0, s55, 0x2000
	s_nop 0
	global_load_lds_dwordx4 v128, s[98:99]
	s_barrier
	s_waitcnt lgkmcnt(0)
	v_mfma_f32_16x16x32_bf16 v[116:119], v[200:203], v[168:171], v[116:119]
	v_mfma_f32_16x16x32_bf16 v[108:111], v[208:211], v[168:171], v[108:111]
	v_mfma_f32_16x16x32_bf16 v[100:103], v[200:203], v[176:179], v[100:103]
	v_mfma_f32_16x16x32_bf16 v[92:95], v[208:211], v[176:179], v[92:95]
	v_mfma_f32_16x16x32_bf16 v[84:87], v[200:203], v[184:187], v[84:87]
	v_mfma_f32_16x16x32_bf16 v[76:79], v[208:211], v[184:187], v[76:79]
	v_mfma_f32_16x16x32_bf16 v[68:71], v[200:203], v[192:195], v[68:71]
	v_mfma_f32_16x16x32_bf16 v[64:67], v[208:211], v[192:195], v[64:67]
	v_mfma_f32_16x16x32_bf16 v[116:119], v[204:207], v[172:175], v[116:119]
	v_mfma_f32_16x16x32_bf16 v[108:111], v[212:215], v[172:175], v[108:111]
	v_mfma_f32_16x16x32_bf16 v[100:103], v[204:207], v[180:183], v[100:103]
	v_mfma_f32_16x16x32_bf16 v[92:95], v[212:215], v[180:183], v[92:95]
	v_mfma_f32_16x16x32_bf16 v[84:87], v[204:207], v[188:191], v[84:87]
	v_mfma_f32_16x16x32_bf16 v[76:79], v[212:215], v[188:191], v[76:79]
	v_mfma_f32_16x16x32_bf16 v[68:71], v[204:207], v[196:199], v[68:71]
	v_mfma_f32_16x16x32_bf16 v[64:67], v[212:215], v[196:199], v[64:67]
	s_mov_b32 m0, s49
	s_barrier
	ds_read_b128 v[168:171], v146 offset:49152
	ds_read_b128 v[172:175], v146 offset:50176
	ds_read_b128 v[176:179], v146 offset:51200
	ds_read_b128 v[180:183], v146 offset:52224
	ds_read_b128 v[184:187], v146 offset:53248
	ds_read_b128 v[188:191], v146 offset:54272
	ds_read_b128 v[192:195], v146 offset:55296
	ds_read_b128 v[196:199], v146 offset:56320
	global_load_lds_dwordx4 v134, s[100:101]
	s_mov_b32 m0, s56
	s_nop 0
	global_load_lds_dwordx4 v130, s[100:101]
	s_barrier
; #define PG8_STAGE(bufoff, gbase, voff) do { _Pragma("unroll") for (int _i = 0; _i < 2; ++_i) \
;         __builtin_amdgcn_global_load_lds((const unsigned*)((const char*)(gbase) + (voff)[_i]), (LAS unsigned*)(lds + (bufoff) + ldsw + _i * 8192), 16, 0, 0); } while (0)
; #define PG8_MMA(ai, bj, At, Bt) do { __builtin_amdgcn_s_setprio(1); _Pragma("unroll") for (int m = 0; m < 4; ++m) _Pragma("unroll") for (int n = 0; n < 2; ++n) _Pragma("unroll") for (int k = 0; k < 2; ++k) \
;         acc[ai][bj][m][n] = __builtin_amdgcn_mfma_f32_16x16x32_bf16(Bt[n][k], At[m][k], acc[ai][bj][m][n], 0, 0, 0); __builtin_amdgcn_s_setprio(0); } while (0)
; #define PG8_WAIT_V(n) asm volatile("s_waitcnt vmcnt(" #n ")" ::: "memory")
; #define PG8_WAIT_L(n) asm volatile("s_waitcnt lgkmcnt(" #n ")" ::: "memory")
; #define PG8_BAR __builtin_amdgcn_s_barrier()
; #define PG8_SCHED __builtin_amdgcn_sched_barrier(0)
; template <class Epi>
; __device__ __forceinline__ void gemm_phase(LAS unsigned char* lds, const Gemm g, const StaticOrder& S, const Epi& E) {
;     ...
;             PG8_BAR; PG8_WAIT_L(0); PG8_MMA(1, 0, At, B0); PG8_BAR; PG8_SCHED;
;             PG8_STAGE(PG8_SB(1, 1), b3 + hstep, voffB);
;             PG8_WAIT_V(6); PG8_BAR; PG8_MMA(1, 1, At, B1); PG8_BAR;
;         }
;         E(acc, cur, wr, wc, fr, fq);
;         if (!has_next) break;
	s_waitcnt lgkmcnt(0)
	v_mfma_f32_16x16x32_bf16 v[60:63], v[148:151], v[168:171], v[60:63]
	v_mfma_f32_16x16x32_bf16 v[56:59], v[160:163], v[168:171], v[56:59]
	v_mfma_f32_16x16x32_bf16 v[52:55], v[148:151], v[176:179], v[52:55]
	v_mfma_f32_16x16x32_bf16 v[44:47], v[160:163], v[176:179], v[44:47]
	v_mfma_f32_16x16x32_bf16 v[36:39], v[148:151], v[184:187], v[36:39]
	v_mfma_f32_16x16x32_bf16 v[28:31], v[160:163], v[184:187], v[28:31]
	v_mfma_f32_16x16x32_bf16 v[20:23], v[148:151], v[192:195], v[20:23]
	v_mfma_f32_16x16x32_bf16 v[12:15], v[160:163], v[192:195], v[12:15]
	v_mfma_f32_16x16x32_bf16 v[60:63], v[152:155], v[172:175], v[60:63]
	v_mfma_f32_16x16x32_bf16 v[56:59], v[164:167], v[172:175], v[56:59]
	v_mfma_f32_16x16x32_bf16 v[52:55], v[152:155], v[180:183], v[52:55]
	v_mfma_f32_16x16x32_bf16 v[44:47], v[164:167], v[180:183], v[44:47]
	v_mfma_f32_16x16x32_bf16 v[36:39], v[152:155], v[188:191], v[36:39]
	v_mfma_f32_16x16x32_bf16 v[28:31], v[164:167], v[188:191], v[28:31]
	v_mfma_f32_16x16x32_bf16 v[20:23], v[152:155], v[196:199], v[20:23]
	v_mfma_f32_16x16x32_bf16 v[12:15], v[164:167], v[196:199], v[12:15]
	s_barrier
	s_add_u32 s52, s52, 0x80080
	s_addc_u32 s53, s53, 0
	s_add_i32 s54, s54, s23
	s_mov_b32 m0, s54
	s_nop 0
	global_load_lds_dwordx4 v132, s[52:53]
	s_add_i32 m0, s54, 0x2000
	s_nop 0
	global_load_lds_dwordx4 v128, s[52:53]
	s_add_i32 s69, s69, 2
	s_add_u32 s50, s50, 0x100
	s_addc_u32 s51, s51, 0
	s_add_u32 s67, s67, 0x100
	s_addc_u32 s68, s68, 0
	s_cmp_gt_u32 s69, 29
	s_waitcnt vmcnt(6)
	s_barrier
	v_mfma_f32_16x16x32_bf16 v[48:51], v[200:203], v[168:171], v[48:51]
	v_mfma_f32_16x16x32_bf16 v[40:43], v[208:211], v[168:171], v[40:43]
	v_mfma_f32_16x16x32_bf16 v[32:35], v[200:203], v[176:179], v[32:35]
	v_mfma_f32_16x16x32_bf16 v[24:27], v[208:211], v[176:179], v[24:27]
	v_mfma_f32_16x16x32_bf16 v[16:19], v[200:203], v[184:187], v[16:19]
	v_mfma_f32_16x16x32_bf16 v[8:11], v[208:211], v[184:187], v[8:11]
	v_mfma_f32_16x16x32_bf16 v[4:7], v[200:203], v[192:195], v[4:7]
	v_mfma_f32_16x16x32_bf16 v[0:3], v[208:211], v[192:195], v[0:3]
	v_mfma_f32_16x16x32_bf16 v[48:51], v[204:207], v[172:175], v[48:51]
	v_mfma_f32_16x16x32_bf16 v[40:43], v[212:215], v[172:175], v[40:43]
	v_mfma_f32_16x16x32_bf16 v[32:35], v[204:207], v[180:183], v[32:35]
	v_mfma_f32_16x16x32_bf16 v[24:27], v[212:215], v[180:183], v[24:27]
	v_mfma_f32_16x16x32_bf16 v[16:19], v[204:207], v[188:191], v[16:19]
	v_mfma_f32_16x16x32_bf16 v[8:11], v[212:215], v[188:191], v[8:11]
	v_mfma_f32_16x16x32_bf16 v[4:7], v[204:207], v[196:199], v[4:7]
	v_mfma_f32_16x16x32_bf16 v[0:3], v[212:215], v[196:199], v[0:3]
	s_barrier
	s_cbranch_scc0 .LBB0_673
; __device__ __forceinline__ u32x4 pack8(f32x4 v0, f32x4 v1) { u32x4 w; w.x = cvt_pk_bf16(v0[0], v0[1]); w.y = cvt_pk_bf16(v0[2], v0[3]); w.z = cvt_pk_bf16(v1[0], v1[1]); w.w = cvt_pk_bf16(v1[2], v1[3]); return w; }
;     __device__ __forceinline__ void operator()(const f32x4 (&acc)[2][2][4][2], const Unit& u, int wr, int wc, int fr, int fq) const {
;         const int row0 = u.pm * BM + wr * 64 + fr, col0 = u.pn * BM + wc * 32 + 8 * fq;
; #pragma unroll
;         for (int ai = 0; ai < 2; ++ai)
; #pragma unroll
;             for (int m = 0; m < 4; ++m) { bf16_t* rowp = O + (size_t)(row0 + ai * HALF + m * 16) * ldc + col0;
; #pragma unroll
;                 for (int bj = 0; bj < 2; ++bj) *(u32x4*)(rowp + bj * HALF) = pack8(acc[ai][bj][m][0], acc[ai][bj][m][1]); }
	v_lshl_add_u32 v148, s48, 8, v142
	v_lshl_or_b32 v140, s64, 8, v144
	v_ashrrev_i32_e32 v149, 31, v148
	v_ashrrev_i32_e32 v141, 31, v140
	v_lshlrev_b64 v[150:151], 12, v[148:149]
	v_lshl_add_u64 v[150:151], s[24:25], 0, v[150:151]
	v_lshlrev_b64 v[152:153], 1, v[140:141]
	v_lshl_add_u64 v[140:141], v[150:151], 0, v[152:153]
	v_cvt_pk_bf16_f32 v124, v124, v125
	v_cvt_pk_bf16_f32 v125, v126, v127
	v_cvt_pk_bf16_f32 v126, v120, v121
	v_cvt_pk_bf16_f32 v127, v122, v123
	global_store_dwordx4 v[140:141], v[124:127], off
	v_cvt_pk_bf16_f32 v116, v116, v117
	v_cvt_pk_bf16_f32 v117, v118, v119
	v_cvt_pk_bf16_f32 v118, v108, v109
	v_or_b32_e32 v108, 16, v148
	v_ashrrev_i32_e32 v109, 31, v108
	v_lshlrev_b64 v[108:109], 12, v[108:109]
	v_lshl_add_u64 v[108:109], s[24:25], 0, v[108:109]
	v_cvt_pk_bf16_f32 v119, v110, v111
	global_store_dwordx4 v[140:141], v[116:119], off offset:256
	s_mov_b32 s64, s40
	s_mov_b32 s48, s42
	v_lshl_add_u64 v[116:117], v[108:109], 0, v[152:153]
	v_cvt_pk_bf16_f32 v108, v112, v113
	v_cvt_pk_bf16_f32 v109, v114, v115
	v_cvt_pk_bf16_f32 v110, v104, v105
	v_cvt_pk_bf16_f32 v111, v106, v107
	global_store_dwordx4 v[116:117], v[108:111], off
	v_cvt_pk_bf16_f32 v100, v100, v101
	v_cvt_pk_bf16_f32 v101, v102, v103
	v_cvt_pk_bf16_f32 v102, v92, v93
	v_or_b32_e32 v92, 32, v148
	v_ashrrev_i32_e32 v93, 31, v92
	v_lshlrev_b64 v[92:93], 12, v[92:93]
	v_lshl_add_u64 v[92:93], s[24:25], 0, v[92:93]
	v_cvt_pk_bf16_f32 v103, v94, v95
	global_store_dwordx4 v[116:117], v[100:103], off offset:256
	s_mov_b64 s[52:53], s[46:47]
	s_mov_b64 s[50:51], s[44:45]
	v_lshl_add_u64 v[100:101], v[92:93], 0, v[152:153]
	v_cvt_pk_bf16_f32 v92, v96, v97
	v_cvt_pk_bf16_f32 v93, v98, v99
	v_cvt_pk_bf16_f32 v94, v88, v89
	v_cvt_pk_bf16_f32 v95, v90, v91
	global_store_dwordx4 v[100:101], v[92:95], off
	v_cvt_pk_bf16_f32 v84, v84, v85
	v_cvt_pk_bf16_f32 v85, v86, v87
	v_cvt_pk_bf16_f32 v86, v76, v77
	v_or_b32_e32 v76, 48, v148
	v_ashrrev_i32_e32 v77, 31, v76
	v_lshlrev_b64 v[76:77], 12, v[76:77]
	v_lshl_add_u64 v[76:77], s[24:25], 0, v[76:77]
	v_cvt_pk_bf16_f32 v87, v78, v79
	global_store_dwordx4 v[100:101], v[84:87], off offset:256
	s_nop 1
	v_lshl_add_u64 v[84:85], v[76:77], 0, v[152:153]
	v_cvt_pk_bf16_f32 v76, v80, v81
	v_cvt_pk_bf16_f32 v77, v82, v83
	v_cvt_pk_bf16_f32 v78, v72, v73
	v_cvt_pk_bf16_f32 v79, v74, v75
	global_store_dwordx4 v[84:85], v[76:79], off
	v_cvt_pk_bf16_f32 v68, v68, v69
	v_cvt_pk_bf16_f32 v69, v70, v71
	v_cvt_pk_bf16_f32 v70, v64, v65
	v_cvt_pk_bf16_f32 v71, v66, v67
	global_store_dwordx4 v[84:85], v[68:71], off offset:256
	v_cvt_pk_bf16_f32 v60, v60, v61
	v_cvt_pk_bf16_f32 v61, v62, v63
	v_cvt_pk_bf16_f32 v62, v56, v57
	v_add_co_u32_e32 v56, vcc, s60, v140
	v_lshl_add_u64 v[64:65], v[140:141], 0, s[2:3]
	s_nop 0
	v_addc_co_u32_e32 v57, vcc, 0, v141, vcc
	v_cvt_pk_bf16_f32 v63, v58, v59
	global_store_dwordx4 v[56:57], v[60:63], off
	v_cvt_pk_bf16_f32 v48, v48, v49
	v_cvt_pk_bf16_f32 v49, v50, v51
	v_cvt_pk_bf16_f32 v50, v40, v41
	v_cvt_pk_bf16_f32 v51, v42, v43
	global_store_dwordx4 v[64:65], v[48:51], off offset:256
	v_cvt_pk_bf16_f32 v40, v52, v53
	v_cvt_pk_bf16_f32 v41, v54, v55
	v_cvt_pk_bf16_f32 v42, v44, v45
	v_add_co_u32_e32 v44, vcc, s61, v140
	s_nop 0
	v_lshl_add_u64 v[48:49], v[140:141], 0, s[8:9]
	v_addc_co_u32_e32 v45, vcc, 0, v141, vcc
	v_cvt_pk_bf16_f32 v43, v46, v47
	global_store_dwordx4 v[44:45], v[40:43], off
	v_cvt_pk_bf16_f32 v32, v32, v33
	v_cvt_pk_bf16_f32 v33, v34, v35
	v_cvt_pk_bf16_f32 v34, v24, v25
	v_cvt_pk_bf16_f32 v35, v26, v27
	global_store_dwordx4 v[48:49], v[32:35], off offset:256
	v_cvt_pk_bf16_f32 v24, v36, v37
	v_cvt_pk_bf16_f32 v25, v38, v39
	v_cvt_pk_bf16_f32 v26, v28, v29
	v_add_co_u32_e32 v28, vcc, s62, v140
	s_nop 0
	v_lshl_add_u64 v[32:33], v[140:141], 0, s[30:31]
	v_addc_co_u32_e32 v29, vcc, 0, v141, vcc
	v_cvt_pk_bf16_f32 v27, v30, v31
	global_store_dwordx4 v[28:29], v[24:27], off
	v_cvt_pk_bf16_f32 v16, v16, v17
	v_cvt_pk_bf16_f32 v17, v18, v19
	v_cvt_pk_bf16_f32 v18, v8, v9
	v_cvt_pk_bf16_f32 v19, v10, v11
	global_store_dwordx4 v[32:33], v[16:19], off offset:256
	v_cvt_pk_bf16_f32 v8, v20, v21
	v_cvt_pk_bf16_f32 v9, v22, v23
	v_cvt_pk_bf16_f32 v10, v12, v13
	v_add_co_u32_e32 v12, vcc, s63, v140
	s_nop 0
	v_lshl_add_u64 v[16:17], v[140:141], 0, s[34:35]
	v_addc_co_u32_e32 v13, vcc, 0, v141, vcc
	s_and_b64 vcc, exec, s[38:39]
	v_cvt_pk_bf16_f32 v11, v14, v15
	global_store_dwordx4 v[12:13], v[8:11], off
	v_cvt_pk_bf16_f32 v4, v4, v5
	v_cvt_pk_bf16_f32 v5, v6, v7
	v_cvt_pk_bf16_f32 v6, v0, v1
	v_cvt_pk_bf16_f32 v7, v2, v3
	global_store_dwordx4 v[16:17], v[4:7], off offset:256
	s_cbranch_vccz .LBB0_670
	s_waitcnt vmcnt(0)
	s_cmpk_gt_u32 s10, 0xff
	v_readlane_b32 s62, v232, 20
	v_readlane_b32 s61, v232, 21
	s_cbranch_scc1 .LBB0_677
	s_barrier

; #define PG8_STAGE(bufoff, gbase, voff) do { _Pragma("unroll") for (int _i = 0; _i < 2; ++_i) \
;         __builtin_amdgcn_global_load_lds((const unsigned*)((const char*)(gbase) + (voff)[_i]), (LAS unsigned*)(lds + (bufoff) + ldsw + _i * 8192), 16, 0, 0); } while (0)
; #define PG8_LDA(dst, b, h) do { _Pragma("unroll") for (int m = 0; m < 4; ++m) _Pragma("unroll") for (int k = 0; k < 2; ++k) dst[m][k] = *(const LAS bf16x8*)(lds + PG8_SA(b, h) + aoff + m * 2048 + k * 1024); } while (0)
; #define PG8_WAIT_V(n) asm volatile("s_waitcnt vmcnt(" #n ")" ::: "memory")
; #define PG8_WAIT_L(n) asm volatile("s_waitcnt lgkmcnt(" #n ")" ::: "memory")
; template <class Epi>
; __device__ __forceinline__ void gemm_phase(LAS unsigned char* lds, const Gemm g, const StaticOrder& S, const Epi& E) {
;     ...
;         for (int t = 0; t < nt; t += 2) {
;             const bool last = (t == nt - 2);
;             const char* a1 = cA + (size_t)(t + 1) * kstep;
;             const char* a2 = last ? nA : cA + (size_t)(t + 2) * kstep; const char* b2 = last ? nB : cB + (size_t)(t + 2) * kstep;
;             const char* a3 = a2 + kstep; const char* b3 = b2 + kstep;
;             PG8_LDB(B0, 0, 0); PG8_SCHED; PG8_LDA(At, 0, 0); PG8_STAGE(PG8_SA(1, 1), a1 + hstep, voffA);
;             PG8_WAIT_L(8); PG8_BAR; PG8_WAIT_L(0); PG8_MMA(0, 0, At, B0); PG8_BAR; PG8_SCHED;
;             PG8_LDB(B1, 0, 1); PG8_STAGE(PG8_SB(0, 0), b2, voffB);
;             PG8_BAR; PG8_WAIT_L(0); PG8_MMA(0, 1, At, B1); PG8_BAR;
;             PG8_LDA(At, 0, 1); PG8_STAGE(PG8_SA(0, 0), a2, voffA);
;             PG8_BAR; PG8_WAIT_L(0); PG8_MMA(1, 0, At, B0); PG8_BAR; PG8_SCHED;
;             PG8_STAGE(PG8_SB(0, 1), b2 + hstep, voffB);
;             PG8_WAIT_V(6); PG8_BAR; PG8_MMA(1, 1, At, B1); PG8_BAR;
;             PG8_LDB(B0, 1, 0); PG8_SCHED; PG8_LDA(At, 1, 0); PG8_STAGE(PG8_SA(0, 1), a2 + hstep, voffA);
;             PG8_WAIT_L(8); PG8_BAR; PG8_WAIT_L(0); PG8_MMA(0, 0, At, B0); PG8_BAR; PG8_SCHED;
;             PG8_LDB(B1, 1, 1); PG8_STAGE(PG8_SB(1, 0), b3, voffB);
;             PG8_BAR; PG8_WAIT_L(0); PG8_MMA(0, 1, At, B1); PG8_BAR;
;             PG8_LDA(At, 1, 1); PG8_STAGE(PG8_SA(1, 0), a3, voffA);
;             PG8_BAR; PG8_WAIT_L(0); PG8_MMA(1, 0, At, B0); PG8_BAR; PG8_SCHED;
;             PG8_STAGE(PG8_SB(1, 1), b3 + hstep, voffB);
;             PG8_WAIT_V(6); PG8_BAR; PG8_MMA(1, 1, At, B1); PG8_BAR;
.LBB0_796:
	ds_read_b128 v[144:147], v155
	ds_read_b128 v[148:151], v155 offset:1024
	ds_read_b128 v[160:163], v155 offset:2048
	ds_read_b128 v[164:167], v155 offset:3072
	s_add_u32 s42, s40, 0xfff80080
	s_addc_u32 s43, s41, -1
	s_cmp_eq_u32 s58, 28
	s_cselect_b32 s45, s31, s43
	s_cselect_b32 s44, s54, s42
	s_cselect_b32 s43, s9, s57
	s_cselect_b32 s42, s55, s56
	s_add_i32 m0, s27, 0xc000
	ds_read_b128 v[168:171], v156
	ds_read_b128 v[172:175], v156 offset:1024
	ds_read_b128 v[176:179], v156 offset:2048
	ds_read_b128 v[180:183], v156 offset:3072
	ds_read_b128 v[184:187], v156 offset:4096
	ds_read_b128 v[188:191], v156 offset:5120
	ds_read_b128 v[192:195], v156 offset:6144
	ds_read_b128 v[196:199], v156 offset:7168
	global_load_lds_dwordx4 v136, s[40:41]
	s_add_i32 m0, s27, 0xe000
	s_nop 0
	global_load_lds_dwordx4 v138, s[40:41]
	s_waitcnt lgkmcnt(8)
	s_barrier
	s_waitcnt lgkmcnt(0)
	v_mfma_f32_16x16x32_bf16 v[124:127], v[144:147], v[168:171], v[124:127]
	v_mfma_f32_16x16x32_bf16 v[120:123], v[160:163], v[168:171], v[120:123]
	v_mfma_f32_16x16x32_bf16 v[108:111], v[144:147], v[176:179], v[108:111]
	v_mfma_f32_16x16x32_bf16 v[104:107], v[160:163], v[176:179], v[104:107]
	v_mfma_f32_16x16x32_bf16 v[92:95], v[144:147], v[184:187], v[92:95]
	v_mfma_f32_16x16x32_bf16 v[88:91], v[160:163], v[184:187], v[88:91]
	v_mfma_f32_16x16x32_bf16 v[76:79], v[144:147], v[192:195], v[76:79]
	v_mfma_f32_16x16x32_bf16 v[72:75], v[160:163], v[192:195], v[72:75]
	v_mfma_f32_16x16x32_bf16 v[124:127], v[148:151], v[172:175], v[124:127]
	v_mfma_f32_16x16x32_bf16 v[120:123], v[164:167], v[172:175], v[120:123]
	v_mfma_f32_16x16x32_bf16 v[108:111], v[148:151], v[180:183], v[108:111]
	v_mfma_f32_16x16x32_bf16 v[104:107], v[164:167], v[180:183], v[104:107]
	v_mfma_f32_16x16x32_bf16 v[92:95], v[148:151], v[188:191], v[92:95]
	v_mfma_f32_16x16x32_bf16 v[88:91], v[164:167], v[188:191], v[88:91]
	v_mfma_f32_16x16x32_bf16 v[76:79], v[148:151], v[196:199], v[76:79]
	v_mfma_f32_16x16x32_bf16 v[72:75], v[164:167], v[196:199], v[72:75]
	s_barrier
	s_add_i32 s59, s50, s23
	s_add_u32 s98, s42, s2
	s_addc_u32 s99, s43, s3
	s_mov_b32 m0, s59
	ds_read_b128 v[200:203], v157
	ds_read_b128 v[204:207], v157 offset:1024
	ds_read_b128 v[208:211], v157 offset:2048
	ds_read_b128 v[212:215], v157 offset:3072
	global_load_lds_dwordx4 v132, s[42:43]
	s_add_i32 m0, s59, 0x2000
	s_nop 0
	global_load_lds_dwordx4 v128, s[42:43]
	s_barrier
	s_waitcnt lgkmcnt(0)
	v_mfma_f32_16x16x32_bf16 v[116:119], v[200:203], v[168:171], v[116:119]
	v_mfma_f32_16x16x32_bf16 v[112:115], v[208:211], v[168:171], v[112:115]
	v_mfma_f32_16x16x32_bf16 v[100:103], v[200:203], v[176:179], v[100:103]
	v_mfma_f32_16x16x32_bf16 v[96:99], v[208:211], v[176:179], v[96:99]
	v_mfma_f32_16x16x32_bf16 v[84:87], v[200:203], v[184:187], v[84:87]
	v_mfma_f32_16x16x32_bf16 v[80:83], v[208:211], v[184:187], v[80:83]
	v_mfma_f32_16x16x32_bf16 v[68:71], v[200:203], v[192:195], v[68:71]
	v_mfma_f32_16x16x32_bf16 v[64:67], v[208:211], v[192:195], v[64:67]
	v_mfma_f32_16x16x32_bf16 v[116:119], v[204:207], v[172:175], v[116:119]
	v_mfma_f32_16x16x32_bf16 v[112:115], v[212:215], v[172:175], v[112:115]
	v_mfma_f32_16x16x32_bf16 v[100:103], v[204:207], v[180:183], v[100:103]
	v_mfma_f32_16x16x32_bf16 v[96:99], v[212:215], v[180:183], v[96:99]
	v_mfma_f32_16x16x32_bf16 v[84:87], v[204:207], v[188:191], v[84:87]
	v_mfma_f32_16x16x32_bf16 v[80:83], v[212:215], v[188:191], v[80:83]
	v_mfma_f32_16x16x32_bf16 v[68:71], v[204:207], v[196:199], v[68:71]
	v_mfma_f32_16x16x32_bf16 v[64:67], v[212:215], v[196:199], v[64:67]
	s_mov_b32 m0, s27
	s_add_u32 s100, s44, s2
	s_addc_u32 s101, s45, s3
	s_barrier
	ds_read_b128 v[168:171], v156 offset:16384
	ds_read_b128 v[172:175], v156 offset:17408
	ds_read_b128 v[176:179], v156 offset:18432
	ds_read_b128 v[180:183], v156 offset:19456
	ds_read_b128 v[184:187], v156 offset:20480
	ds_read_b128 v[188:191], v156 offset:21504
	ds_read_b128 v[192:195], v156 offset:22528
	ds_read_b128 v[196:199], v156 offset:23552
	global_load_lds_dwordx4 v134, s[44:45]
	s_mov_b32 m0, s28
	s_nop 0
	global_load_lds_dwordx4 v130, s[44:45]
	s_barrier
	s_waitcnt lgkmcnt(0)
	v_mfma_f32_16x16x32_bf16 v[60:63], v[144:147], v[168:171], v[60:63]
	v_mfma_f32_16x16x32_bf16 v[56:59], v[160:163], v[168:171], v[56:59]
	v_mfma_f32_16x16x32_bf16 v[44:47], v[144:147], v[176:179], v[44:47]
	v_mfma_f32_16x16x32_bf16 v[40:43], v[160:163], v[176:179], v[40:43]
	v_mfma_f32_16x16x32_bf16 v[28:31], v[144:147], v[184:187], v[28:31]
	v_mfma_f32_16x16x32_bf16 v[24:27], v[160:163], v[184:187], v[24:27]
	v_mfma_f32_16x16x32_bf16 v[12:15], v[144:147], v[192:195], v[12:15]
	v_mfma_f32_16x16x32_bf16 v[8:11], v[160:163], v[192:195], v[8:11]
	v_mfma_f32_16x16x32_bf16 v[60:63], v[148:151], v[172:175], v[60:63]
	v_mfma_f32_16x16x32_bf16 v[56:59], v[164:167], v[172:175], v[56:59]
	v_mfma_f32_16x16x32_bf16 v[44:47], v[148:151], v[180:183], v[44:47]
	v_mfma_f32_16x16x32_bf16 v[40:43], v[164:167], v[180:183], v[40:43]
	v_mfma_f32_16x16x32_bf16 v[28:31], v[148:151], v[188:191], v[28:31]
	v_mfma_f32_16x16x32_bf16 v[24:27], v[164:167], v[188:191], v[24:27]
	v_mfma_f32_16x16x32_bf16 v[12:15], v[148:151], v[196:199], v[12:15]
	v_mfma_f32_16x16x32_bf16 v[8:11], v[164:167], v[196:199], v[8:11]
	s_barrier
	s_add_u32 s60, s42, 0x80000
	s_addc_u32 s61, s43, 0
	s_add_i32 s59, s51, s23
	s_mov_b32 m0, s59
	s_nop 0
	global_load_lds_dwordx4 v132, s[60:61]
	s_add_i32 m0, s59, 0x2000
	s_nop 0
	global_load_lds_dwordx4 v128, s[60:61]
	s_waitcnt vmcnt(6)
	s_barrier
; #define PG8_STAGE(bufoff, gbase, voff) do { _Pragma("unroll") for (int _i = 0; _i < 2; ++_i) \
;         __builtin_amdgcn_global_load_lds((const unsigned*)((const char*)(gbase) + (voff)[_i]), (LAS unsigned*)(lds + (bufoff) + ldsw + _i * 8192), 16, 0, 0); } while (0)
; #define PG8_LDA(dst, b, h) do { _Pragma("unroll") for (int m = 0; m < 4; ++m) _Pragma("unroll") for (int k = 0; k < 2; ++k) dst[m][k] = *(const LAS bf16x8*)(lds + PG8_SA(b, h) + aoff + m * 2048 + k * 1024); } while (0)
; #define PG8_LDB(dst, b, h) do { _Pragma("unroll") for (int n = 0; n < 2; ++n) _Pragma("unroll") for (int k = 0; k < 2; ++k) dst[n][k] = *(const LAS bf16x8*)(lds + PG8_SB(b, h) + boff + n * 2048 + k * 1024); } while (0)
; #define PG8_MMA(ai, bj, At, Bt) do { __builtin_amdgcn_s_setprio(1); _Pragma("unroll") for (int m = 0; m < 4; ++m) _Pragma("unroll") for (int n = 0; n < 2; ++n) _Pragma("unroll") for (int k = 0; k < 2; ++k) \
;         acc[ai][bj][m][n] = __builtin_amdgcn_mfma_f32_16x16x32_bf16(Bt[n][k], At[m][k], acc[ai][bj][m][n], 0, 0, 0); __builtin_amdgcn_s_setprio(0); } while (0)
; #define PG8_WAIT_V(n) asm volatile("s_waitcnt vmcnt(" #n ")" ::: "memory")
; #define PG8_WAIT_L(n) asm volatile("s_waitcnt lgkmcnt(" #n ")" ::: "memory")
; #define PG8_BAR __builtin_amdgcn_s_barrier()
; #define PG8_SCHED __builtin_amdgcn_sched_barrier(0)
; template <class Epi>
; __device__ __forceinline__ void gemm_phase(LAS unsigned char* lds, const Gemm g, const StaticOrder& S, const Epi& E) {
;     ...
;             PG8_WAIT_V(6); PG8_BAR; PG8_MMA(1, 1, At, B1); PG8_BAR;
;             PG8_LDB(B0, 1, 0); PG8_SCHED; PG8_LDA(At, 1, 0); PG8_STAGE(PG8_SA(0, 1), a2 + hstep, voffA);
;             PG8_WAIT_L(8); PG8_BAR; PG8_WAIT_L(0); PG8_MMA(0, 0, At, B0); PG8_BAR; PG8_SCHED;
;             PG8_LDB(B1, 1, 1); PG8_STAGE(PG8_SB(1, 0), b3, voffB);
;             PG8_BAR; PG8_WAIT_L(0); PG8_MMA(0, 1, At, B1); PG8_BAR;
;             PG8_LDA(At, 1, 1); PG8_STAGE(PG8_SA(1, 0), a3, voffA);
;             PG8_BAR; PG8_WAIT_L(0); PG8_MMA(1, 0, At, B0); PG8_BAR; PG8_SCHED;
;             PG8_STAGE(PG8_SB(1, 1), b3 + hstep, voffB);
;             PG8_WAIT_V(6); PG8_BAR; PG8_MMA(1, 1, At, B1); PG8_BAR;
	v_mfma_f32_16x16x32_bf16 v[52:55], v[200:203], v[168:171], v[52:55]
	v_mfma_f32_16x16x32_bf16 v[48:51], v[208:211], v[168:171], v[48:51]
	v_mfma_f32_16x16x32_bf16 v[36:39], v[200:203], v[176:179], v[36:39]
	v_mfma_f32_16x16x32_bf16 v[32:35], v[208:211], v[176:179], v[32:35]
	v_mfma_f32_16x16x32_bf16 v[20:23], v[200:203], v[184:187], v[20:23]
	v_mfma_f32_16x16x32_bf16 v[16:19], v[208:211], v[184:187], v[16:19]
	v_mfma_f32_16x16x32_bf16 v[4:7], v[200:203], v[192:195], v[4:7]
	v_mfma_f32_16x16x32_bf16 v[0:3], v[208:211], v[192:195], v[0:3]
	v_mfma_f32_16x16x32_bf16 v[52:55], v[204:207], v[172:175], v[52:55]
	v_mfma_f32_16x16x32_bf16 v[48:51], v[212:215], v[172:175], v[48:51]
	v_mfma_f32_16x16x32_bf16 v[36:39], v[204:207], v[180:183], v[36:39]
	v_mfma_f32_16x16x32_bf16 v[32:35], v[212:215], v[180:183], v[32:35]
	v_mfma_f32_16x16x32_bf16 v[20:23], v[204:207], v[188:191], v[20:23]
	v_mfma_f32_16x16x32_bf16 v[16:19], v[212:215], v[188:191], v[16:19]
	v_mfma_f32_16x16x32_bf16 v[4:7], v[204:207], v[196:199], v[4:7]
	v_mfma_f32_16x16x32_bf16 v[0:3], v[212:215], v[196:199], v[0:3]
	s_add_i32 s59, 0, 0x18000
	v_add_u32_e32 v164, s59, v153
	s_barrier
	ds_read_b128 v[144:147], v164
	ds_read_b128 v[148:151], v164 offset:1024
	ds_read_b128 v[160:163], v164 offset:2048
	ds_read_b128 v[164:167], v164 offset:3072
	s_add_u32 s44, s44, 0x80000
	s_addc_u32 s45, s45, 0
	s_mov_b32 m0, s29
	ds_read_b128 v[168:171], v156 offset:32768
	ds_read_b128 v[172:175], v156 offset:33792
	ds_read_b128 v[176:179], v156 offset:34816
	ds_read_b128 v[180:183], v156 offset:35840
	ds_read_b128 v[184:187], v156 offset:36864
	ds_read_b128 v[188:191], v156 offset:37888
	ds_read_b128 v[192:195], v156 offset:38912
	ds_read_b128 v[196:199], v156 offset:39936
	global_load_lds_dwordx4 v134, s[44:45]
	s_mov_b32 m0, s33
	s_nop 0
	global_load_lds_dwordx4 v130, s[44:45]
	s_waitcnt lgkmcnt(8)
	s_barrier
	s_waitcnt lgkmcnt(0)
	v_mfma_f32_16x16x32_bf16 v[124:127], v[144:147], v[168:171], v[124:127]
	v_mfma_f32_16x16x32_bf16 v[120:123], v[160:163], v[168:171], v[120:123]
	v_mfma_f32_16x16x32_bf16 v[108:111], v[144:147], v[176:179], v[108:111]
	v_mfma_f32_16x16x32_bf16 v[104:107], v[160:163], v[176:179], v[104:107]
	v_mfma_f32_16x16x32_bf16 v[92:95], v[144:147], v[184:187], v[92:95]
	v_mfma_f32_16x16x32_bf16 v[88:91], v[160:163], v[184:187], v[88:91]
	v_mfma_f32_16x16x32_bf16 v[76:79], v[144:147], v[192:195], v[76:79]
	v_mfma_f32_16x16x32_bf16 v[72:75], v[160:163], v[192:195], v[72:75]
	v_mfma_f32_16x16x32_bf16 v[124:127], v[148:151], v[172:175], v[124:127]
	v_mfma_f32_16x16x32_bf16 v[120:123], v[164:167], v[172:175], v[120:123]
	v_mfma_f32_16x16x32_bf16 v[108:111], v[148:151], v[180:183], v[108:111]
	v_mfma_f32_16x16x32_bf16 v[104:107], v[164:167], v[180:183], v[104:107]
	v_mfma_f32_16x16x32_bf16 v[92:95], v[148:151], v[188:191], v[92:95]
	v_mfma_f32_16x16x32_bf16 v[88:91], v[164:167], v[188:191], v[88:91]
	v_mfma_f32_16x16x32_bf16 v[76:79], v[148:151], v[196:199], v[76:79]
	v_mfma_f32_16x16x32_bf16 v[72:75], v[164:167], v[196:199], v[72:75]
	s_barrier
	s_add_i32 s44, 0, 0x1c000
	s_add_i32 s45, s59, s23
	v_add_u32_e32 v212, s44, v153
	s_mov_b32 m0, s45
	ds_read_b128 v[200:203], v212
	ds_read_b128 v[204:207], v212 offset:1024
	ds_read_b128 v[208:211], v212 offset:2048
	ds_read_b128 v[212:215], v212 offset:3072
	global_load_lds_dwordx4 v132, s[98:99]
	s_add_i32 m0, s45, 0x2000
	s_nop 0
	global_load_lds_dwordx4 v128, s[98:99]
	s_barrier
	s_waitcnt lgkmcnt(0)
	v_mfma_f32_16x16x32_bf16 v[116:119], v[200:203], v[168:171], v[116:119]
	v_mfma_f32_16x16x32_bf16 v[112:115], v[208:211], v[168:171], v[112:115]
	v_mfma_f32_16x16x32_bf16 v[100:103], v[200:203], v[176:179], v[100:103]
	v_mfma_f32_16x16x32_bf16 v[96:99], v[208:211], v[176:179], v[96:99]
	v_mfma_f32_16x16x32_bf16 v[84:87], v[200:203], v[184:187], v[84:87]
	v_mfma_f32_16x16x32_bf16 v[80:83], v[208:211], v[184:187], v[80:83]
	v_mfma_f32_16x16x32_bf16 v[68:71], v[200:203], v[192:195], v[68:71]
	v_mfma_f32_16x16x32_bf16 v[64:67], v[208:211], v[192:195], v[64:67]
	v_mfma_f32_16x16x32_bf16 v[116:119], v[204:207], v[172:175], v[116:119]
	v_mfma_f32_16x16x32_bf16 v[112:115], v[212:215], v[172:175], v[112:115]
	v_mfma_f32_16x16x32_bf16 v[100:103], v[204:207], v[180:183], v[100:103]
	v_mfma_f32_16x16x32_bf16 v[96:99], v[212:215], v[180:183], v[96:99]
	v_mfma_f32_16x16x32_bf16 v[84:87], v[204:207], v[188:191], v[84:87]
	v_mfma_f32_16x16x32_bf16 v[80:83], v[212:215], v[188:191], v[80:83]
	v_mfma_f32_16x16x32_bf16 v[68:71], v[204:207], v[196:199], v[68:71]
	v_mfma_f32_16x16x32_bf16 v[64:67], v[212:215], v[196:199], v[64:67]
	s_mov_b32 m0, s46
	s_barrier
	ds_read_b128 v[168:171], v156 offset:49152
	ds_read_b128 v[172:175], v156 offset:50176
	ds_read_b128 v[176:179], v156 offset:51200
	ds_read_b128 v[180:183], v156 offset:52224
	ds_read_b128 v[184:187], v156 offset:53248
	ds_read_b128 v[188:191], v156 offset:54272
	ds_read_b128 v[192:195], v156 offset:55296
	ds_read_b128 v[196:199], v156 offset:56320
	global_load_lds_dwordx4 v134, s[100:101]
	s_mov_b32 m0, s47
	s_nop 0
	global_load_lds_dwordx4 v130, s[100:101]
	s_barrier
; __device__ __forceinline__ float fast_rcp(float x) { return __builtin_amdgcn_rcpf(x); }
; __device__ __forceinline__ float fast_exp2(float x) { return __builtin_amdgcn_exp2f(x); }
; #define PG8_STAGE(bufoff, gbase, voff) do { _Pragma("unroll") for (int _i = 0; _i < 2; ++_i) \
;         __builtin_amdgcn_global_load_lds((const unsigned*)((const char*)(gbase) + (voff)[_i]), (LAS unsigned*)(lds + (bufoff) + ldsw + _i * 8192), 16, 0, 0); } while (0)
; #define PG8_MMA(ai, bj, At, Bt) do { __builtin_amdgcn_s_setprio(1); _Pragma("unroll") for (int m = 0; m < 4; ++m) _Pragma("unroll") for (int n = 0; n < 2; ++n) _Pragma("unroll") for (int k = 0; k < 2; ++k) \
;         acc[ai][bj][m][n] = __builtin_amdgcn_mfma_f32_16x16x32_bf16(Bt[n][k], At[m][k], acc[ai][bj][m][n], 0, 0, 0); __builtin_amdgcn_s_setprio(0); } while (0)
; #define PG8_WAIT_V(n) asm volatile("s_waitcnt vmcnt(" #n ")" ::: "memory")
; #define PG8_BAR __builtin_amdgcn_s_barrier()
; template <class Epi>
; __device__ __forceinline__ void gemm_phase(LAS unsigned char* lds, const Gemm g, const StaticOrder& S, const Epi& E) {
;     ...
;             PG8_STAGE(PG8_SB(1, 1), b3 + hstep, voffB);
;             PG8_WAIT_V(6); PG8_BAR; PG8_MMA(1, 1, At, B1); PG8_BAR;
;         }
;         E(acc, cur, wr, wc, fr, fq);
;         if (!has_next) break;
;     __device__ __forceinline__ void operator()(const f32x4 (&acc)[2][2][4][2], const Unit& u, int wr, int wc, int fr, int fq) const {
;         const int row0 = u.pm * BM + wr * 64 + fr, col0 = u.pn * HALF + wc * 32 + 8 * fq;
; #pragma unroll
;         for (int ai = 0; ai < 2; ++ai)
; #pragma unroll
;             for (int m = 0; m < 4; ++m) { bf16_t* rowp = O + (size_t)(row0 + ai * HALF + m * 16) * DFF + col0;
;                 const float r = rs[row0 + ai * HALF + m * 16], r2 = r * r;
;                 f32x4 h0, h1;
; #pragma unroll
;                 for (int j = 0; j < 4; ++j) {
;                     const float g0 = acc[ai][0][m][0][j], g1 = acc[ai][0][m][1][j];
;                     h0[j] = g0 * r2 * fast_rcp(1.0f + fast_exp2(g0 * (-LOG2E * r))) * acc[ai][1][m][0][j];
;                     h1[j] = g1 * r2 * fast_rcp(1.0f + fast_exp2(g1 * (-LOG2E * r))) * acc[ai][1][m][1][j]; }
;                 *(u32x4*)rowp = pack8(h0, h1); }
	s_waitcnt lgkmcnt(0)
	v_mfma_f32_16x16x32_bf16 v[60:63], v[144:147], v[168:171], v[60:63]
	v_mfma_f32_16x16x32_bf16 v[56:59], v[160:163], v[168:171], v[56:59]
	v_mfma_f32_16x16x32_bf16 v[44:47], v[144:147], v[176:179], v[44:47]
	v_mfma_f32_16x16x32_bf16 v[40:43], v[160:163], v[176:179], v[40:43]
	v_mfma_f32_16x16x32_bf16 v[28:31], v[144:147], v[184:187], v[28:31]
	v_mfma_f32_16x16x32_bf16 v[24:27], v[160:163], v[184:187], v[24:27]
	v_mfma_f32_16x16x32_bf16 v[12:15], v[144:147], v[192:195], v[12:15]
	v_mfma_f32_16x16x32_bf16 v[8:11], v[160:163], v[192:195], v[8:11]
	v_mfma_f32_16x16x32_bf16 v[60:63], v[148:151], v[172:175], v[60:63]
	v_mfma_f32_16x16x32_bf16 v[56:59], v[164:167], v[172:175], v[56:59]
	v_mfma_f32_16x16x32_bf16 v[44:47], v[148:151], v[180:183], v[44:47]
	v_mfma_f32_16x16x32_bf16 v[40:43], v[164:167], v[180:183], v[40:43]
	v_mfma_f32_16x16x32_bf16 v[28:31], v[148:151], v[188:191], v[28:31]
	v_mfma_f32_16x16x32_bf16 v[24:27], v[164:167], v[188:191], v[24:27]
	v_mfma_f32_16x16x32_bf16 v[12:15], v[148:151], v[196:199], v[12:15]
	v_mfma_f32_16x16x32_bf16 v[8:11], v[164:167], v[196:199], v[8:11]
	s_barrier
	s_add_u32 s42, s42, 0x80080
	s_addc_u32 s43, s43, 0
	s_add_i32 s44, s44, s23
	s_mov_b32 m0, s44
	s_nop 0
	global_load_lds_dwordx4 v132, s[42:43]
	s_add_i32 m0, s44, 0x2000
	s_nop 0
	global_load_lds_dwordx4 v128, s[42:43]
	s_add_i32 s58, s58, 2
	s_add_u32 s40, s40, 0x100
	s_addc_u32 s41, s41, 0
	s_add_u32 s56, s56, 0x100
	s_addc_u32 s57, s57, 0
	s_cmp_gt_u32 s58, 29
	s_waitcnt vmcnt(6)
	s_barrier
	v_mfma_f32_16x16x32_bf16 v[52:55], v[200:203], v[168:171], v[52:55]
	v_mfma_f32_16x16x32_bf16 v[48:51], v[208:211], v[168:171], v[48:51]
	v_mfma_f32_16x16x32_bf16 v[36:39], v[200:203], v[176:179], v[36:39]
	v_mfma_f32_16x16x32_bf16 v[32:35], v[208:211], v[176:179], v[32:35]
	v_mfma_f32_16x16x32_bf16 v[20:23], v[200:203], v[184:187], v[20:23]
	v_mfma_f32_16x16x32_bf16 v[16:19], v[208:211], v[184:187], v[16:19]
	v_mfma_f32_16x16x32_bf16 v[4:7], v[200:203], v[192:195], v[4:7]
	v_mfma_f32_16x16x32_bf16 v[0:3], v[208:211], v[192:195], v[0:3]
	v_mfma_f32_16x16x32_bf16 v[52:55], v[204:207], v[172:175], v[52:55]
	v_mfma_f32_16x16x32_bf16 v[48:51], v[212:215], v[172:175], v[48:51]
	v_mfma_f32_16x16x32_bf16 v[36:39], v[204:207], v[180:183], v[36:39]
	v_mfma_f32_16x16x32_bf16 v[32:35], v[212:215], v[180:183], v[32:35]
	v_mfma_f32_16x16x32_bf16 v[20:23], v[204:207], v[188:191], v[20:23]
	v_mfma_f32_16x16x32_bf16 v[16:19], v[212:215], v[188:191], v[16:19]
	v_mfma_f32_16x16x32_bf16 v[4:7], v[204:207], v[196:199], v[4:7]
	v_mfma_f32_16x16x32_bf16 v[0:3], v[212:215], v[196:199], v[0:3]
	s_barrier
	s_cbranch_scc0 .LBB0_796
	v_lshl_add_u32 v144, s38, 8, v152
	v_ashrrev_i32_e32 v145, 31, v144
	v_lshl_add_u64 v[150:151], v[144:145], 2, s[14:15]
	v_mov_b32_e32 v145, v224
	v_mov_b32_e32 v204, v225
	v_mov_b32_e32 v205, v226
	v_mov_b32_e32 v206, v227
	v_mov_b32_e32 v207, v228
	v_mov_b32_e32 v208, v229
	v_mov_b32_e32 v209, v230
	v_mov_b32_e32 v210, v231
	v_lshl_or_b32 v148, s53, 7, v154
	v_mov_b64_e32 v[146:147], s[20:21]
	v_ashrrev_i32_e32 v149, 31, v148
	v_mad_i64_i32 v[160:161], s[40:41], v144, s52, v[146:147]
	v_lshlrev_b64 v[148:149], 1, v[148:149]
	v_lshl_add_u64 v[160:161], v[160:161], 0, v[148:149]
	s_and_b64 vcc, exec, s[6:7]
	s_mov_b32 s53, s8
	s_mov_b32 s38, s30
	s_mov_b64 s[42:43], s[36:37]
	v_mul_f32_e32 v162, v145, v145
	v_mul_f32_e32 v145, 0xbfb8aa3b, v145
	v_mul_f32_e32 v163, v124, v162
	v_mul_f32_e32 v164, v120, v162
	v_mul_f32_e32 v120, v120, v145
	v_mul_f32_e32 v165, v125, v162
	v_mul_f32_e32 v125, v125, v145
	v_mul_f32_e32 v166, v121, v162
	v_mul_f32_e32 v121, v121, v145
	v_mul_f32_e32 v167, v126, v162
	v_mul_f32_e32 v126, v126, v145
	v_mul_f32_e32 v168, v122, v162
	v_mul_f32_e32 v122, v122, v145
	v_mul_f32_e32 v169, v127, v162
	v_mul_f32_e32 v127, v127, v145
	v_mul_f32_e32 v162, v123, v162
	v_mul_f32_e32 v123, v123, v145
	v_mul_f32_e32 v124, v124, v145
	v_exp_f32_e32 v120, v120
	v_exp_f32_e32 v125, v125
	v_exp_f32_e32 v121, v121
	v_exp_f32_e32 v126, v126
	v_exp_f32_e32 v122, v122
	v_exp_f32_e32 v127, v127
	v_exp_f32_e32 v123, v123
	v_exp_f32_e32 v124, v124
	v_add_f32_e32 v120, 1.0, v120
	v_add_f32_e32 v125, 1.0, v125
	v_add_f32_e32 v121, 1.0, v121
	v_add_f32_e32 v126, 1.0, v126
	v_add_f32_e32 v122, 1.0, v122
	v_add_f32_e32 v127, 1.0, v127
	v_add_f32_e32 v123, 1.0, v123
	v_add_f32_e32 v124, 1.0, v124
	v_rcp_f32_e32 v120, v120
	v_rcp_f32_e32 v125, v125
	v_rcp_f32_e32 v121, v121
	v_rcp_f32_e32 v126, v126
	v_rcp_f32_e32 v122, v122
	v_rcp_f32_e32 v127, v127
	v_rcp_f32_e32 v123, v123
	v_rcp_f32_e32 v124, v124
	v_mul_f32_e32 v120, v164, v120
	v_mul_f32_e32 v125, v165, v125
	v_mul_f32_e32 v121, v166, v121
	v_mul_f32_e32 v126, v167, v126
	v_mul_f32_e32 v122, v168, v122
	v_mul_f32_e32 v127, v169, v127
	v_mul_f32_e32 v123, v162, v123
	v_mul_f32_e32 v124, v163, v124
	v_mul_f32_e32 v120, v112, v120
	v_mul_f32_e32 v112, v117, v125
	v_mul_f32_e32 v117, v113, v121
	v_mul_f32_e32 v113, v118, v126
	v_mul_f32_e32 v118, v114, v122
	v_mul_f32_e32 v114, v119, v127
	v_mul_f32_e32 v115, v115, v123
	v_mul_f32_e32 v116, v116, v124
	v_cvt_pk_bf16_f32 v112, v116, v112
	v_cvt_pk_bf16_f32 v113, v113, v114
	v_cvt_pk_bf16_f32 v114, v120, v117
	v_cvt_pk_bf16_f32 v115, v118, v115
	global_store_dwordx4 v[160:161], v[112:115], off
	s_nop 1
	v_mov_b32_e32 v114, v204
	s_nop 0
	v_or_b32_e32 v112, 16, v144
	v_mad_i64_i32 v[112:113], s[40:41], v112, s52, v[146:147]
	v_lshl_add_u64 v[112:113], v[112:113], 0, v[148:149]
	v_mul_f32_e32 v115, v114, v114
	v_mul_f32_e32 v114, 0xbfb8aa3b, v114
	v_mul_f32_e32 v116, v108, v115
	v_mul_f32_e32 v117, v104, v115
	v_mul_f32_e32 v104, v104, v114
; __device__ __forceinline__ float fast_rcp(float x) { return __builtin_amdgcn_rcpf(x); }
; __device__ __forceinline__ float fast_exp2(float x) { return __builtin_amdgcn_exp2f(x); }
; __device__ __forceinline__ u32x4 pack8(f32x4 v0, f32x4 v1) { u32x4 w; w.x = cvt_pk_bf16(v0[0], v0[1]); w.y = cvt_pk_bf16(v0[2], v0[3]); w.z = cvt_pk_bf16(v1[0], v1[1]); w.w = cvt_pk_bf16(v1[2], v1[3]); return w; }
;     __device__ __forceinline__ void operator()(const f32x4 (&acc)[2][2][4][2], const Unit& u, int wr, int wc, int fr, int fq) const {
;     ...
;             for (int m = 0; m < 4; ++m) { bf16_t* rowp = O + (size_t)(row0 + ai * HALF + m * 16) * DFF + col0;
;                 const float r = rs[row0 + ai * HALF + m * 16], r2 = r * r;
;                 f32x4 h0, h1;
; #pragma unroll
;                 for (int j = 0; j < 4; ++j) {
;                     const float g0 = acc[ai][0][m][0][j], g1 = acc[ai][0][m][1][j];
;                     h0[j] = g0 * r2 * fast_rcp(1.0f + fast_exp2(g0 * (-LOG2E * r))) * acc[ai][1][m][0][j];
;                     h1[j] = g1 * r2 * fast_rcp(1.0f + fast_exp2(g1 * (-LOG2E * r))) * acc[ai][1][m][1][j]; }
;                 *(u32x4*)rowp = pack8(h0, h1); }
	v_mul_f32_e32 v118, v109, v115
	v_mul_f32_e32 v109, v109, v114
	v_mul_f32_e32 v119, v105, v115
	v_mul_f32_e32 v105, v105, v114
	v_mul_f32_e32 v120, v110, v115
	v_mul_f32_e32 v110, v110, v114
	v_mul_f32_e32 v121, v106, v115
	v_mul_f32_e32 v106, v106, v114
	v_mul_f32_e32 v122, v111, v115
	v_mul_f32_e32 v111, v111, v114
	v_mul_f32_e32 v115, v107, v115
	v_mul_f32_e32 v107, v107, v114
	v_mul_f32_e32 v108, v108, v114
	v_exp_f32_e32 v104, v104
	v_exp_f32_e32 v109, v109
	v_exp_f32_e32 v105, v105
	v_exp_f32_e32 v110, v110
	v_exp_f32_e32 v106, v106
	v_exp_f32_e32 v111, v111
	v_exp_f32_e32 v107, v107
	v_exp_f32_e32 v108, v108
	v_add_f32_e32 v104, 1.0, v104
	v_add_f32_e32 v109, 1.0, v109
	v_add_f32_e32 v105, 1.0, v105
	v_add_f32_e32 v110, 1.0, v110
	v_add_f32_e32 v106, 1.0, v106
	v_add_f32_e32 v111, 1.0, v111
	v_add_f32_e32 v107, 1.0, v107
	v_add_f32_e32 v108, 1.0, v108
	v_rcp_f32_e32 v104, v104
	v_rcp_f32_e32 v109, v109
	v_rcp_f32_e32 v105, v105
	v_rcp_f32_e32 v110, v110
	v_rcp_f32_e32 v106, v106
	v_rcp_f32_e32 v111, v111
	v_rcp_f32_e32 v107, v107
	v_rcp_f32_e32 v108, v108
	v_mul_f32_e32 v104, v117, v104
	v_mul_f32_e32 v109, v118, v109
	v_mul_f32_e32 v105, v119, v105
	v_mul_f32_e32 v110, v120, v110
	v_mul_f32_e32 v106, v121, v106
	v_mul_f32_e32 v111, v122, v111
	v_mul_f32_e32 v107, v115, v107
	v_mul_f32_e32 v108, v116, v108
	v_mul_f32_e32 v104, v96, v104
	v_mul_f32_e32 v96, v101, v109
	v_mul_f32_e32 v101, v97, v105
	v_mul_f32_e32 v97, v102, v110
	v_mul_f32_e32 v102, v98, v106
	v_mul_f32_e32 v98, v103, v111
	v_mul_f32_e32 v99, v99, v107
	v_mul_f32_e32 v100, v100, v108
	v_cvt_pk_bf16_f32 v96, v100, v96
	v_cvt_pk_bf16_f32 v97, v97, v98
	v_cvt_pk_bf16_f32 v98, v104, v101
	v_cvt_pk_bf16_f32 v99, v102, v99
	global_store_dwordx4 v[112:113], v[96:99], off
	s_nop 1
	v_mov_b32_e32 v98, v205
	s_nop 0
	v_or_b32_e32 v96, 32, v144
	v_mad_i64_i32 v[96:97], s[40:41], v96, s52, v[146:147]
	v_lshl_add_u64 v[96:97], v[96:97], 0, v[148:149]
	v_mul_f32_e32 v99, v98, v98
	v_mul_f32_e32 v98, 0xbfb8aa3b, v98
	v_mul_f32_e32 v100, v92, v99
	v_mul_f32_e32 v101, v88, v99
	v_mul_f32_e32 v88, v88, v98
	v_mul_f32_e32 v102, v93, v99
	v_mul_f32_e32 v93, v93, v98
	v_mul_f32_e32 v103, v89, v99
	v_mul_f32_e32 v89, v89, v98
	v_mul_f32_e32 v104, v94, v99
	v_mul_f32_e32 v94, v94, v98
	v_mul_f32_e32 v105, v90, v99
	v_mul_f32_e32 v90, v90, v98
	v_mul_f32_e32 v106, v95, v99
	v_mul_f32_e32 v95, v95, v98
	v_mul_f32_e32 v99, v91, v99
	v_mul_f32_e32 v91, v91, v98
	v_mul_f32_e32 v92, v92, v98
	v_exp_f32_e32 v88, v88
	v_exp_f32_e32 v93, v93
	v_exp_f32_e32 v89, v89
	v_exp_f32_e32 v94, v94
	v_exp_f32_e32 v90, v90
	v_exp_f32_e32 v95, v95
	v_exp_f32_e32 v91, v91
	v_exp_f32_e32 v92, v92
	v_add_f32_e32 v88, 1.0, v88
	v_add_f32_e32 v93, 1.0, v93
	v_add_f32_e32 v89, 1.0, v89
	v_add_f32_e32 v94, 1.0, v94
	v_add_f32_e32 v90, 1.0, v90
	v_add_f32_e32 v95, 1.0, v95
	v_add_f32_e32 v91, 1.0, v91
	v_add_f32_e32 v92, 1.0, v92
	v_rcp_f32_e32 v88, v88
	v_rcp_f32_e32 v93, v93
	v_rcp_f32_e32 v89, v89
	v_rcp_f32_e32 v94, v94
	v_rcp_f32_e32 v90, v90
	v_rcp_f32_e32 v95, v95
	v_rcp_f32_e32 v91, v91
	v_rcp_f32_e32 v92, v92
	v_mul_f32_e32 v88, v101, v88
	v_mul_f32_e32 v93, v102, v93
	v_mul_f32_e32 v89, v103, v89
	v_mul_f32_e32 v94, v104, v94
	v_mul_f32_e32 v90, v105, v90
	v_mul_f32_e32 v95, v106, v95
	v_mul_f32_e32 v91, v99, v91
	v_mul_f32_e32 v92, v100, v92
	v_mul_f32_e32 v88, v80, v88
	v_mul_f32_e32 v80, v85, v93
	v_mul_f32_e32 v85, v81, v89
	v_mul_f32_e32 v81, v86, v94
	v_mul_f32_e32 v86, v82, v90
	v_mul_f32_e32 v82, v87, v95
	v_mul_f32_e32 v83, v83, v91
	v_mul_f32_e32 v84, v84, v92
	v_cvt_pk_bf16_f32 v80, v84, v80
	v_cvt_pk_bf16_f32 v81, v81, v82
	v_cvt_pk_bf16_f32 v82, v88, v85
	v_cvt_pk_bf16_f32 v83, v86, v83
	global_store_dwordx4 v[96:97], v[80:83], off
	s_nop 1
	v_mov_b32_e32 v82, v206
	s_nop 0
	v_or_b32_e32 v80, 48, v144
	v_mad_i64_i32 v[80:81], s[40:41], v80, s52, v[146:147]
	v_lshl_add_u64 v[80:81], v[80:81], 0, v[148:149]
	v_mul_f32_e32 v83, v82, v82
	v_mul_f32_e32 v82, 0xbfb8aa3b, v82
	v_mul_f32_e32 v84, v76, v83
	v_mul_f32_e32 v85, v72, v83
	v_mul_f32_e32 v72, v72, v82
	v_mul_f32_e32 v86, v77, v83
	v_mul_f32_e32 v77, v77, v82
	v_mul_f32_e32 v87, v73, v83
	v_mul_f32_e32 v73, v73, v82
	v_mul_f32_e32 v88, v78, v83
	v_mul_f32_e32 v78, v78, v82
	v_mul_f32_e32 v89, v74, v83
	v_mul_f32_e32 v74, v74, v82
	v_mul_f32_e32 v90, v79, v83
	v_mul_f32_e32 v79, v79, v82
	v_mul_f32_e32 v83, v75, v83
	v_mul_f32_e32 v75, v75, v82
	v_mul_f32_e32 v76, v76, v82
	v_exp_f32_e32 v72, v72
	v_exp_f32_e32 v77, v77
	v_exp_f32_e32 v73, v73
	v_exp_f32_e32 v78, v78
	v_exp_f32_e32 v74, v74
	v_exp_f32_e32 v79, v79
	v_exp_f32_e32 v75, v75
	v_exp_f32_e32 v76, v76
	v_add_f32_e32 v72, 1.0, v72
	v_add_f32_e32 v77, 1.0, v77
	v_add_f32_e32 v73, 1.0, v73
	v_add_f32_e32 v78, 1.0, v78
	v_add_f32_e32 v74, 1.0, v74
	v_add_f32_e32 v79, 1.0, v79
	v_add_f32_e32 v75, 1.0, v75
	v_add_f32_e32 v76, 1.0, v76
	v_rcp_f32_e32 v72, v72
	v_rcp_f32_e32 v77, v77
	v_rcp_f32_e32 v73, v73
	v_rcp_f32_e32 v78, v78
	v_rcp_f32_e32 v74, v74
	v_rcp_f32_e32 v79, v79
	v_rcp_f32_e32 v75, v75
	v_rcp_f32_e32 v76, v76
	v_mul_f32_e32 v72, v85, v72
	v_mul_f32_e32 v77, v86, v77
	v_mul_f32_e32 v73, v87, v73
	v_mul_f32_e32 v78, v88, v78
	v_mul_f32_e32 v74, v89, v74
	v_mul_f32_e32 v79, v90, v79
	v_mul_f32_e32 v75, v83, v75
	v_mul_f32_e32 v76, v84, v76
	v_mul_f32_e32 v72, v64, v72
	v_mul_f32_e32 v64, v69, v77
	v_mul_f32_e32 v69, v65, v73
	v_mul_f32_e32 v65, v70, v78
	v_mul_f32_e32 v70, v66, v74
	v_mul_f32_e32 v66, v71, v79
	v_mul_f32_e32 v67, v67, v75
	v_mul_f32_e32 v68, v68, v76
	v_cvt_pk_bf16_f32 v64, v68, v64
	v_cvt_pk_bf16_f32 v65, v65, v66
	v_cvt_pk_bf16_f32 v66, v72, v69
; __device__ __forceinline__ float fast_rcp(float x) { return __builtin_amdgcn_rcpf(x); }
; __device__ __forceinline__ float fast_exp2(float x) { return __builtin_amdgcn_exp2f(x); }
; __device__ __forceinline__ u32x4 pack8(f32x4 v0, f32x4 v1) { u32x4 w; w.x = cvt_pk_bf16(v0[0], v0[1]); w.y = cvt_pk_bf16(v0[2], v0[3]); w.z = cvt_pk_bf16(v1[0], v1[1]); w.w = cvt_pk_bf16(v1[2], v1[3]); return w; }
;     __device__ __forceinline__ void operator()(const f32x4 (&acc)[2][2][4][2], const Unit& u, int wr, int wc, int fr, int fq) const {
;     ...
;             for (int m = 0; m < 4; ++m) { bf16_t* rowp = O + (size_t)(row0 + ai * HALF + m * 16) * DFF + col0;
;                 const float r = rs[row0 + ai * HALF + m * 16], r2 = r * r;
;                 f32x4 h0, h1;
; #pragma unroll
;                 for (int j = 0; j < 4; ++j) {
;                     const float g0 = acc[ai][0][m][0][j], g1 = acc[ai][0][m][1][j];
;                     h0[j] = g0 * r2 * fast_rcp(1.0f + fast_exp2(g0 * (-LOG2E * r))) * acc[ai][1][m][0][j];
;                     h1[j] = g1 * r2 * fast_rcp(1.0f + fast_exp2(g1 * (-LOG2E * r))) * acc[ai][1][m][1][j]; }
;                 *(u32x4*)rowp = pack8(h0, h1); }
	v_cvt_pk_bf16_f32 v67, v70, v67
	global_store_dwordx4 v[80:81], v[64:67], off
	s_nop 1
	v_mov_b32_e32 v66, v207
	s_nop 0
	v_add_u32_e32 v64, 0x80, v144
	v_mad_i64_i32 v[64:65], s[40:41], v64, s52, v[146:147]
	v_lshl_add_u64 v[64:65], v[64:65], 0, v[148:149]
	v_mul_f32_e32 v67, v66, v66
	v_mul_f32_e32 v66, 0xbfb8aa3b, v66
	v_mul_f32_e32 v68, v60, v67
	v_mul_f32_e32 v69, v56, v67
	v_mul_f32_e32 v56, v56, v66
	v_mul_f32_e32 v70, v61, v67
	v_mul_f32_e32 v61, v61, v66
	v_mul_f32_e32 v71, v57, v67
	v_mul_f32_e32 v57, v57, v66
	v_mul_f32_e32 v72, v62, v67
	v_mul_f32_e32 v62, v62, v66
	v_mul_f32_e32 v73, v58, v67
	v_mul_f32_e32 v58, v58, v66
	v_mul_f32_e32 v74, v63, v67
	v_mul_f32_e32 v63, v63, v66
	v_mul_f32_e32 v67, v59, v67
	v_mul_f32_e32 v59, v59, v66
	v_mul_f32_e32 v60, v60, v66
	v_exp_f32_e32 v56, v56
	v_exp_f32_e32 v61, v61
	v_exp_f32_e32 v57, v57
	v_exp_f32_e32 v62, v62
	v_exp_f32_e32 v58, v58
	v_exp_f32_e32 v63, v63
	v_exp_f32_e32 v59, v59
	v_exp_f32_e32 v60, v60
	v_add_f32_e32 v56, 1.0, v56
	v_add_f32_e32 v61, 1.0, v61
	v_add_f32_e32 v57, 1.0, v57
	v_add_f32_e32 v62, 1.0, v62
	v_add_f32_e32 v58, 1.0, v58
	v_add_f32_e32 v63, 1.0, v63
	v_add_f32_e32 v59, 1.0, v59
	v_add_f32_e32 v60, 1.0, v60
	v_rcp_f32_e32 v56, v56
	v_rcp_f32_e32 v61, v61
	v_rcp_f32_e32 v57, v57
	v_rcp_f32_e32 v62, v62
	v_rcp_f32_e32 v58, v58
	v_rcp_f32_e32 v63, v63
	v_rcp_f32_e32 v59, v59
	v_rcp_f32_e32 v60, v60
	v_mul_f32_e32 v56, v69, v56
	v_mul_f32_e32 v61, v70, v61
	v_mul_f32_e32 v57, v71, v57
	v_mul_f32_e32 v62, v72, v62
	v_mul_f32_e32 v58, v73, v58
	v_mul_f32_e32 v63, v74, v63
	v_mul_f32_e32 v59, v67, v59
	v_mul_f32_e32 v60, v68, v60
	v_mul_f32_e32 v56, v48, v56
	v_mul_f32_e32 v48, v53, v61
	v_mul_f32_e32 v53, v49, v57
	v_mul_f32_e32 v49, v54, v62
	v_mul_f32_e32 v54, v50, v58
	v_mul_f32_e32 v50, v55, v63
	v_mul_f32_e32 v51, v51, v59
	v_mul_f32_e32 v52, v52, v60
	v_cvt_pk_bf16_f32 v48, v52, v48
	v_cvt_pk_bf16_f32 v49, v49, v50
	v_cvt_pk_bf16_f32 v50, v56, v53
	v_cvt_pk_bf16_f32 v51, v54, v51
	global_store_dwordx4 v[64:65], v[48:51], off
	s_nop 1
	v_mov_b32_e32 v50, v208
	s_nop 0
	v_add_u32_e32 v48, 0x90, v144
	v_mad_i64_i32 v[48:49], s[40:41], v48, s52, v[146:147]
	v_lshl_add_u64 v[48:49], v[48:49], 0, v[148:149]
	v_mul_f32_e32 v51, v50, v50
	v_mul_f32_e32 v50, 0xbfb8aa3b, v50
	v_mul_f32_e32 v52, v44, v51
	v_mul_f32_e32 v53, v40, v51
	v_mul_f32_e32 v40, v40, v50
	v_mul_f32_e32 v54, v45, v51
	v_mul_f32_e32 v45, v45, v50
	v_mul_f32_e32 v55, v41, v51
	v_mul_f32_e32 v41, v41, v50
	v_mul_f32_e32 v56, v46, v51
	v_mul_f32_e32 v46, v46, v50
	v_mul_f32_e32 v57, v42, v51
	v_mul_f32_e32 v42, v42, v50
	v_mul_f32_e32 v58, v47, v51
	v_mul_f32_e32 v47, v47, v50
	v_mul_f32_e32 v51, v43, v51
	v_mul_f32_e32 v43, v43, v50
	v_mul_f32_e32 v44, v44, v50
	v_exp_f32_e32 v40, v40
	v_exp_f32_e32 v45, v45
	v_exp_f32_e32 v41, v41
	v_exp_f32_e32 v46, v46
	v_exp_f32_e32 v42, v42
	v_exp_f32_e32 v47, v47
	v_exp_f32_e32 v43, v43
	v_exp_f32_e32 v44, v44
	v_add_f32_e32 v40, 1.0, v40
	v_add_f32_e32 v45, 1.0, v45
	v_add_f32_e32 v41, 1.0, v41
	v_add_f32_e32 v46, 1.0, v46
	v_add_f32_e32 v42, 1.0, v42
	v_add_f32_e32 v47, 1.0, v47
	v_add_f32_e32 v43, 1.0, v43
	v_add_f32_e32 v44, 1.0, v44
	v_rcp_f32_e32 v40, v40
	v_rcp_f32_e32 v45, v45
	v_rcp_f32_e32 v41, v41
	v_rcp_f32_e32 v46, v46
	v_rcp_f32_e32 v42, v42
	v_rcp_f32_e32 v47, v47
	v_rcp_f32_e32 v43, v43
	v_rcp_f32_e32 v44, v44
	v_mul_f32_e32 v40, v53, v40
	v_mul_f32_e32 v45, v54, v45
	v_mul_f32_e32 v41, v55, v41
	v_mul_f32_e32 v46, v56, v46
	v_mul_f32_e32 v42, v57, v42
	v_mul_f32_e32 v47, v58, v47
	v_mul_f32_e32 v43, v51, v43
	v_mul_f32_e32 v44, v52, v44
	v_mul_f32_e32 v40, v32, v40
	v_mul_f32_e32 v32, v37, v45
	v_mul_f32_e32 v37, v33, v41
	v_mul_f32_e32 v33, v38, v46
	v_mul_f32_e32 v38, v34, v42
	v_mul_f32_e32 v34, v39, v47
	v_mul_f32_e32 v35, v35, v43
	v_mul_f32_e32 v36, v36, v44
	v_cvt_pk_bf16_f32 v32, v36, v32
	v_cvt_pk_bf16_f32 v33, v33, v34
	v_cvt_pk_bf16_f32 v34, v40, v37
	v_cvt_pk_bf16_f32 v35, v38, v35
	global_store_dwordx4 v[48:49], v[32:35], off
; __device__ __forceinline__ float fast_rcp(float x) { return __builtin_amdgcn_rcpf(x); }
; __device__ __forceinline__ float fast_exp2(float x) { return __builtin_amdgcn_exp2f(x); }
; #define PG8_WAIT_V(n) asm volatile("s_waitcnt vmcnt(" #n ")" ::: "memory")
; #define PG8_BAR __builtin_amdgcn_s_barrier()
; __device__ __forceinline__ u32x4 pack8(f32x4 v0, f32x4 v1) { u32x4 w; w.x = cvt_pk_bf16(v0[0], v0[1]); w.y = cvt_pk_bf16(v0[2], v0[3]); w.z = cvt_pk_bf16(v1[0], v1[1]); w.w = cvt_pk_bf16(v1[2], v1[3]); return w; }
; template <class Epi>
; __device__ __forceinline__ void gemm_phase(LAS unsigned char* lds, const Gemm g, const StaticOrder& S, const Epi& E) {
;     ...
;         if (!has_next) break;
; #pragma unroll
;         for (int a = 0; a < 2; ++a)
; #pragma unroll
;             for (int b = 0; b < 2; ++b)
; #pragma unroll
;                 for (int m = 0; m < 4; ++m)
; #pragma unroll
;                     for (int n = 0; n < 2; ++n) acc[a][b][m][n] = (f32x4){0.f, 0.f, 0.f, 0.f};
;         cur = nxt; cA = nA; cB = nB; ++ui;
;     }
;     PG8_WAIT_V(0);
;     if (wr == 0) PG8_BAR;
;     PG8_BAR;
;     __device__ __forceinline__ void operator()(const f32x4 (&acc)[2][2][4][2], const Unit& u, int wr, int wc, int fr, int fq) const {
;     ...
;             for (int m = 0; m < 4; ++m) { bf16_t* rowp = O + (size_t)(row0 + ai * HALF + m * 16) * DFF + col0;
;                 const float r = rs[row0 + ai * HALF + m * 16], r2 = r * r;
;                 f32x4 h0, h1;
; #pragma unroll
;                 for (int j = 0; j < 4; ++j) {
;                     const float g0 = acc[ai][0][m][0][j], g1 = acc[ai][0][m][1][j];
;                     h0[j] = g0 * r2 * fast_rcp(1.0f + fast_exp2(g0 * (-LOG2E * r))) * acc[ai][1][m][0][j];
;                     h1[j] = g1 * r2 * fast_rcp(1.0f + fast_exp2(g1 * (-LOG2E * r))) * acc[ai][1][m][1][j]; }
;                 *(u32x4*)rowp = pack8(h0, h1); }
	s_nop 1
	v_mov_b32_e32 v34, v209
	s_nop 0
	v_add_u32_e32 v32, 0xa0, v144
	v_mad_i64_i32 v[32:33], s[40:41], v32, s52, v[146:147]
	v_lshl_add_u64 v[32:33], v[32:33], 0, v[148:149]
	s_mov_b64 s[40:41], s[34:35]
	v_mul_f32_e32 v35, v34, v34
	v_mul_f32_e32 v34, 0xbfb8aa3b, v34
	v_mul_f32_e32 v36, v28, v35
	v_mul_f32_e32 v37, v24, v35
	v_mul_f32_e32 v24, v24, v34
	v_mul_f32_e32 v38, v29, v35
	v_mul_f32_e32 v29, v29, v34
	v_mul_f32_e32 v39, v25, v35
	v_mul_f32_e32 v25, v25, v34
	v_mul_f32_e32 v40, v30, v35
	v_mul_f32_e32 v30, v30, v34
	v_mul_f32_e32 v41, v26, v35
	v_mul_f32_e32 v26, v26, v34
	v_mul_f32_e32 v42, v31, v35
	v_mul_f32_e32 v31, v31, v34
	v_mul_f32_e32 v35, v27, v35
	v_mul_f32_e32 v27, v27, v34
	v_mul_f32_e32 v28, v28, v34
	v_exp_f32_e32 v24, v24
	v_exp_f32_e32 v29, v29
	v_exp_f32_e32 v25, v25
	v_exp_f32_e32 v30, v30
	v_exp_f32_e32 v26, v26
	v_exp_f32_e32 v31, v31
	v_exp_f32_e32 v27, v27
	v_exp_f32_e32 v28, v28
	v_add_f32_e32 v24, 1.0, v24
	v_add_f32_e32 v29, 1.0, v29
	v_add_f32_e32 v25, 1.0, v25
	v_add_f32_e32 v30, 1.0, v30
	v_add_f32_e32 v26, 1.0, v26
	v_add_f32_e32 v31, 1.0, v31
	v_add_f32_e32 v27, 1.0, v27
	v_add_f32_e32 v28, 1.0, v28
	v_rcp_f32_e32 v24, v24
	v_rcp_f32_e32 v29, v29
	v_rcp_f32_e32 v25, v25
	v_rcp_f32_e32 v30, v30
	v_rcp_f32_e32 v26, v26
	v_rcp_f32_e32 v31, v31
	v_rcp_f32_e32 v27, v27
	v_rcp_f32_e32 v28, v28
	v_mul_f32_e32 v24, v37, v24
	v_mul_f32_e32 v29, v38, v29
	v_mul_f32_e32 v25, v39, v25
	v_mul_f32_e32 v30, v40, v30
	v_mul_f32_e32 v26, v41, v26
	v_mul_f32_e32 v31, v42, v31
	v_mul_f32_e32 v27, v35, v27
	v_mul_f32_e32 v28, v36, v28
	v_mul_f32_e32 v24, v16, v24
	v_mul_f32_e32 v16, v21, v29
	v_mul_f32_e32 v21, v17, v25
	v_mul_f32_e32 v17, v22, v30
	v_mul_f32_e32 v22, v18, v26
	v_mul_f32_e32 v18, v23, v31
	v_mul_f32_e32 v19, v19, v27
	v_mul_f32_e32 v20, v20, v28
	v_cvt_pk_bf16_f32 v16, v20, v16
	v_cvt_pk_bf16_f32 v17, v17, v18
	v_cvt_pk_bf16_f32 v18, v24, v21
	v_cvt_pk_bf16_f32 v19, v22, v19
	global_store_dwordx4 v[32:33], v[16:19], off
	s_nop 1
	v_mov_b32_e32 v18, v210
	s_nop 0
	v_add_u32_e32 v16, 0xb0, v144
	v_mad_i64_i32 v[16:17], s[6:7], v16, s52, v[146:147]
	v_lshl_add_u64 v[16:17], v[16:17], 0, v[148:149]
	v_mul_f32_e32 v19, v18, v18
	v_mul_f32_e32 v18, 0xbfb8aa3b, v18
	v_mul_f32_e32 v20, v12, v19
	v_mul_f32_e32 v21, v8, v19
	v_mul_f32_e32 v8, v8, v18
	v_mul_f32_e32 v22, v13, v19
	v_mul_f32_e32 v13, v13, v18
	v_mul_f32_e32 v23, v9, v19
	v_mul_f32_e32 v9, v9, v18
	v_mul_f32_e32 v24, v14, v19
	v_mul_f32_e32 v14, v14, v18
	v_mul_f32_e32 v25, v10, v19
	v_mul_f32_e32 v10, v10, v18
	v_mul_f32_e32 v26, v15, v19
	v_mul_f32_e32 v15, v15, v18
	v_mul_f32_e32 v19, v11, v19
	v_mul_f32_e32 v11, v11, v18
	v_mul_f32_e32 v12, v12, v18
	v_exp_f32_e32 v8, v8
	v_exp_f32_e32 v13, v13
	v_exp_f32_e32 v9, v9
	v_exp_f32_e32 v14, v14
	v_exp_f32_e32 v10, v10
	v_exp_f32_e32 v15, v15
	v_exp_f32_e32 v11, v11
	v_exp_f32_e32 v12, v12
	v_add_f32_e32 v8, 1.0, v8
	v_add_f32_e32 v13, 1.0, v13
	v_add_f32_e32 v9, 1.0, v9
	v_add_f32_e32 v14, 1.0, v14
	v_add_f32_e32 v10, 1.0, v10
	v_add_f32_e32 v15, 1.0, v15
	v_add_f32_e32 v11, 1.0, v11
	v_add_f32_e32 v12, 1.0, v12
	v_rcp_f32_e32 v8, v8
	v_rcp_f32_e32 v13, v13
	v_rcp_f32_e32 v9, v9
	v_rcp_f32_e32 v14, v14
	v_rcp_f32_e32 v10, v10
	v_rcp_f32_e32 v15, v15
	v_rcp_f32_e32 v11, v11
	v_rcp_f32_e32 v12, v12
	v_mul_f32_e32 v8, v21, v8
	v_mul_f32_e32 v13, v22, v13
	v_mul_f32_e32 v9, v23, v9
	v_mul_f32_e32 v14, v24, v14
	v_mul_f32_e32 v10, v25, v10
	v_mul_f32_e32 v15, v26, v15
	v_mul_f32_e32 v11, v19, v11
	v_mul_f32_e32 v12, v20, v12
	v_mul_f32_e32 v8, v0, v8
	v_mul_f32_e32 v0, v5, v13
	v_mul_f32_e32 v5, v1, v9
	v_mul_f32_e32 v1, v6, v14
	v_mul_f32_e32 v6, v2, v10
	v_mul_f32_e32 v2, v7, v15
	v_mul_f32_e32 v3, v3, v11
	v_mul_f32_e32 v4, v4, v12
	v_cvt_pk_bf16_f32 v0, v4, v0
	v_cvt_pk_bf16_f32 v1, v1, v2
	v_cvt_pk_bf16_f32 v2, v8, v5
	v_cvt_pk_bf16_f32 v3, v6, v3
	global_store_dwordx4 v[16:17], v[0:3], off
	s_cbranch_vccz .LBB0_793
	s_waitcnt vmcnt(0)
	s_cmpk_gt_u32 s10, 0xff
	s_cbranch_scc1 .LBB0_800
	s_barrier

; #define PG8_STAGE(bufoff, gbase, voff) do { _Pragma("unroll") for (int _i = 0; _i < 2; ++_i) \
;         __builtin_amdgcn_global_load_lds((const unsigned*)((const char*)(gbase) + (voff)[_i]), (LAS unsigned*)(lds + (bufoff) + ldsw + _i * 8192), 16, 0, 0); } while (0)
; #define PG8_LDA(dst, b, h) do { _Pragma("unroll") for (int m = 0; m < 4; ++m) _Pragma("unroll") for (int k = 0; k < 2; ++k) dst[m][k] = *(const LAS bf16x8*)(lds + PG8_SA(b, h) + aoff + m * 2048 + k * 1024); } while (0)
; #define PG8_LDB(dst, b, h) do { _Pragma("unroll") for (int n = 0; n < 2; ++n) _Pragma("unroll") for (int k = 0; k < 2; ++k) dst[n][k] = *(const LAS bf16x8*)(lds + PG8_SB(b, h) + boff + n * 2048 + k * 1024); } while (0)
; #define PG8_MMA(ai, bj, At, Bt) do { __builtin_amdgcn_s_setprio(1); _Pragma("unroll") for (int m = 0; m < 4; ++m) _Pragma("unroll") for (int n = 0; n < 2; ++n) _Pragma("unroll") for (int k = 0; k < 2; ++k) \
;         acc[ai][bj][m][n] = __builtin_amdgcn_mfma_f32_16x16x32_bf16(Bt[n][k], At[m][k], acc[ai][bj][m][n], 0, 0, 0); __builtin_amdgcn_s_setprio(0); } while (0)
; #define PG8_WAIT_V(n) asm volatile("s_waitcnt vmcnt(" #n ")" ::: "memory")
; #define PG8_WAIT_L(n) asm volatile("s_waitcnt lgkmcnt(" #n ")" ::: "memory")
; #define PG8_BAR __builtin_amdgcn_s_barrier()
; #define PG8_SCHED __builtin_amdgcn_sched_barrier(0)
; template <class Epi>
; __device__ __forceinline__ void gemm_phase(LAS unsigned char* lds, const Gemm g, const StaticOrder& S, const Epi& E) {
;     ...
;             PG8_LDB(B0, 0, 0); PG8_SCHED; PG8_LDA(At, 0, 0); PG8_STAGE(PG8_SA(1, 1), a1 + hstep, voffA);
;             PG8_WAIT_L(8); PG8_BAR; PG8_WAIT_L(0); PG8_MMA(0, 0, At, B0); PG8_BAR; PG8_SCHED;
;             PG8_LDB(B1, 0, 1); PG8_STAGE(PG8_SB(0, 0), b2, voffB);
;             PG8_BAR; PG8_WAIT_L(0); PG8_MMA(0, 1, At, B1); PG8_BAR;
;             PG8_LDA(At, 0, 1); PG8_STAGE(PG8_SA(0, 0), a2, voffA);
;             PG8_BAR; PG8_WAIT_L(0); PG8_MMA(1, 0, At, B0); PG8_BAR; PG8_SCHED;
;             PG8_STAGE(PG8_SB(0, 1), b2 + hstep, voffB);
;             PG8_WAIT_V(6); PG8_BAR; PG8_MMA(1, 1, At, B1); PG8_BAR;
.LBB0_864:
	ds_read_b128 v[148:151], v145
	ds_read_b128 v[152:155], v145 offset:1024
	ds_read_b128 v[160:163], v145 offset:2048
	ds_read_b128 v[164:167], v145 offset:3072
	s_add_u32 s44, s42, 0x100
	s_addc_u32 s45, s43, 0
	s_cmpk_eq_i32 s67, 0x54
	s_cselect_b32 s49, s41, s45
	s_cselect_b32 s48, s40, s44
	s_cselect_b32 s47, s7, s66
	s_cselect_b32 s46, s6, s65
	s_add_i32 m0, s28, 0xc000
	ds_read_b128 v[168:171], v146
	ds_read_b128 v[172:175], v146 offset:1024
	ds_read_b128 v[176:179], v146 offset:2048
	ds_read_b128 v[180:183], v146 offset:3072
	ds_read_b128 v[184:187], v146 offset:4096
	ds_read_b128 v[188:191], v146 offset:5120
	ds_read_b128 v[192:195], v146 offset:6144
	ds_read_b128 v[196:199], v146 offset:7168
	global_load_lds_dwordx4 v136, s[42:43]
	s_add_i32 m0, s28, 0xe000
	s_nop 0
	global_load_lds_dwordx4 v138, s[42:43]
	s_waitcnt lgkmcnt(8)
	s_barrier
	s_waitcnt lgkmcnt(0)
	v_mfma_f32_16x16x32_bf16 v[124:127], v[148:151], v[168:171], v[124:127]
	v_mfma_f32_16x16x32_bf16 v[120:123], v[160:163], v[168:171], v[120:123]
	v_mfma_f32_16x16x32_bf16 v[112:115], v[148:151], v[176:179], v[112:115]
	v_mfma_f32_16x16x32_bf16 v[104:107], v[160:163], v[176:179], v[104:107]
	v_mfma_f32_16x16x32_bf16 v[96:99], v[148:151], v[184:187], v[96:99]
	v_mfma_f32_16x16x32_bf16 v[88:91], v[160:163], v[184:187], v[88:91]
	v_mfma_f32_16x16x32_bf16 v[80:83], v[148:151], v[192:195], v[80:83]
	v_mfma_f32_16x16x32_bf16 v[72:75], v[160:163], v[192:195], v[72:75]
	v_mfma_f32_16x16x32_bf16 v[124:127], v[152:155], v[172:175], v[124:127]
	v_mfma_f32_16x16x32_bf16 v[120:123], v[164:167], v[172:175], v[120:123]
	v_mfma_f32_16x16x32_bf16 v[112:115], v[152:155], v[180:183], v[112:115]
	v_mfma_f32_16x16x32_bf16 v[104:107], v[164:167], v[180:183], v[104:107]
	v_mfma_f32_16x16x32_bf16 v[96:99], v[152:155], v[188:191], v[96:99]
	v_mfma_f32_16x16x32_bf16 v[88:91], v[164:167], v[188:191], v[88:91]
	v_mfma_f32_16x16x32_bf16 v[80:83], v[152:155], v[196:199], v[80:83]
	v_mfma_f32_16x16x32_bf16 v[72:75], v[164:167], v[196:199], v[72:75]
	s_barrier
	s_add_i32 s42, s55, s23
	s_add_u32 s98, s46, s2
	s_addc_u32 s99, s47, s3
	s_mov_b32 m0, s42
	ds_read_b128 v[200:203], v147
	ds_read_b128 v[204:207], v147 offset:1024
	ds_read_b128 v[208:211], v147 offset:2048
	ds_read_b128 v[212:215], v147 offset:3072
	global_load_lds_dwordx4 v132, s[46:47]
	s_add_i32 m0, s42, 0x2000
	s_nop 0
	global_load_lds_dwordx4 v128, s[46:47]
	s_barrier
	s_waitcnt lgkmcnt(0)
	v_mfma_f32_16x16x32_bf16 v[116:119], v[200:203], v[168:171], v[116:119]
	v_mfma_f32_16x16x32_bf16 v[108:111], v[208:211], v[168:171], v[108:111]
	v_mfma_f32_16x16x32_bf16 v[100:103], v[200:203], v[176:179], v[100:103]
	v_mfma_f32_16x16x32_bf16 v[92:95], v[208:211], v[176:179], v[92:95]
	v_mfma_f32_16x16x32_bf16 v[84:87], v[200:203], v[184:187], v[84:87]
	v_mfma_f32_16x16x32_bf16 v[76:79], v[208:211], v[184:187], v[76:79]
	v_mfma_f32_16x16x32_bf16 v[68:71], v[200:203], v[192:195], v[68:71]
	v_mfma_f32_16x16x32_bf16 v[64:67], v[208:211], v[192:195], v[64:67]
	v_mfma_f32_16x16x32_bf16 v[116:119], v[204:207], v[172:175], v[116:119]
	v_mfma_f32_16x16x32_bf16 v[108:111], v[212:215], v[172:175], v[108:111]
	v_mfma_f32_16x16x32_bf16 v[100:103], v[204:207], v[180:183], v[100:103]
	v_mfma_f32_16x16x32_bf16 v[92:95], v[212:215], v[180:183], v[92:95]
	v_mfma_f32_16x16x32_bf16 v[84:87], v[204:207], v[188:191], v[84:87]
	v_mfma_f32_16x16x32_bf16 v[76:79], v[212:215], v[188:191], v[76:79]
	v_mfma_f32_16x16x32_bf16 v[68:71], v[204:207], v[196:199], v[68:71]
	v_mfma_f32_16x16x32_bf16 v[64:67], v[212:215], v[196:199], v[64:67]
	s_mov_b32 m0, s28
	s_add_u32 s100, s48, s2
	s_addc_u32 s101, s49, s3
	s_barrier
	ds_read_b128 v[168:171], v146 offset:16384
	ds_read_b128 v[172:175], v146 offset:17408
	ds_read_b128 v[176:179], v146 offset:18432
	ds_read_b128 v[180:183], v146 offset:19456
	ds_read_b128 v[184:187], v146 offset:20480
	ds_read_b128 v[188:191], v146 offset:21504
	ds_read_b128 v[192:195], v146 offset:22528
	ds_read_b128 v[196:199], v146 offset:23552
	global_load_lds_dwordx4 v134, s[48:49]
	s_mov_b32 m0, s29
	s_nop 0
	global_load_lds_dwordx4 v130, s[48:49]
	s_barrier
	s_waitcnt lgkmcnt(0)
	v_mfma_f32_16x16x32_bf16 v[60:63], v[148:151], v[168:171], v[60:63]
	v_mfma_f32_16x16x32_bf16 v[56:59], v[160:163], v[168:171], v[56:59]
	v_mfma_f32_16x16x32_bf16 v[52:55], v[148:151], v[176:179], v[52:55]
	v_mfma_f32_16x16x32_bf16 v[44:47], v[160:163], v[176:179], v[44:47]
	v_mfma_f32_16x16x32_bf16 v[36:39], v[148:151], v[184:187], v[36:39]
	v_mfma_f32_16x16x32_bf16 v[28:31], v[160:163], v[184:187], v[28:31]
	v_mfma_f32_16x16x32_bf16 v[20:23], v[148:151], v[192:195], v[20:23]
	v_mfma_f32_16x16x32_bf16 v[12:15], v[160:163], v[192:195], v[12:15]
	v_mfma_f32_16x16x32_bf16 v[60:63], v[152:155], v[172:175], v[60:63]
	v_mfma_f32_16x16x32_bf16 v[56:59], v[164:167], v[172:175], v[56:59]
	v_mfma_f32_16x16x32_bf16 v[52:55], v[152:155], v[180:183], v[52:55]
	v_mfma_f32_16x16x32_bf16 v[44:47], v[164:167], v[180:183], v[44:47]
	v_mfma_f32_16x16x32_bf16 v[36:39], v[152:155], v[188:191], v[36:39]
	v_mfma_f32_16x16x32_bf16 v[28:31], v[164:167], v[188:191], v[28:31]
	v_mfma_f32_16x16x32_bf16 v[20:23], v[152:155], v[196:199], v[20:23]
	v_mfma_f32_16x16x32_bf16 v[12:15], v[164:167], v[196:199], v[12:15]
	s_barrier
	s_add_u32 s42, s46, 0x160000
	s_addc_u32 s43, s47, 0
	s_add_i32 s68, s56, s23
	s_mov_b32 m0, s68
	s_nop 0
	global_load_lds_dwordx4 v132, s[42:43]
	s_add_i32 m0, s68, 0x2000
	s_nop 0
	global_load_lds_dwordx4 v128, s[42:43]
	s_waitcnt vmcnt(6)
	s_barrier
; #define PG8_STAGE(bufoff, gbase, voff) do { _Pragma("unroll") for (int _i = 0; _i < 2; ++_i) \
;         __builtin_amdgcn_global_load_lds((const unsigned*)((const char*)(gbase) + (voff)[_i]), (LAS unsigned*)(lds + (bufoff) + ldsw + _i * 8192), 16, 0, 0); } while (0)
; #define PG8_LDA(dst, b, h) do { _Pragma("unroll") for (int m = 0; m < 4; ++m) _Pragma("unroll") for (int k = 0; k < 2; ++k) dst[m][k] = *(const LAS bf16x8*)(lds + PG8_SA(b, h) + aoff + m * 2048 + k * 1024); } while (0)
; #define PG8_LDB(dst, b, h) do { _Pragma("unroll") for (int n = 0; n < 2; ++n) _Pragma("unroll") for (int k = 0; k < 2; ++k) dst[n][k] = *(const LAS bf16x8*)(lds + PG8_SB(b, h) + boff + n * 2048 + k * 1024); } while (0)
; #define PG8_MMA(ai, bj, At, Bt) do { __builtin_amdgcn_s_setprio(1); _Pragma("unroll") for (int m = 0; m < 4; ++m) _Pragma("unroll") for (int n = 0; n < 2; ++n) _Pragma("unroll") for (int k = 0; k < 2; ++k) \
;         acc[ai][bj][m][n] = __builtin_amdgcn_mfma_f32_16x16x32_bf16(Bt[n][k], At[m][k], acc[ai][bj][m][n], 0, 0, 0); __builtin_amdgcn_s_setprio(0); } while (0)
; #define PG8_WAIT_V(n) asm volatile("s_waitcnt vmcnt(" #n ")" ::: "memory")
; #define PG8_WAIT_L(n) asm volatile("s_waitcnt lgkmcnt(" #n ")" ::: "memory")
; #define PG8_BAR __builtin_amdgcn_s_barrier()
; #define PG8_SCHED __builtin_amdgcn_sched_barrier(0)
; template <class Epi>
; __device__ __forceinline__ void gemm_phase(LAS unsigned char* lds, const Gemm g, const StaticOrder& S, const Epi& E) {
;     ...
;             PG8_WAIT_V(6); PG8_BAR; PG8_MMA(1, 1, At, B1); PG8_BAR;
;             PG8_LDB(B0, 1, 0); PG8_SCHED; PG8_LDA(At, 1, 0); PG8_STAGE(PG8_SA(0, 1), a2 + hstep, voffA);
;             PG8_WAIT_L(8); PG8_BAR; PG8_WAIT_L(0); PG8_MMA(0, 0, At, B0); PG8_BAR; PG8_SCHED;
;             PG8_LDB(B1, 1, 1); PG8_STAGE(PG8_SB(1, 0), b3, voffB);
;             PG8_BAR; PG8_WAIT_L(0); PG8_MMA(0, 1, At, B1); PG8_BAR;
;             PG8_LDA(At, 1, 1); PG8_STAGE(PG8_SA(1, 0), a3, voffA);
;             PG8_BAR; PG8_WAIT_L(0); PG8_MMA(1, 0, At, B0); PG8_BAR; PG8_SCHED;
	v_mfma_f32_16x16x32_bf16 v[48:51], v[200:203], v[168:171], v[48:51]
	v_mfma_f32_16x16x32_bf16 v[40:43], v[208:211], v[168:171], v[40:43]
	v_mfma_f32_16x16x32_bf16 v[32:35], v[200:203], v[176:179], v[32:35]
	v_mfma_f32_16x16x32_bf16 v[24:27], v[208:211], v[176:179], v[24:27]
	v_mfma_f32_16x16x32_bf16 v[16:19], v[200:203], v[184:187], v[16:19]
	v_mfma_f32_16x16x32_bf16 v[8:11], v[208:211], v[184:187], v[8:11]
	v_mfma_f32_16x16x32_bf16 v[4:7], v[200:203], v[192:195], v[4:7]
	v_mfma_f32_16x16x32_bf16 v[0:3], v[208:211], v[192:195], v[0:3]
	v_mfma_f32_16x16x32_bf16 v[48:51], v[204:207], v[172:175], v[48:51]
	v_mfma_f32_16x16x32_bf16 v[40:43], v[212:215], v[172:175], v[40:43]
	v_mfma_f32_16x16x32_bf16 v[32:35], v[204:207], v[180:183], v[32:35]
	v_mfma_f32_16x16x32_bf16 v[24:27], v[212:215], v[180:183], v[24:27]
	v_mfma_f32_16x16x32_bf16 v[16:19], v[204:207], v[188:191], v[16:19]
	v_mfma_f32_16x16x32_bf16 v[8:11], v[212:215], v[188:191], v[8:11]
	v_mfma_f32_16x16x32_bf16 v[4:7], v[204:207], v[196:199], v[4:7]
	v_mfma_f32_16x16x32_bf16 v[0:3], v[212:215], v[196:199], v[0:3]
	s_add_i32 s68, 0, 0x18000
	v_add_u32_e32 v164, s68, v143
	s_barrier
	ds_read_b128 v[148:151], v164
	ds_read_b128 v[152:155], v164 offset:1024
	ds_read_b128 v[160:163], v164 offset:2048
	ds_read_b128 v[164:167], v164 offset:3072
	s_add_u32 s42, s48, 0x160000
	s_addc_u32 s43, s49, 0
	s_mov_b32 m0, s33
	ds_read_b128 v[168:171], v146 offset:32768
	ds_read_b128 v[172:175], v146 offset:33792
	ds_read_b128 v[176:179], v146 offset:34816
	ds_read_b128 v[180:183], v146 offset:35840
	ds_read_b128 v[184:187], v146 offset:36864
	ds_read_b128 v[188:191], v146 offset:37888
	ds_read_b128 v[192:195], v146 offset:38912
	ds_read_b128 v[196:199], v146 offset:39936
	global_load_lds_dwordx4 v134, s[42:43]
	s_mov_b32 m0, s50
	s_nop 0
	global_load_lds_dwordx4 v130, s[42:43]
	s_waitcnt lgkmcnt(8)
	s_barrier
	s_waitcnt lgkmcnt(0)
	v_mfma_f32_16x16x32_bf16 v[124:127], v[148:151], v[168:171], v[124:127]
	v_mfma_f32_16x16x32_bf16 v[120:123], v[160:163], v[168:171], v[120:123]
	v_mfma_f32_16x16x32_bf16 v[112:115], v[148:151], v[176:179], v[112:115]
	v_mfma_f32_16x16x32_bf16 v[104:107], v[160:163], v[176:179], v[104:107]
	v_mfma_f32_16x16x32_bf16 v[96:99], v[148:151], v[184:187], v[96:99]
	v_mfma_f32_16x16x32_bf16 v[88:91], v[160:163], v[184:187], v[88:91]
	v_mfma_f32_16x16x32_bf16 v[80:83], v[148:151], v[192:195], v[80:83]
	v_mfma_f32_16x16x32_bf16 v[72:75], v[160:163], v[192:195], v[72:75]
	v_mfma_f32_16x16x32_bf16 v[124:127], v[152:155], v[172:175], v[124:127]
	v_mfma_f32_16x16x32_bf16 v[120:123], v[164:167], v[172:175], v[120:123]
	v_mfma_f32_16x16x32_bf16 v[112:115], v[152:155], v[180:183], v[112:115]
	v_mfma_f32_16x16x32_bf16 v[104:107], v[164:167], v[180:183], v[104:107]
	v_mfma_f32_16x16x32_bf16 v[96:99], v[152:155], v[188:191], v[96:99]
	v_mfma_f32_16x16x32_bf16 v[88:91], v[164:167], v[188:191], v[88:91]
	v_mfma_f32_16x16x32_bf16 v[80:83], v[152:155], v[196:199], v[80:83]
	v_mfma_f32_16x16x32_bf16 v[72:75], v[164:167], v[196:199], v[72:75]
	s_barrier
	s_add_i32 s48, 0, 0x1c000
	s_add_i32 s42, s68, s23
	v_add_u32_e32 v212, s48, v143
	s_mov_b32 m0, s42
	ds_read_b128 v[200:203], v212
	ds_read_b128 v[204:207], v212 offset:1024
	ds_read_b128 v[208:211], v212 offset:2048
	ds_read_b128 v[212:215], v212 offset:3072
	global_load_lds_dwordx4 v132, s[98:99]
	s_add_i32 m0, s42, 0x2000
	s_nop 0
	global_load_lds_dwordx4 v128, s[98:99]
	s_barrier
	s_waitcnt lgkmcnt(0)
	v_mfma_f32_16x16x32_bf16 v[116:119], v[200:203], v[168:171], v[116:119]
	v_mfma_f32_16x16x32_bf16 v[108:111], v[208:211], v[168:171], v[108:111]
	v_mfma_f32_16x16x32_bf16 v[100:103], v[200:203], v[176:179], v[100:103]
	v_mfma_f32_16x16x32_bf16 v[92:95], v[208:211], v[176:179], v[92:95]
	v_mfma_f32_16x16x32_bf16 v[84:87], v[200:203], v[184:187], v[84:87]
	v_mfma_f32_16x16x32_bf16 v[76:79], v[208:211], v[184:187], v[76:79]
	v_mfma_f32_16x16x32_bf16 v[68:71], v[200:203], v[192:195], v[68:71]
	v_mfma_f32_16x16x32_bf16 v[64:67], v[208:211], v[192:195], v[64:67]
	v_mfma_f32_16x16x32_bf16 v[116:119], v[204:207], v[172:175], v[116:119]
	v_mfma_f32_16x16x32_bf16 v[108:111], v[212:215], v[172:175], v[108:111]
	v_mfma_f32_16x16x32_bf16 v[100:103], v[204:207], v[180:183], v[100:103]
	v_mfma_f32_16x16x32_bf16 v[92:95], v[212:215], v[180:183], v[92:95]
	v_mfma_f32_16x16x32_bf16 v[84:87], v[204:207], v[188:191], v[84:87]
	v_mfma_f32_16x16x32_bf16 v[76:79], v[212:215], v[188:191], v[76:79]
	v_mfma_f32_16x16x32_bf16 v[68:71], v[204:207], v[196:199], v[68:71]
	v_mfma_f32_16x16x32_bf16 v[64:67], v[212:215], v[196:199], v[64:67]
	s_mov_b32 m0, s52
	s_barrier
	ds_read_b128 v[168:171], v146 offset:49152
	ds_read_b128 v[172:175], v146 offset:50176
	ds_read_b128 v[176:179], v146 offset:51200
	ds_read_b128 v[180:183], v146 offset:52224
	ds_read_b128 v[184:187], v146 offset:53248
	ds_read_b128 v[188:191], v146 offset:54272
	ds_read_b128 v[192:195], v146 offset:55296
	ds_read_b128 v[196:199], v146 offset:56320
	global_load_lds_dwordx4 v134, s[100:101]
	s_mov_b32 m0, s53
	s_nop 0
	global_load_lds_dwordx4 v130, s[100:101]
	s_barrier
; #define PG8_STAGE(bufoff, gbase, voff) do { _Pragma("unroll") for (int _i = 0; _i < 2; ++_i) \
;         __builtin_amdgcn_global_load_lds((const unsigned*)((const char*)(gbase) + (voff)[_i]), (LAS unsigned*)(lds + (bufoff) + ldsw + _i * 8192), 16, 0, 0); } while (0)
; #define PG8_MMA(ai, bj, At, Bt) do { __builtin_amdgcn_s_setprio(1); _Pragma("unroll") for (int m = 0; m < 4; ++m) _Pragma("unroll") for (int n = 0; n < 2; ++n) _Pragma("unroll") for (int k = 0; k < 2; ++k) \
;         acc[ai][bj][m][n] = __builtin_amdgcn_mfma_f32_16x16x32_bf16(Bt[n][k], At[m][k], acc[ai][bj][m][n], 0, 0, 0); __builtin_amdgcn_s_setprio(0); } while (0)
; #define PG8_WAIT_V(n) asm volatile("s_waitcnt vmcnt(" #n ")" ::: "memory")
; #define PG8_WAIT_L(n) asm volatile("s_waitcnt lgkmcnt(" #n ")" ::: "memory")
; #define PG8_BAR __builtin_amdgcn_s_barrier()
; #define PG8_SCHED __builtin_amdgcn_sched_barrier(0)
; template <class Epi>
; __device__ __forceinline__ void gemm_phase(LAS unsigned char* lds, const Gemm g, const StaticOrder& S, const Epi& E) {
;     ...
;             PG8_BAR; PG8_WAIT_L(0); PG8_MMA(1, 0, At, B0); PG8_BAR; PG8_SCHED;
;             PG8_STAGE(PG8_SB(1, 1), b3 + hstep, voffB);
;             PG8_WAIT_V(6); PG8_BAR; PG8_MMA(1, 1, At, B1); PG8_BAR;
	s_waitcnt lgkmcnt(0)
	v_mfma_f32_16x16x32_bf16 v[60:63], v[148:151], v[168:171], v[60:63]
	v_mfma_f32_16x16x32_bf16 v[56:59], v[160:163], v[168:171], v[56:59]
	v_mfma_f32_16x16x32_bf16 v[52:55], v[148:151], v[176:179], v[52:55]
	v_mfma_f32_16x16x32_bf16 v[44:47], v[160:163], v[176:179], v[44:47]
	v_mfma_f32_16x16x32_bf16 v[36:39], v[148:151], v[184:187], v[36:39]
	v_mfma_f32_16x16x32_bf16 v[28:31], v[160:163], v[184:187], v[28:31]
	v_mfma_f32_16x16x32_bf16 v[20:23], v[148:151], v[192:195], v[20:23]
	v_mfma_f32_16x16x32_bf16 v[12:15], v[160:163], v[192:195], v[12:15]
	v_mfma_f32_16x16x32_bf16 v[60:63], v[152:155], v[172:175], v[60:63]
	v_mfma_f32_16x16x32_bf16 v[56:59], v[164:167], v[172:175], v[56:59]
	v_mfma_f32_16x16x32_bf16 v[52:55], v[152:155], v[180:183], v[52:55]
	v_mfma_f32_16x16x32_bf16 v[44:47], v[164:167], v[180:183], v[44:47]
	v_mfma_f32_16x16x32_bf16 v[36:39], v[152:155], v[188:191], v[36:39]
	v_mfma_f32_16x16x32_bf16 v[28:31], v[164:167], v[188:191], v[28:31]
	v_mfma_f32_16x16x32_bf16 v[20:23], v[152:155], v[196:199], v[20:23]
	v_mfma_f32_16x16x32_bf16 v[12:15], v[164:167], v[196:199], v[12:15]
	s_barrier
	s_add_u32 s42, s46, 0x160080
	s_addc_u32 s43, s47, 0
	s_add_i32 s46, s48, s23
	s_mov_b32 m0, s46
	s_nop 0
	global_load_lds_dwordx4 v132, s[42:43]
	s_add_i32 m0, s46, 0x2000
	s_nop 0
	global_load_lds_dwordx4 v128, s[42:43]
	s_add_i32 s67, s67, 2
	s_add_u32 s65, s65, 0x100
	s_addc_u32 s66, s66, 0
	s_cmpk_gt_u32 s67, 0x55
	s_mov_b64 s[42:43], s[44:45]
	s_waitcnt vmcnt(6)
	s_barrier
	v_mfma_f32_16x16x32_bf16 v[48:51], v[200:203], v[168:171], v[48:51]
	v_mfma_f32_16x16x32_bf16 v[40:43], v[208:211], v[168:171], v[40:43]
	v_mfma_f32_16x16x32_bf16 v[32:35], v[200:203], v[176:179], v[32:35]
	v_mfma_f32_16x16x32_bf16 v[24:27], v[208:211], v[176:179], v[24:27]
	v_mfma_f32_16x16x32_bf16 v[16:19], v[200:203], v[184:187], v[16:19]
	v_mfma_f32_16x16x32_bf16 v[8:11], v[208:211], v[184:187], v[8:11]
	v_mfma_f32_16x16x32_bf16 v[4:7], v[200:203], v[192:195], v[4:7]
	v_mfma_f32_16x16x32_bf16 v[0:3], v[208:211], v[192:195], v[0:3]
	v_mfma_f32_16x16x32_bf16 v[48:51], v[204:207], v[172:175], v[48:51]
	v_mfma_f32_16x16x32_bf16 v[40:43], v[212:215], v[172:175], v[40:43]
	v_mfma_f32_16x16x32_bf16 v[32:35], v[204:207], v[180:183], v[32:35]
	v_mfma_f32_16x16x32_bf16 v[24:27], v[212:215], v[180:183], v[24:27]
	v_mfma_f32_16x16x32_bf16 v[16:19], v[204:207], v[188:191], v[16:19]
	v_mfma_f32_16x16x32_bf16 v[8:11], v[212:215], v[188:191], v[8:11]
	v_mfma_f32_16x16x32_bf16 v[4:7], v[204:207], v[196:199], v[4:7]
	v_mfma_f32_16x16x32_bf16 v[0:3], v[212:215], v[196:199], v[0:3]
	s_barrier
	s_cbranch_scc0 .LBB0_864
; __device__ __forceinline__ u32x4 pack8(f32x4 v0, f32x4 v1) { u32x4 w; w.x = cvt_pk_bf16(v0[0], v0[1]); w.y = cvt_pk_bf16(v0[2], v0[3]); w.z = cvt_pk_bf16(v1[0], v1[1]); w.w = cvt_pk_bf16(v1[2], v1[3]); return w; }
;     __device__ __forceinline__ void operator()(const f32x4 (&acc)[2][2][4][2], const Unit& u, int wr, int wc, int fr, int fq) const {
;         const int row0 = u.pm * BM + wr * 64 + fr, col0 = u.pn * BM + wc * 32 + 8 * fq;
; #pragma unroll
;         for (int ai = 0; ai < 2; ++ai)
; #pragma unroll
;             for (int m = 0; m < 4; ++m) { bf16_t* rowp = O + (size_t)(row0 + ai * HALF + m * 16) * ldc + col0;
; #pragma unroll
;                 for (int bj = 0; bj < 2; ++bj) *(u32x4*)(rowp + bj * HALF) = pack8(acc[ai][bj][m][0], acc[ai][bj][m][1]); }
;     }
	v_lshl_add_u32 v148, s63, 8, v142
	v_lshl_or_b32 v140, s64, 8, v144
	v_ashrrev_i32_e32 v149, 31, v148
	v_ashrrev_i32_e32 v141, 31, v140
	v_lshlrev_b64 v[150:151], 12, v[148:149]
	v_lshl_add_u64 v[150:151], s[24:25], 0, v[150:151]
	v_lshlrev_b64 v[152:153], 1, v[140:141]
	v_lshl_add_u64 v[140:141], v[150:151], 0, v[152:153]
	v_cvt_pk_bf16_f32 v124, v124, v125
	v_cvt_pk_bf16_f32 v125, v126, v127
	v_cvt_pk_bf16_f32 v126, v120, v121
	v_cvt_pk_bf16_f32 v127, v122, v123
	global_store_dwordx4 v[140:141], v[124:127], off
	v_cvt_pk_bf16_f32 v116, v116, v117
	v_cvt_pk_bf16_f32 v117, v118, v119
	v_cvt_pk_bf16_f32 v118, v108, v109
	v_or_b32_e32 v108, 16, v148
	v_ashrrev_i32_e32 v109, 31, v108
	v_lshlrev_b64 v[108:109], 12, v[108:109]
	v_lshl_add_u64 v[108:109], s[24:25], 0, v[108:109]
	v_cvt_pk_bf16_f32 v119, v110, v111
	global_store_dwordx4 v[140:141], v[116:119], off offset:256
	s_mov_b32 s64, s61
	s_mov_b32 s63, s62
	v_lshl_add_u64 v[116:117], v[108:109], 0, v[152:153]
	v_cvt_pk_bf16_f32 v108, v112, v113
	v_cvt_pk_bf16_f32 v109, v114, v115
	v_cvt_pk_bf16_f32 v110, v104, v105
	v_cvt_pk_bf16_f32 v111, v106, v107
	global_store_dwordx4 v[116:117], v[108:111], off
	v_cvt_pk_bf16_f32 v100, v100, v101
	v_cvt_pk_bf16_f32 v101, v102, v103
	v_cvt_pk_bf16_f32 v102, v92, v93
	v_or_b32_e32 v92, 32, v148
	v_ashrrev_i32_e32 v93, 31, v92
	v_lshlrev_b64 v[92:93], 12, v[92:93]
	v_lshl_add_u64 v[92:93], s[24:25], 0, v[92:93]
	v_cvt_pk_bf16_f32 v103, v94, v95
	global_store_dwordx4 v[116:117], v[100:103], off offset:256
	s_mov_b64 s[44:45], s[6:7]
	s_mov_b64 s[42:43], s[40:41]
	v_lshl_add_u64 v[100:101], v[92:93], 0, v[152:153]
	v_cvt_pk_bf16_f32 v92, v96, v97
	v_cvt_pk_bf16_f32 v93, v98, v99
	v_cvt_pk_bf16_f32 v94, v88, v89
	v_cvt_pk_bf16_f32 v95, v90, v91
	global_store_dwordx4 v[100:101], v[92:95], off
	v_cvt_pk_bf16_f32 v84, v84, v85
	v_cvt_pk_bf16_f32 v85, v86, v87
	v_cvt_pk_bf16_f32 v86, v76, v77
	v_or_b32_e32 v76, 48, v148
	v_ashrrev_i32_e32 v77, 31, v76
	v_lshlrev_b64 v[76:77], 12, v[76:77]
	v_lshl_add_u64 v[76:77], s[24:25], 0, v[76:77]
	v_cvt_pk_bf16_f32 v87, v78, v79
	global_store_dwordx4 v[100:101], v[84:87], off offset:256
	s_nop 1
	v_lshl_add_u64 v[84:85], v[76:77], 0, v[152:153]
	v_cvt_pk_bf16_f32 v76, v80, v81
	v_cvt_pk_bf16_f32 v77, v82, v83
	v_cvt_pk_bf16_f32 v78, v72, v73
	v_cvt_pk_bf16_f32 v79, v74, v75
	global_store_dwordx4 v[84:85], v[76:79], off
	v_cvt_pk_bf16_f32 v68, v68, v69
	v_cvt_pk_bf16_f32 v69, v70, v71
	v_cvt_pk_bf16_f32 v70, v64, v65
	v_cvt_pk_bf16_f32 v71, v66, v67
	global_store_dwordx4 v[84:85], v[68:71], off offset:256
	v_cvt_pk_bf16_f32 v60, v60, v61
	v_cvt_pk_bf16_f32 v61, v62, v63
	v_cvt_pk_bf16_f32 v62, v56, v57
	v_add_co_u32_e32 v56, vcc, s57, v140
	v_lshl_add_u64 v[64:65], v[140:141], 0, s[8:9]
	s_nop 0
	v_addc_co_u32_e32 v57, vcc, 0, v141, vcc
	v_cvt_pk_bf16_f32 v63, v58, v59
	global_store_dwordx4 v[56:57], v[60:63], off
	v_cvt_pk_bf16_f32 v48, v48, v49
	v_cvt_pk_bf16_f32 v49, v50, v51
	v_cvt_pk_bf16_f32 v50, v40, v41
	v_cvt_pk_bf16_f32 v51, v42, v43
	global_store_dwordx4 v[64:65], v[48:51], off offset:256
	v_cvt_pk_bf16_f32 v40, v52, v53
	v_cvt_pk_bf16_f32 v41, v54, v55
	v_cvt_pk_bf16_f32 v42, v44, v45
	v_add_co_u32_e32 v44, vcc, s58, v140
	s_nop 0
	v_lshl_add_u64 v[48:49], v[140:141], 0, s[30:31]
	v_addc_co_u32_e32 v45, vcc, 0, v141, vcc
	v_cvt_pk_bf16_f32 v43, v46, v47
	global_store_dwordx4 v[44:45], v[40:43], off
	v_cvt_pk_bf16_f32 v32, v32, v33
	v_cvt_pk_bf16_f32 v33, v34, v35
	v_cvt_pk_bf16_f32 v34, v24, v25
	v_cvt_pk_bf16_f32 v35, v26, v27
	global_store_dwordx4 v[48:49], v[32:35], off offset:256
	v_cvt_pk_bf16_f32 v24, v36, v37
	v_cvt_pk_bf16_f32 v25, v38, v39
	v_cvt_pk_bf16_f32 v26, v28, v29
	v_add_co_u32_e32 v28, vcc, s59, v140
	s_nop 0
	v_lshl_add_u64 v[32:33], v[140:141], 0, s[34:35]
	v_addc_co_u32_e32 v29, vcc, 0, v141, vcc
	v_cvt_pk_bf16_f32 v27, v30, v31
	global_store_dwordx4 v[28:29], v[24:27], off
	v_cvt_pk_bf16_f32 v16, v16, v17
	v_cvt_pk_bf16_f32 v17, v18, v19
	v_cvt_pk_bf16_f32 v18, v8, v9
	v_cvt_pk_bf16_f32 v19, v10, v11
	global_store_dwordx4 v[32:33], v[16:19], off offset:256
	v_cvt_pk_bf16_f32 v8, v20, v21
	v_cvt_pk_bf16_f32 v9, v22, v23
	v_cvt_pk_bf16_f32 v10, v12, v13
	v_add_co_u32_e32 v12, vcc, s60, v140
	s_nop 0
	v_lshl_add_u64 v[16:17], v[140:141], 0, s[36:37]
	v_addc_co_u32_e32 v13, vcc, 0, v141, vcc
	s_and_b64 vcc, exec, s[38:39]
	v_cvt_pk_bf16_f32 v11, v14, v15
	global_store_dwordx4 v[12:13], v[8:11], off
	v_cvt_pk_bf16_f32 v4, v4, v5
	v_cvt_pk_bf16_f32 v5, v6, v7
	v_cvt_pk_bf16_f32 v6, v0, v1
	v_cvt_pk_bf16_f32 v7, v2, v3
	global_store_dwordx4 v[16:17], v[4:7], off offset:256
	s_cbranch_vccz .LBB0_857
	s_waitcnt vmcnt(0)
	s_cmpk_gt_u32 s10, 0xff
	v_readlane_b32 s62, v232, 20
	v_readlane_b32 s61, v232, 21
	s_cbranch_scc1 .LBB0_868
	s_barrier

; #define PG8_STAGE(bufoff, gbase, voff) do { _Pragma("unroll") for (int _i = 0; _i < 2; ++_i) \
;         __builtin_amdgcn_global_load_lds((const unsigned*)((const char*)(gbase) + (voff)[_i]), (LAS unsigned*)(lds + (bufoff) + ldsw + _i * 8192), 16, 0, 0); } while (0)
; #define PG8_LDA(dst, b, h) do { _Pragma("unroll") for (int m = 0; m < 4; ++m) _Pragma("unroll") for (int k = 0; k < 2; ++k) dst[m][k] = *(const LAS bf16x8*)(lds + PG8_SA(b, h) + aoff + m * 2048 + k * 1024); } while (0)
; #define PG8_LDB(dst, b, h) do { _Pragma("unroll") for (int n = 0; n < 2; ++n) _Pragma("unroll") for (int k = 0; k < 2; ++k) dst[n][k] = *(const LAS bf16x8*)(lds + PG8_SB(b, h) + boff + n * 2048 + k * 1024); } while (0)
; #define PG8_MMA(ai, bj, At, Bt) do { __builtin_amdgcn_s_setprio(1); _Pragma("unroll") for (int m = 0; m < 4; ++m) _Pragma("unroll") for (int n = 0; n < 2; ++n) _Pragma("unroll") for (int k = 0; k < 2; ++k) \
;         acc[ai][bj][m][n] = __builtin_amdgcn_mfma_f32_16x16x32_bf16(Bt[n][k], At[m][k], acc[ai][bj][m][n], 0, 0, 0); __builtin_amdgcn_s_setprio(0); } while (0)
; #define PG8_WAIT_V(n) asm volatile("s_waitcnt vmcnt(" #n ")" ::: "memory")
; #define PG8_WAIT_L(n) asm volatile("s_waitcnt lgkmcnt(" #n ")" ::: "memory")
; #define PG8_BAR __builtin_amdgcn_s_barrier()
; #define PG8_SCHED __builtin_amdgcn_sched_barrier(0)
; template <class Epi>
; __device__ __forceinline__ void gemm_phase(LAS unsigned char* lds, const Gemm g, const StaticOrder& S, const Epi& E) {
;     ...
;             PG8_LDB(B0, 0, 0); PG8_SCHED; PG8_LDA(At, 0, 0); PG8_STAGE(PG8_SA(1, 1), a1 + hstep, voffA);
;             PG8_WAIT_L(8); PG8_BAR; PG8_WAIT_L(0); PG8_MMA(0, 0, At, B0); PG8_BAR; PG8_SCHED;
;             PG8_LDB(B1, 0, 1); PG8_STAGE(PG8_SB(0, 0), b2, voffB);
;             PG8_BAR; PG8_WAIT_L(0); PG8_MMA(0, 1, At, B1); PG8_BAR;
;             PG8_LDA(At, 0, 1); PG8_STAGE(PG8_SA(0, 0), a2, voffA);
;             PG8_BAR; PG8_WAIT_L(0); PG8_MMA(1, 0, At, B0); PG8_BAR; PG8_SCHED;
;             PG8_STAGE(PG8_SB(0, 1), b2 + hstep, voffB);
;             PG8_WAIT_V(6); PG8_BAR; PG8_MMA(1, 1, At, B1); PG8_BAR;
.LBB0_999:
	ds_read_b128 v[140:143], v151
	ds_read_b128 v[144:147], v151 offset:1024
	ds_read_b128 v[154:157], v151 offset:2048
	ds_read_b128 v[160:163], v151 offset:3072
	s_add_u32 s48, s46, 0xfff80080
	s_addc_u32 s49, s47, -1
	s_cmp_eq_u32 s63, 28
	s_cselect_b32 s51, s37, s49
	s_cselect_b32 s50, s59, s48
	s_cselect_b32 s49, s35, s62
	s_cselect_b32 s48, s60, s61
	s_add_i32 m0, s28, 0xc000
	ds_read_b128 v[164:167], v152
	ds_read_b128 v[168:171], v152 offset:1024
	ds_read_b128 v[172:175], v152 offset:2048
	ds_read_b128 v[176:179], v152 offset:3072
	ds_read_b128 v[180:183], v152 offset:4096
	ds_read_b128 v[184:187], v152 offset:5120
	ds_read_b128 v[188:191], v152 offset:6144
	ds_read_b128 v[192:195], v152 offset:7168
	global_load_lds_dwordx4 v136, s[46:47]
	s_add_i32 m0, s28, 0xe000
	s_nop 0
	global_load_lds_dwordx4 v138, s[46:47]
	s_waitcnt lgkmcnt(8)
	s_barrier
	s_waitcnt lgkmcnt(0)
	v_mfma_f32_16x16x32_bf16 v[124:127], v[140:143], v[164:167], v[124:127]
	v_mfma_f32_16x16x32_bf16 v[120:123], v[154:157], v[164:167], v[120:123]
	v_mfma_f32_16x16x32_bf16 v[108:111], v[140:143], v[172:175], v[108:111]
	v_mfma_f32_16x16x32_bf16 v[104:107], v[154:157], v[172:175], v[104:107]
	v_mfma_f32_16x16x32_bf16 v[92:95], v[140:143], v[180:183], v[92:95]
	v_mfma_f32_16x16x32_bf16 v[88:91], v[154:157], v[180:183], v[88:91]
	v_mfma_f32_16x16x32_bf16 v[76:79], v[140:143], v[188:191], v[76:79]
	v_mfma_f32_16x16x32_bf16 v[72:75], v[154:157], v[188:191], v[72:75]
	v_mfma_f32_16x16x32_bf16 v[124:127], v[144:147], v[168:171], v[124:127]
	v_mfma_f32_16x16x32_bf16 v[120:123], v[160:163], v[168:171], v[120:123]
	v_mfma_f32_16x16x32_bf16 v[108:111], v[144:147], v[176:179], v[108:111]
	v_mfma_f32_16x16x32_bf16 v[104:107], v[160:163], v[176:179], v[104:107]
	v_mfma_f32_16x16x32_bf16 v[92:95], v[144:147], v[184:187], v[92:95]
	v_mfma_f32_16x16x32_bf16 v[88:91], v[160:163], v[184:187], v[88:91]
	v_mfma_f32_16x16x32_bf16 v[76:79], v[144:147], v[192:195], v[76:79]
	v_mfma_f32_16x16x32_bf16 v[72:75], v[160:163], v[192:195], v[72:75]
	s_barrier
	s_add_i32 s64, s56, s23
	s_add_u32 s98, s48, s4
	s_addc_u32 s99, s49, s5
	s_mov_b32 m0, s64
	ds_read_b128 v[196:199], v153
	ds_read_b128 v[200:203], v153 offset:1024
	ds_read_b128 v[204:207], v153 offset:2048
	ds_read_b128 v[208:211], v153 offset:3072
	global_load_lds_dwordx4 v132, s[48:49]
	s_add_i32 m0, s64, 0x2000
	s_nop 0
	global_load_lds_dwordx4 v128, s[48:49]
	s_barrier
	s_waitcnt lgkmcnt(0)
	v_mfma_f32_16x16x32_bf16 v[116:119], v[196:199], v[164:167], v[116:119]
	v_mfma_f32_16x16x32_bf16 v[112:115], v[204:207], v[164:167], v[112:115]
	v_mfma_f32_16x16x32_bf16 v[100:103], v[196:199], v[172:175], v[100:103]
	v_mfma_f32_16x16x32_bf16 v[96:99], v[204:207], v[172:175], v[96:99]
	v_mfma_f32_16x16x32_bf16 v[84:87], v[196:199], v[180:183], v[84:87]
	v_mfma_f32_16x16x32_bf16 v[80:83], v[204:207], v[180:183], v[80:83]
	v_mfma_f32_16x16x32_bf16 v[68:71], v[196:199], v[188:191], v[68:71]
	v_mfma_f32_16x16x32_bf16 v[64:67], v[204:207], v[188:191], v[64:67]
	v_mfma_f32_16x16x32_bf16 v[116:119], v[200:203], v[168:171], v[116:119]
	v_mfma_f32_16x16x32_bf16 v[112:115], v[208:211], v[168:171], v[112:115]
	v_mfma_f32_16x16x32_bf16 v[100:103], v[200:203], v[176:179], v[100:103]
	v_mfma_f32_16x16x32_bf16 v[96:99], v[208:211], v[176:179], v[96:99]
	v_mfma_f32_16x16x32_bf16 v[84:87], v[200:203], v[184:187], v[84:87]
	v_mfma_f32_16x16x32_bf16 v[80:83], v[208:211], v[184:187], v[80:83]
	v_mfma_f32_16x16x32_bf16 v[68:71], v[200:203], v[192:195], v[68:71]
	v_mfma_f32_16x16x32_bf16 v[64:67], v[208:211], v[192:195], v[64:67]
	s_mov_b32 m0, s28
	s_add_u32 s100, s50, s4
	s_addc_u32 s101, s51, s5
	s_barrier
	ds_read_b128 v[164:167], v152 offset:16384
	ds_read_b128 v[168:171], v152 offset:17408
	ds_read_b128 v[172:175], v152 offset:18432
	ds_read_b128 v[176:179], v152 offset:19456
	ds_read_b128 v[180:183], v152 offset:20480
	ds_read_b128 v[184:187], v152 offset:21504
	ds_read_b128 v[188:191], v152 offset:22528
	ds_read_b128 v[192:195], v152 offset:23552
	global_load_lds_dwordx4 v134, s[50:51]
	s_mov_b32 m0, s29
	s_nop 0
	global_load_lds_dwordx4 v130, s[50:51]
	s_barrier
	s_waitcnt lgkmcnt(0)
	v_mfma_f32_16x16x32_bf16 v[60:63], v[140:143], v[164:167], v[60:63]
	v_mfma_f32_16x16x32_bf16 v[56:59], v[154:157], v[164:167], v[56:59]
	v_mfma_f32_16x16x32_bf16 v[44:47], v[140:143], v[172:175], v[44:47]
	v_mfma_f32_16x16x32_bf16 v[40:43], v[154:157], v[172:175], v[40:43]
	v_mfma_f32_16x16x32_bf16 v[28:31], v[140:143], v[180:183], v[28:31]
	v_mfma_f32_16x16x32_bf16 v[24:27], v[154:157], v[180:183], v[24:27]
	v_mfma_f32_16x16x32_bf16 v[12:15], v[140:143], v[188:191], v[12:15]
	v_mfma_f32_16x16x32_bf16 v[8:11], v[154:157], v[188:191], v[8:11]
	v_mfma_f32_16x16x32_bf16 v[60:63], v[144:147], v[168:171], v[60:63]
	v_mfma_f32_16x16x32_bf16 v[56:59], v[160:163], v[168:171], v[56:59]
	v_mfma_f32_16x16x32_bf16 v[44:47], v[144:147], v[176:179], v[44:47]
	v_mfma_f32_16x16x32_bf16 v[40:43], v[160:163], v[176:179], v[40:43]
	v_mfma_f32_16x16x32_bf16 v[28:31], v[144:147], v[184:187], v[28:31]
	v_mfma_f32_16x16x32_bf16 v[24:27], v[160:163], v[184:187], v[24:27]
	v_mfma_f32_16x16x32_bf16 v[12:15], v[144:147], v[192:195], v[12:15]
	v_mfma_f32_16x16x32_bf16 v[8:11], v[160:163], v[192:195], v[8:11]
	s_barrier
	s_add_u32 s64, s48, 0x80000
	s_addc_u32 s65, s49, 0
	s_add_i32 s66, s57, s23
	s_mov_b32 m0, s66
	s_nop 0
	global_load_lds_dwordx4 v132, s[64:65]
	s_add_i32 m0, s66, 0x2000
	s_nop 0
	global_load_lds_dwordx4 v128, s[64:65]
	s_waitcnt vmcnt(6)
	s_barrier
; #define PG8_STAGE(bufoff, gbase, voff) do { _Pragma("unroll") for (int _i = 0; _i < 2; ++_i) \
;         __builtin_amdgcn_global_load_lds((const unsigned*)((const char*)(gbase) + (voff)[_i]), (LAS unsigned*)(lds + (bufoff) + ldsw + _i * 8192), 16, 0, 0); } while (0)
; #define PG8_LDA(dst, b, h) do { _Pragma("unroll") for (int m = 0; m < 4; ++m) _Pragma("unroll") for (int k = 0; k < 2; ++k) dst[m][k] = *(const LAS bf16x8*)(lds + PG8_SA(b, h) + aoff + m * 2048 + k * 1024); } while (0)
; #define PG8_LDB(dst, b, h) do { _Pragma("unroll") for (int n = 0; n < 2; ++n) _Pragma("unroll") for (int k = 0; k < 2; ++k) dst[n][k] = *(const LAS bf16x8*)(lds + PG8_SB(b, h) + boff + n * 2048 + k * 1024); } while (0)
; #define PG8_MMA(ai, bj, At, Bt) do { __builtin_amdgcn_s_setprio(1); _Pragma("unroll") for (int m = 0; m < 4; ++m) _Pragma("unroll") for (int n = 0; n < 2; ++n) _Pragma("unroll") for (int k = 0; k < 2; ++k) \
;         acc[ai][bj][m][n] = __builtin_amdgcn_mfma_f32_16x16x32_bf16(Bt[n][k], At[m][k], acc[ai][bj][m][n], 0, 0, 0); __builtin_amdgcn_s_setprio(0); } while (0)
; #define PG8_WAIT_V(n) asm volatile("s_waitcnt vmcnt(" #n ")" ::: "memory")
; #define PG8_WAIT_L(n) asm volatile("s_waitcnt lgkmcnt(" #n ")" ::: "memory")
; #define PG8_BAR __builtin_amdgcn_s_barrier()
; #define PG8_SCHED __builtin_amdgcn_sched_barrier(0)
; template <class Epi>
; __device__ __forceinline__ void gemm_phase(LAS unsigned char* lds, const Gemm g, const StaticOrder& S, const Epi& E) {
;     ...
;             PG8_WAIT_V(6); PG8_BAR; PG8_MMA(1, 1, At, B1); PG8_BAR;
;             PG8_LDB(B0, 1, 0); PG8_SCHED; PG8_LDA(At, 1, 0); PG8_STAGE(PG8_SA(0, 1), a2 + hstep, voffA);
;             PG8_WAIT_L(8); PG8_BAR; PG8_WAIT_L(0); PG8_MMA(0, 0, At, B0); PG8_BAR; PG8_SCHED;
;             PG8_LDB(B1, 1, 1); PG8_STAGE(PG8_SB(1, 0), b3, voffB);
;             PG8_BAR; PG8_WAIT_L(0); PG8_MMA(0, 1, At, B1); PG8_BAR;
;             PG8_LDA(At, 1, 1); PG8_STAGE(PG8_SA(1, 0), a3, voffA);
;             PG8_BAR; PG8_WAIT_L(0); PG8_MMA(1, 0, At, B0); PG8_BAR; PG8_SCHED;
	v_mfma_f32_16x16x32_bf16 v[52:55], v[196:199], v[164:167], v[52:55]
	v_mfma_f32_16x16x32_bf16 v[48:51], v[204:207], v[164:167], v[48:51]
	v_mfma_f32_16x16x32_bf16 v[36:39], v[196:199], v[172:175], v[36:39]
	v_mfma_f32_16x16x32_bf16 v[32:35], v[204:207], v[172:175], v[32:35]
	v_mfma_f32_16x16x32_bf16 v[20:23], v[196:199], v[180:183], v[20:23]
	v_mfma_f32_16x16x32_bf16 v[16:19], v[204:207], v[180:183], v[16:19]
	v_mfma_f32_16x16x32_bf16 v[4:7], v[196:199], v[188:191], v[4:7]
	v_mfma_f32_16x16x32_bf16 v[0:3], v[204:207], v[188:191], v[0:3]
	v_mfma_f32_16x16x32_bf16 v[52:55], v[200:203], v[168:171], v[52:55]
	v_mfma_f32_16x16x32_bf16 v[48:51], v[208:211], v[168:171], v[48:51]
	v_mfma_f32_16x16x32_bf16 v[36:39], v[200:203], v[176:179], v[36:39]
	v_mfma_f32_16x16x32_bf16 v[32:35], v[208:211], v[176:179], v[32:35]
	v_mfma_f32_16x16x32_bf16 v[20:23], v[200:203], v[184:187], v[20:23]
	v_mfma_f32_16x16x32_bf16 v[16:19], v[208:211], v[184:187], v[16:19]
	v_mfma_f32_16x16x32_bf16 v[4:7], v[200:203], v[192:195], v[4:7]
	v_mfma_f32_16x16x32_bf16 v[0:3], v[208:211], v[192:195], v[0:3]
	s_add_i32 s64, 0, 0x18000
	v_add_u32_e32 v160, s64, v149
	s_barrier
	ds_read_b128 v[140:143], v160
	ds_read_b128 v[144:147], v160 offset:1024
	ds_read_b128 v[154:157], v160 offset:2048
	ds_read_b128 v[160:163], v160 offset:3072
	s_add_u32 s50, s50, 0x80000
	s_addc_u32 s51, s51, 0
	s_mov_b32 m0, s33
	ds_read_b128 v[164:167], v152 offset:32768
	ds_read_b128 v[168:171], v152 offset:33792
	ds_read_b128 v[172:175], v152 offset:34816
	ds_read_b128 v[176:179], v152 offset:35840
	ds_read_b128 v[180:183], v152 offset:36864
	ds_read_b128 v[184:187], v152 offset:37888
	ds_read_b128 v[188:191], v152 offset:38912
	ds_read_b128 v[192:195], v152 offset:39936
	global_load_lds_dwordx4 v134, s[50:51]
	s_mov_b32 m0, s45
	s_nop 0
	global_load_lds_dwordx4 v130, s[50:51]
	s_waitcnt lgkmcnt(8)
	s_barrier
	s_waitcnt lgkmcnt(0)
	v_mfma_f32_16x16x32_bf16 v[124:127], v[140:143], v[164:167], v[124:127]
	v_mfma_f32_16x16x32_bf16 v[120:123], v[154:157], v[164:167], v[120:123]
	v_mfma_f32_16x16x32_bf16 v[108:111], v[140:143], v[172:175], v[108:111]
	v_mfma_f32_16x16x32_bf16 v[104:107], v[154:157], v[172:175], v[104:107]
	v_mfma_f32_16x16x32_bf16 v[92:95], v[140:143], v[180:183], v[92:95]
	v_mfma_f32_16x16x32_bf16 v[88:91], v[154:157], v[180:183], v[88:91]
	v_mfma_f32_16x16x32_bf16 v[76:79], v[140:143], v[188:191], v[76:79]
	v_mfma_f32_16x16x32_bf16 v[72:75], v[154:157], v[188:191], v[72:75]
	v_mfma_f32_16x16x32_bf16 v[124:127], v[144:147], v[168:171], v[124:127]
	v_mfma_f32_16x16x32_bf16 v[120:123], v[160:163], v[168:171], v[120:123]
	v_mfma_f32_16x16x32_bf16 v[108:111], v[144:147], v[176:179], v[108:111]
	v_mfma_f32_16x16x32_bf16 v[104:107], v[160:163], v[176:179], v[104:107]
	v_mfma_f32_16x16x32_bf16 v[92:95], v[144:147], v[184:187], v[92:95]
	v_mfma_f32_16x16x32_bf16 v[88:91], v[160:163], v[184:187], v[88:91]
	v_mfma_f32_16x16x32_bf16 v[76:79], v[144:147], v[192:195], v[76:79]
	v_mfma_f32_16x16x32_bf16 v[72:75], v[160:163], v[192:195], v[72:75]
	s_barrier
	s_add_i32 s50, 0, 0x1c000
	s_add_i32 s51, s64, s23
	v_add_u32_e32 v208, s50, v149
	s_mov_b32 m0, s51
	ds_read_b128 v[196:199], v208
	ds_read_b128 v[200:203], v208 offset:1024
	ds_read_b128 v[204:207], v208 offset:2048
	ds_read_b128 v[208:211], v208 offset:3072
	global_load_lds_dwordx4 v132, s[98:99]
	s_add_i32 m0, s51, 0x2000
	s_nop 0
	global_load_lds_dwordx4 v128, s[98:99]
	s_barrier
	s_waitcnt lgkmcnt(0)
	v_mfma_f32_16x16x32_bf16 v[116:119], v[196:199], v[164:167], v[116:119]
	v_mfma_f32_16x16x32_bf16 v[112:115], v[204:207], v[164:167], v[112:115]
	v_mfma_f32_16x16x32_bf16 v[100:103], v[196:199], v[172:175], v[100:103]
	v_mfma_f32_16x16x32_bf16 v[96:99], v[204:207], v[172:175], v[96:99]
	v_mfma_f32_16x16x32_bf16 v[84:87], v[196:199], v[180:183], v[84:87]
	v_mfma_f32_16x16x32_bf16 v[80:83], v[204:207], v[180:183], v[80:83]
	v_mfma_f32_16x16x32_bf16 v[68:71], v[196:199], v[188:191], v[68:71]
	v_mfma_f32_16x16x32_bf16 v[64:67], v[204:207], v[188:191], v[64:67]
	v_mfma_f32_16x16x32_bf16 v[116:119], v[200:203], v[168:171], v[116:119]
	v_mfma_f32_16x16x32_bf16 v[112:115], v[208:211], v[168:171], v[112:115]
	v_mfma_f32_16x16x32_bf16 v[100:103], v[200:203], v[176:179], v[100:103]
	v_mfma_f32_16x16x32_bf16 v[96:99], v[208:211], v[176:179], v[96:99]
	v_mfma_f32_16x16x32_bf16 v[84:87], v[200:203], v[184:187], v[84:87]
	v_mfma_f32_16x16x32_bf16 v[80:83], v[208:211], v[184:187], v[80:83]
	v_mfma_f32_16x16x32_bf16 v[68:71], v[200:203], v[192:195], v[68:71]
	v_mfma_f32_16x16x32_bf16 v[64:67], v[208:211], v[192:195], v[64:67]
	s_mov_b32 m0, s53
	s_barrier
	ds_read_b128 v[164:167], v152 offset:49152
	ds_read_b128 v[168:171], v152 offset:50176
	ds_read_b128 v[172:175], v152 offset:51200
	ds_read_b128 v[176:179], v152 offset:52224
	ds_read_b128 v[180:183], v152 offset:53248
	ds_read_b128 v[184:187], v152 offset:54272
	ds_read_b128 v[188:191], v152 offset:55296
	ds_read_b128 v[192:195], v152 offset:56320
	global_load_lds_dwordx4 v134, s[100:101]
	s_mov_b32 m0, s54
	s_nop 0
	global_load_lds_dwordx4 v130, s[100:101]
	s_barrier
; __device__ __forceinline__ float bf_lo(unsigned w) { return __uint_as_float(w << 16); }
; __device__ __forceinline__ float bf_hi(unsigned w) { return __uint_as_float(w & 0xffff0000u); }
; __device__ __forceinline__ float fast_rcp(float x) { return __builtin_amdgcn_rcpf(x); }
; __device__ __forceinline__ float fast_exp2(float x) { return __builtin_amdgcn_exp2f(x); }
; #define PG8_STAGE(bufoff, gbase, voff) do { _Pragma("unroll") for (int _i = 0; _i < 2; ++_i) \
;         __builtin_amdgcn_global_load_lds((const unsigned*)((const char*)(gbase) + (voff)[_i]), (LAS unsigned*)(lds + (bufoff) + ldsw + _i * 8192), 16, 0, 0); } while (0)
; #define PG8_WAIT_V(n) asm volatile("s_waitcnt vmcnt(" #n ")" ::: "memory")
; #define PG8_WAIT_L(n) asm volatile("s_waitcnt lgkmcnt(" #n ")" ::: "memory")
; #define PG8_BAR __builtin_amdgcn_s_barrier()
; #define PG8_SCHED __builtin_amdgcn_sched_barrier(0)
; template <class Epi>
; __device__ __forceinline__ void gemm_phase(LAS unsigned char* lds, const Gemm g, const StaticOrder& S, const Epi& E) {
;     ...
;             PG8_BAR; PG8_WAIT_L(0); PG8_MMA(1, 0, At, B0); PG8_BAR; PG8_SCHED;
;             PG8_STAGE(PG8_SB(1, 1), b3 + hstep, voffB);
;             PG8_WAIT_V(6); PG8_BAR; PG8_MMA(1, 1, At, B1); PG8_BAR;
;     __device__ __forceinline__ void operator()(const f32x4 (&acc)[2][2][4][2], const Unit& u, int wr, int wc, int fr, int fq) const {
;         const int row0 = u.pm * BM + wr * 64 + fr, col0 = u.pn * BM + wc * 32 + 8 * fq;
; #pragma unroll
;         for (int ai = 0; ai < 2; ++ai)
; #pragma unroll
;             for (int m = 0; m < 4; ++m) { const size_t ro = (size_t)(row0 + ai * HALF + m * 16) * DM + col0; const float nr = -LOG2E * rs[row0 + ai * HALF + m * 16];
; #pragma unroll
;                 for (int bj = 0; bj < 2; ++bj) {
;                     const u32x4 pw = *(const u32x4*)(PP + ro + bj * HALF);
;                     const float pv[8] = {bf_lo(pw.x), bf_hi(pw.x), bf_lo(pw.y), bf_hi(pw.y), bf_lo(pw.z), bf_hi(pw.z), bf_lo(pw.w), bf_hi(pw.w)};
;                     f32x4 t0, t1;
; #pragma unroll
;                     for (int j = 0; j < 4; ++j) {
;                         t0[j] = fast_rcp(1.0f + fast_exp2(acc[ai][bj][m][0][j] * nr)) * pv[j];
;                         t1[j] = fast_rcp(1.0f + fast_exp2(acc[ai][bj][m][1][j] * nr)) * pv[4 + j]; }
;                     *(u32x4*)(O + ro + bj * HALF) = pack8(t0, t1); } }
	s_waitcnt lgkmcnt(0)
	v_mfma_f32_16x16x32_bf16 v[60:63], v[140:143], v[164:167], v[60:63]
	v_mfma_f32_16x16x32_bf16 v[56:59], v[154:157], v[164:167], v[56:59]
	v_mfma_f32_16x16x32_bf16 v[44:47], v[140:143], v[172:175], v[44:47]
	v_mfma_f32_16x16x32_bf16 v[40:43], v[154:157], v[172:175], v[40:43]
	v_mfma_f32_16x16x32_bf16 v[28:31], v[140:143], v[180:183], v[28:31]
	v_mfma_f32_16x16x32_bf16 v[24:27], v[154:157], v[180:183], v[24:27]
	v_mfma_f32_16x16x32_bf16 v[12:15], v[140:143], v[188:191], v[12:15]
	v_mfma_f32_16x16x32_bf16 v[8:11], v[154:157], v[188:191], v[8:11]
	v_mfma_f32_16x16x32_bf16 v[60:63], v[144:147], v[168:171], v[60:63]
	v_mfma_f32_16x16x32_bf16 v[56:59], v[160:163], v[168:171], v[56:59]
	v_mfma_f32_16x16x32_bf16 v[44:47], v[144:147], v[176:179], v[44:47]
	v_mfma_f32_16x16x32_bf16 v[40:43], v[160:163], v[176:179], v[40:43]
	v_mfma_f32_16x16x32_bf16 v[28:31], v[144:147], v[184:187], v[28:31]
	v_mfma_f32_16x16x32_bf16 v[24:27], v[160:163], v[184:187], v[24:27]
	v_mfma_f32_16x16x32_bf16 v[12:15], v[144:147], v[192:195], v[12:15]
	v_mfma_f32_16x16x32_bf16 v[8:11], v[160:163], v[192:195], v[8:11]
	s_barrier
	s_add_u32 s48, s48, 0x80080
	s_addc_u32 s49, s49, 0
	s_add_i32 s50, s50, s23
	s_mov_b32 m0, s50
	s_nop 0
	global_load_lds_dwordx4 v132, s[48:49]
	s_add_i32 m0, s50, 0x2000
	s_nop 0
	global_load_lds_dwordx4 v128, s[48:49]
	s_add_i32 s63, s63, 2
	s_add_u32 s46, s46, 0x100
	s_addc_u32 s47, s47, 0
	s_add_u32 s61, s61, 0x100
	s_addc_u32 s62, s62, 0
	s_cmp_gt_u32 s63, 29
	s_waitcnt vmcnt(6)
	s_barrier
	v_mfma_f32_16x16x32_bf16 v[52:55], v[196:199], v[164:167], v[52:55]
	v_mfma_f32_16x16x32_bf16 v[48:51], v[204:207], v[164:167], v[48:51]
	v_mfma_f32_16x16x32_bf16 v[36:39], v[196:199], v[172:175], v[36:39]
	v_mfma_f32_16x16x32_bf16 v[32:35], v[204:207], v[172:175], v[32:35]
	v_mfma_f32_16x16x32_bf16 v[20:23], v[196:199], v[180:183], v[20:23]
	v_mfma_f32_16x16x32_bf16 v[16:19], v[204:207], v[180:183], v[16:19]
	v_mfma_f32_16x16x32_bf16 v[4:7], v[196:199], v[188:191], v[4:7]
	v_mfma_f32_16x16x32_bf16 v[0:3], v[204:207], v[188:191], v[0:3]
	v_mfma_f32_16x16x32_bf16 v[52:55], v[200:203], v[168:171], v[52:55]
	v_mfma_f32_16x16x32_bf16 v[48:51], v[208:211], v[168:171], v[48:51]
	v_mfma_f32_16x16x32_bf16 v[36:39], v[200:203], v[176:179], v[36:39]
	v_mfma_f32_16x16x32_bf16 v[32:35], v[208:211], v[176:179], v[32:35]
	v_mfma_f32_16x16x32_bf16 v[20:23], v[200:203], v[184:187], v[20:23]
	v_mfma_f32_16x16x32_bf16 v[16:19], v[208:211], v[184:187], v[16:19]
	v_mfma_f32_16x16x32_bf16 v[4:7], v[200:203], v[192:195], v[4:7]
	v_mfma_f32_16x16x32_bf16 v[0:3], v[208:211], v[192:195], v[0:3]
	s_barrier
	s_cbranch_scc0 .LBB0_999
	v_lshl_add_u32 v144, s44, 8, v148
	v_ashrrev_i32_e32 v145, 31, v144
	v_lshl_add_u64 v[140:141], v[144:145], 2, s[14:15]
	global_load_dword v164, v[140:141], off
	v_lshl_or_b32 v146, s58, 8, v150
	v_ashrrev_i32_e32 v147, 31, v146
	v_lshlrev_b64 v[142:143], 11, v[144:145]
	v_lshl_add_u64 v[142:143], v[142:143], 0, v[146:147]
	v_lshlrev_b64 v[142:143], 1, v[142:143]
	v_lshl_add_u64 v[160:161], s[20:21], 0, v[142:143]
	global_load_dwordx4 v[154:157], v[160:161], off
	global_load_dwordx4 v[220:223], v[160:161], off offset:256
	v_lshl_add_u64 v[162:163], s[24:25], 0, v[142:143]
	s_and_b64 vcc, exec, s[38:39]
	s_mov_b32 s58, s34
	s_mov_b32 s44, s36
	s_mov_b64 s[48:49], s[42:43]
	s_mov_b64 s[46:47], s[40:41]
	s_waitcnt vmcnt(0)
	v_mul_f32_e32 v145, 0xbfb8aa3b, v164
	v_mul_f32_e32 v124, v124, v145
	v_mul_f32_e32 v120, v120, v145
	v_mul_f32_e32 v125, v125, v145
	v_mul_f32_e32 v121, v121, v145
	v_mul_f32_e32 v126, v126, v145
	v_mul_f32_e32 v122, v122, v145
	v_mul_f32_e32 v127, v127, v145
	v_mul_f32_e32 v123, v123, v145
	v_exp_f32_e32 v124, v124
	v_exp_f32_e32 v120, v120
	v_exp_f32_e32 v125, v125
	v_exp_f32_e32 v121, v121
	v_exp_f32_e32 v126, v126
	v_exp_f32_e32 v122, v122
	v_exp_f32_e32 v127, v127
	v_exp_f32_e32 v123, v123
	v_add_f32_e32 v124, 1.0, v124
	v_add_f32_e32 v120, 1.0, v120
	v_add_f32_e32 v125, 1.0, v125
	v_add_f32_e32 v121, 1.0, v121
	v_add_f32_e32 v126, 1.0, v126
	v_add_f32_e32 v122, 1.0, v122
	v_add_f32_e32 v127, 1.0, v127
	v_add_f32_e32 v123, 1.0, v123
	v_rcp_f32_e32 v124, v124
	v_rcp_f32_e32 v120, v120
	v_rcp_f32_e32 v125, v125
	v_rcp_f32_e32 v121, v121
	v_rcp_f32_e32 v126, v126
	v_rcp_f32_e32 v122, v122
	v_rcp_f32_e32 v127, v127
	v_rcp_f32_e32 v123, v123
	v_lshlrev_b32_e32 v164, 16, v154
	v_and_b32_e32 v154, 0xffff0000, v154
	v_lshlrev_b32_e32 v165, 16, v155
	v_and_b32_e32 v155, 0xffff0000, v155
	v_lshlrev_b32_e32 v166, 16, v156
	v_and_b32_e32 v156, 0xffff0000, v156
	v_lshlrev_b32_e32 v167, 16, v157
	v_and_b32_e32 v157, 0xffff0000, v157
	v_mul_f32_e32 v124, v124, v164
	v_mul_f32_e32 v164, v120, v166
	v_mul_f32_e32 v120, v125, v154
	v_mul_f32_e32 v125, v121, v156
	v_mul_f32_e32 v121, v126, v165
	v_mul_f32_e32 v126, v122, v167
	v_mul_f32_e32 v122, v127, v155
	v_mul_f32_e32 v123, v123, v157
	v_cvt_pk_bf16_f32 v120, v124, v120
	v_cvt_pk_bf16_f32 v121, v121, v122
	v_cvt_pk_bf16_f32 v122, v164, v125
	v_cvt_pk_bf16_f32 v123, v126, v123
	global_store_dwordx4 v[162:163], v[120:123], off
	v_mul_f32_e32 v116, v116, v145
	v_mul_f32_e32 v112, v112, v145
	v_mul_f32_e32 v117, v117, v145
	v_mul_f32_e32 v113, v113, v145
	v_mul_f32_e32 v118, v118, v145
	v_mul_f32_e32 v114, v114, v145
	v_mul_f32_e32 v119, v119, v145
	v_mul_f32_e32 v115, v115, v145
	v_exp_f32_e32 v116, v116
	v_exp_f32_e32 v112, v112
	v_exp_f32_e32 v117, v117
	v_exp_f32_e32 v113, v113
	v_exp_f32_e32 v118, v118
	v_exp_f32_e32 v114, v114
	v_exp_f32_e32 v119, v119
	v_exp_f32_e32 v115, v115
	v_add_f32_e32 v116, 1.0, v116
	v_add_f32_e32 v112, 1.0, v112
	v_add_f32_e32 v117, 1.0, v117
; __device__ __forceinline__ float bf_lo(unsigned w) { return __uint_as_float(w << 16); }
; __device__ __forceinline__ float bf_hi(unsigned w) { return __uint_as_float(w & 0xffff0000u); }
; __device__ __forceinline__ float fast_rcp(float x) { return __builtin_amdgcn_rcpf(x); }
; __device__ __forceinline__ float fast_exp2(float x) { return __builtin_amdgcn_exp2f(x); }
; __device__ __forceinline__ u32x4 pack8(f32x4 v0, f32x4 v1) { u32x4 w; w.x = cvt_pk_bf16(v0[0], v0[1]); w.y = cvt_pk_bf16(v0[2], v0[3]); w.z = cvt_pk_bf16(v1[0], v1[1]); w.w = cvt_pk_bf16(v1[2], v1[3]); return w; }
;     __device__ __forceinline__ void operator()(const f32x4 (&acc)[2][2][4][2], const Unit& u, int wr, int wc, int fr, int fq) const {
;     ...
;             for (int m = 0; m < 4; ++m) { const size_t ro = (size_t)(row0 + ai * HALF + m * 16) * DM + col0; const float nr = -LOG2E * rs[row0 + ai * HALF + m * 16];
; #pragma unroll
;                 for (int bj = 0; bj < 2; ++bj) {
;                     const u32x4 pw = *(const u32x4*)(PP + ro + bj * HALF);
;                     const float pv[8] = {bf_lo(pw.x), bf_hi(pw.x), bf_lo(pw.y), bf_hi(pw.y), bf_lo(pw.z), bf_hi(pw.z), bf_lo(pw.w), bf_hi(pw.w)};
;                     f32x4 t0, t1;
; #pragma unroll
;                     for (int j = 0; j < 4; ++j) {
;                         t0[j] = fast_rcp(1.0f + fast_exp2(acc[ai][bj][m][0][j] * nr)) * pv[j];
;                         t1[j] = fast_rcp(1.0f + fast_exp2(acc[ai][bj][m][1][j] * nr)) * pv[4 + j]; }
;                     *(u32x4*)(O + ro + bj * HALF) = pack8(t0, t1); } }
	v_add_f32_e32 v113, 1.0, v113
	v_add_f32_e32 v118, 1.0, v118
	v_add_f32_e32 v114, 1.0, v114
	v_add_f32_e32 v119, 1.0, v119
	v_add_f32_e32 v115, 1.0, v115
	v_rcp_f32_e32 v116, v116
	v_rcp_f32_e32 v112, v112
	v_rcp_f32_e32 v117, v117
	v_rcp_f32_e32 v113, v113
	v_rcp_f32_e32 v118, v118
	v_rcp_f32_e32 v114, v114
	v_rcp_f32_e32 v119, v119
	v_rcp_f32_e32 v115, v115
	v_or_b32_e32 v124, 16, v144
	v_ashrrev_i32_e32 v125, 31, v124
	v_lshlrev_b64 v[124:125], 11, v[124:125]
	v_lshl_add_u64 v[124:125], v[124:125], 0, v[146:147]
	v_lshlrev_b64 v[124:125], 1, v[124:125]
	v_lshl_add_u64 v[126:127], s[20:21], 0, v[124:125]
	v_lshlrev_b32_e32 v145, 16, v220
	v_and_b32_e32 v120, 0xffff0000, v220
	v_lshlrev_b32_e32 v154, 16, v221
	v_and_b32_e32 v121, 0xffff0000, v221
	v_lshlrev_b32_e32 v155, 16, v222
	v_and_b32_e32 v122, 0xffff0000, v222
	v_lshlrev_b32_e32 v156, 16, v223
	v_and_b32_e32 v123, 0xffff0000, v223
	v_mul_f32_e32 v116, v116, v145
	v_mul_f32_e32 v145, v112, v155
	v_mul_f32_e32 v112, v117, v120
	v_mul_f32_e32 v117, v113, v122
	v_mul_f32_e32 v113, v118, v154
	v_mul_f32_e32 v118, v114, v156
	v_mul_f32_e32 v114, v119, v121
	v_mul_f32_e32 v115, v115, v123
	v_cvt_pk_bf16_f32 v112, v116, v112
	v_cvt_pk_bf16_f32 v113, v113, v114
	v_cvt_pk_bf16_f32 v114, v145, v117
	v_cvt_pk_bf16_f32 v115, v118, v115
	global_store_dwordx4 v[162:163], v[112:115], off offset:256
	global_load_dword v118, v[140:141], off offset:64
	s_nop 0
	global_load_dwordx4 v[112:115], v[126:127], off
	global_load_dwordx4 v[224:227], v[126:127], off offset:256
	v_lshl_add_u64 v[116:117], s[24:25], 0, v[124:125]
	s_waitcnt vmcnt(0)
	v_mul_f32_e32 v118, 0xbfb8aa3b, v118
	v_mul_f32_e32 v108, v108, v118
	v_mul_f32_e32 v104, v104, v118
	v_mul_f32_e32 v109, v109, v118
	v_mul_f32_e32 v105, v105, v118
	v_mul_f32_e32 v110, v110, v118
	v_mul_f32_e32 v106, v106, v118
	v_mul_f32_e32 v111, v111, v118
	v_mul_f32_e32 v107, v107, v118
	v_exp_f32_e32 v108, v108
	v_exp_f32_e32 v104, v104
	v_exp_f32_e32 v109, v109
	v_exp_f32_e32 v105, v105
	v_exp_f32_e32 v110, v110
	v_exp_f32_e32 v106, v106
	v_exp_f32_e32 v111, v111
	v_exp_f32_e32 v107, v107
	v_add_f32_e32 v108, 1.0, v108
	v_add_f32_e32 v104, 1.0, v104
	v_add_f32_e32 v109, 1.0, v109
	v_add_f32_e32 v105, 1.0, v105
	v_add_f32_e32 v110, 1.0, v110
	v_add_f32_e32 v106, 1.0, v106
	v_add_f32_e32 v111, 1.0, v111
	v_add_f32_e32 v107, 1.0, v107
	v_rcp_f32_e32 v108, v108
	v_rcp_f32_e32 v104, v104
	v_rcp_f32_e32 v109, v109
	v_rcp_f32_e32 v105, v105
	v_rcp_f32_e32 v110, v110
	v_rcp_f32_e32 v106, v106
	v_rcp_f32_e32 v111, v111
	v_rcp_f32_e32 v107, v107
	v_lshlrev_b32_e32 v119, 16, v112
	v_and_b32_e32 v112, 0xffff0000, v112
	v_lshlrev_b32_e32 v120, 16, v113
	v_and_b32_e32 v113, 0xffff0000, v113
	v_lshlrev_b32_e32 v121, 16, v114
	v_and_b32_e32 v114, 0xffff0000, v114
	v_lshlrev_b32_e32 v122, 16, v115
	v_and_b32_e32 v115, 0xffff0000, v115
	v_mul_f32_e32 v108, v108, v119
	v_mul_f32_e32 v119, v104, v121
	v_mul_f32_e32 v104, v109, v112
	v_mul_f32_e32 v109, v105, v114
	v_mul_f32_e32 v105, v110, v120
	v_mul_f32_e32 v110, v106, v122
	v_mul_f32_e32 v106, v111, v113
	v_mul_f32_e32 v107, v107, v115
	v_cvt_pk_bf16_f32 v104, v108, v104
	v_cvt_pk_bf16_f32 v105, v105, v106
	v_cvt_pk_bf16_f32 v106, v119, v109
	v_cvt_pk_bf16_f32 v107, v110, v107
	global_store_dwordx4 v[116:117], v[104:107], off
	v_mul_f32_e32 v100, v100, v118
	v_mul_f32_e32 v96, v96, v118
	v_mul_f32_e32 v101, v101, v118
	v_mul_f32_e32 v97, v97, v118
	v_mul_f32_e32 v102, v102, v118
	v_mul_f32_e32 v98, v98, v118
	v_mul_f32_e32 v103, v103, v118
	v_mul_f32_e32 v99, v99, v118
	v_exp_f32_e32 v100, v100
	v_exp_f32_e32 v96, v96
	v_exp_f32_e32 v101, v101
	v_exp_f32_e32 v97, v97
	v_exp_f32_e32 v102, v102
	v_exp_f32_e32 v98, v98
	v_exp_f32_e32 v103, v103
	v_exp_f32_e32 v99, v99
	v_add_f32_e32 v100, 1.0, v100
	v_add_f32_e32 v96, 1.0, v96
	v_add_f32_e32 v101, 1.0, v101
	v_add_f32_e32 v97, 1.0, v97
	v_add_f32_e32 v102, 1.0, v102
	v_add_f32_e32 v98, 1.0, v98
	v_add_f32_e32 v103, 1.0, v103
	v_add_f32_e32 v99, 1.0, v99
	v_rcp_f32_e32 v100, v100
	v_rcp_f32_e32 v96, v96
	v_rcp_f32_e32 v101, v101
	v_rcp_f32_e32 v97, v97
	v_rcp_f32_e32 v102, v102
	v_rcp_f32_e32 v98, v98
	v_rcp_f32_e32 v103, v103
	v_rcp_f32_e32 v99, v99
	v_or_b32_e32 v108, 32, v144
	v_ashrrev_i32_e32 v109, 31, v108
	v_lshlrev_b64 v[108:109], 11, v[108:109]
	v_lshl_add_u64 v[108:109], v[108:109], 0, v[146:147]
	v_lshlrev_b64 v[108:109], 1, v[108:109]
	v_lshl_add_u64 v[110:111], s[20:21], 0, v[108:109]
	v_lshlrev_b32_e32 v112, 16, v224
	v_and_b32_e32 v104, 0xffff0000, v224
	v_lshlrev_b32_e32 v113, 16, v225
	v_and_b32_e32 v105, 0xffff0000, v225
	v_lshlrev_b32_e32 v114, 16, v226
	v_and_b32_e32 v106, 0xffff0000, v226
	v_lshlrev_b32_e32 v115, 16, v227
	v_and_b32_e32 v107, 0xffff0000, v227
	v_mul_f32_e32 v100, v100, v112
	v_mul_f32_e32 v112, v96, v114
	v_mul_f32_e32 v96, v101, v104
	v_mul_f32_e32 v101, v97, v106
	v_mul_f32_e32 v97, v102, v113
	v_mul_f32_e32 v102, v98, v115
	v_mul_f32_e32 v98, v103, v105
	v_mul_f32_e32 v99, v99, v107
	v_cvt_pk_bf16_f32 v96, v100, v96
	v_cvt_pk_bf16_f32 v97, v97, v98
	v_cvt_pk_bf16_f32 v98, v112, v101
	v_cvt_pk_bf16_f32 v99, v102, v99
	global_store_dwordx4 v[116:117], v[96:99], off offset:256
	global_load_dword v102, v[140:141], off offset:128
	s_nop 0
	global_load_dwordx4 v[96:99], v[110:111], off
	global_load_dwordx4 v[220:223], v[110:111], off offset:256
	v_lshl_add_u64 v[100:101], s[24:25], 0, v[108:109]
	s_waitcnt vmcnt(0)
; __device__ __forceinline__ float bf_lo(unsigned w) { return __uint_as_float(w << 16); }
; __device__ __forceinline__ float bf_hi(unsigned w) { return __uint_as_float(w & 0xffff0000u); }
; __device__ __forceinline__ float fast_rcp(float x) { return __builtin_amdgcn_rcpf(x); }
; __device__ __forceinline__ float fast_exp2(float x) { return __builtin_amdgcn_exp2f(x); }
; __device__ __forceinline__ u32x4 pack8(f32x4 v0, f32x4 v1) { u32x4 w; w.x = cvt_pk_bf16(v0[0], v0[1]); w.y = cvt_pk_bf16(v0[2], v0[3]); w.z = cvt_pk_bf16(v1[0], v1[1]); w.w = cvt_pk_bf16(v1[2], v1[3]); return w; }
;     __device__ __forceinline__ void operator()(const f32x4 (&acc)[2][2][4][2], const Unit& u, int wr, int wc, int fr, int fq) const {
;     ...
;             for (int m = 0; m < 4; ++m) { const size_t ro = (size_t)(row0 + ai * HALF + m * 16) * DM + col0; const float nr = -LOG2E * rs[row0 + ai * HALF + m * 16];
; #pragma unroll
;                 for (int bj = 0; bj < 2; ++bj) {
;                     const u32x4 pw = *(const u32x4*)(PP + ro + bj * HALF);
;                     const float pv[8] = {bf_lo(pw.x), bf_hi(pw.x), bf_lo(pw.y), bf_hi(pw.y), bf_lo(pw.z), bf_hi(pw.z), bf_lo(pw.w), bf_hi(pw.w)};
;                     f32x4 t0, t1;
; #pragma unroll
;                     for (int j = 0; j < 4; ++j) {
;                         t0[j] = fast_rcp(1.0f + fast_exp2(acc[ai][bj][m][0][j] * nr)) * pv[j];
;                         t1[j] = fast_rcp(1.0f + fast_exp2(acc[ai][bj][m][1][j] * nr)) * pv[4 + j]; }
;                     *(u32x4*)(O + ro + bj * HALF) = pack8(t0, t1); } }
	v_mul_f32_e32 v102, 0xbfb8aa3b, v102
	v_mul_f32_e32 v92, v92, v102
	v_mul_f32_e32 v88, v88, v102
	v_mul_f32_e32 v93, v93, v102
	v_mul_f32_e32 v89, v89, v102
	v_mul_f32_e32 v94, v94, v102
	v_mul_f32_e32 v90, v90, v102
	v_mul_f32_e32 v95, v95, v102
	v_mul_f32_e32 v91, v91, v102
	v_exp_f32_e32 v92, v92
	v_exp_f32_e32 v88, v88
	v_exp_f32_e32 v93, v93
	v_exp_f32_e32 v89, v89
	v_exp_f32_e32 v94, v94
	v_exp_f32_e32 v90, v90
	v_exp_f32_e32 v95, v95
	v_exp_f32_e32 v91, v91
	v_add_f32_e32 v92, 1.0, v92
	v_add_f32_e32 v88, 1.0, v88
	v_add_f32_e32 v93, 1.0, v93
	v_add_f32_e32 v89, 1.0, v89
	v_add_f32_e32 v94, 1.0, v94
	v_add_f32_e32 v90, 1.0, v90
	v_add_f32_e32 v95, 1.0, v95
	v_add_f32_e32 v91, 1.0, v91
	v_rcp_f32_e32 v92, v92
	v_rcp_f32_e32 v88, v88
	v_rcp_f32_e32 v93, v93
	v_rcp_f32_e32 v89, v89
	v_rcp_f32_e32 v94, v94
	v_rcp_f32_e32 v90, v90
	v_rcp_f32_e32 v95, v95
	v_rcp_f32_e32 v91, v91
	v_lshlrev_b32_e32 v103, 16, v96
	v_and_b32_e32 v96, 0xffff0000, v96
	v_lshlrev_b32_e32 v104, 16, v97
	v_and_b32_e32 v97, 0xffff0000, v97
	v_lshlrev_b32_e32 v105, 16, v98
	v_and_b32_e32 v98, 0xffff0000, v98
	v_lshlrev_b32_e32 v106, 16, v99
	v_and_b32_e32 v99, 0xffff0000, v99
	v_mul_f32_e32 v92, v92, v103
	v_mul_f32_e32 v103, v88, v105
	v_mul_f32_e32 v88, v93, v96
	v_mul_f32_e32 v93, v89, v98
	v_mul_f32_e32 v89, v94, v104
	v_mul_f32_e32 v94, v90, v106
	v_mul_f32_e32 v90, v95, v97
	v_mul_f32_e32 v91, v91, v99
	v_cvt_pk_bf16_f32 v88, v92, v88
	v_cvt_pk_bf16_f32 v89, v89, v90
	v_cvt_pk_bf16_f32 v90, v103, v93
	v_cvt_pk_bf16_f32 v91, v94, v91
	global_store_dwordx4 v[100:101], v[88:91], off
	v_mul_f32_e32 v84, v84, v102
	v_mul_f32_e32 v80, v80, v102
	v_mul_f32_e32 v85, v85, v102
	v_mul_f32_e32 v81, v81, v102
	v_mul_f32_e32 v86, v86, v102
	v_mul_f32_e32 v82, v82, v102
	v_mul_f32_e32 v87, v87, v102
	v_mul_f32_e32 v83, v83, v102
	v_exp_f32_e32 v84, v84
	v_exp_f32_e32 v80, v80
	v_exp_f32_e32 v85, v85
	v_exp_f32_e32 v81, v81
	v_exp_f32_e32 v86, v86
	v_exp_f32_e32 v82, v82
	v_exp_f32_e32 v87, v87
	v_exp_f32_e32 v83, v83
	v_add_f32_e32 v84, 1.0, v84
	v_add_f32_e32 v80, 1.0, v80
	v_add_f32_e32 v85, 1.0, v85
	v_add_f32_e32 v81, 1.0, v81
	v_add_f32_e32 v86, 1.0, v86
	v_add_f32_e32 v82, 1.0, v82
	v_add_f32_e32 v87, 1.0, v87
	v_add_f32_e32 v83, 1.0, v83
	v_rcp_f32_e32 v84, v84
	v_rcp_f32_e32 v80, v80
	v_rcp_f32_e32 v85, v85
	v_rcp_f32_e32 v81, v81
	v_rcp_f32_e32 v86, v86
	v_rcp_f32_e32 v82, v82
	v_rcp_f32_e32 v87, v87
	v_rcp_f32_e32 v83, v83
	v_or_b32_e32 v92, 48, v144
	v_ashrrev_i32_e32 v93, 31, v92
	v_lshlrev_b64 v[92:93], 11, v[92:93]
	v_lshl_add_u64 v[92:93], v[92:93], 0, v[146:147]
	v_lshlrev_b64 v[92:93], 1, v[92:93]
	v_lshl_add_u64 v[94:95], s[20:21], 0, v[92:93]
	v_lshlrev_b32_e32 v96, 16, v220
	v_and_b32_e32 v88, 0xffff0000, v220
	v_lshlrev_b32_e32 v97, 16, v221
	v_and_b32_e32 v89, 0xffff0000, v221
	v_lshlrev_b32_e32 v98, 16, v222
	v_and_b32_e32 v90, 0xffff0000, v222
	v_lshlrev_b32_e32 v99, 16, v223
	v_and_b32_e32 v91, 0xffff0000, v223
	v_mul_f32_e32 v84, v84, v96
	v_mul_f32_e32 v96, v80, v98
	v_mul_f32_e32 v80, v85, v88
	v_mul_f32_e32 v85, v81, v90
	v_mul_f32_e32 v81, v86, v97
	v_mul_f32_e32 v86, v82, v99
	v_mul_f32_e32 v82, v87, v89
	v_mul_f32_e32 v83, v83, v91
	v_cvt_pk_bf16_f32 v80, v84, v80
	v_cvt_pk_bf16_f32 v81, v81, v82
	v_cvt_pk_bf16_f32 v82, v96, v85
	v_cvt_pk_bf16_f32 v83, v86, v83
	global_store_dwordx4 v[100:101], v[80:83], off offset:256
	global_load_dword v86, v[140:141], off offset:192
	s_nop 0
	global_load_dwordx4 v[80:83], v[94:95], off
	global_load_dwordx4 v[224:227], v[94:95], off offset:256
	v_lshl_add_u64 v[84:85], s[24:25], 0, v[92:93]
	s_waitcnt vmcnt(0)
	v_mul_f32_e32 v86, 0xbfb8aa3b, v86
	v_mul_f32_e32 v76, v76, v86
	v_mul_f32_e32 v72, v72, v86
	v_mul_f32_e32 v77, v77, v86
	v_mul_f32_e32 v73, v73, v86
	v_mul_f32_e32 v78, v78, v86
	v_mul_f32_e32 v74, v74, v86
	v_mul_f32_e32 v79, v79, v86
	v_mul_f32_e32 v75, v75, v86
	v_exp_f32_e32 v76, v76
	v_exp_f32_e32 v72, v72
	v_exp_f32_e32 v77, v77
	v_exp_f32_e32 v73, v73
	v_exp_f32_e32 v78, v78
	v_exp_f32_e32 v74, v74
	v_exp_f32_e32 v79, v79
	v_exp_f32_e32 v75, v75
	v_add_f32_e32 v76, 1.0, v76
	v_add_f32_e32 v72, 1.0, v72
	v_add_f32_e32 v77, 1.0, v77
	v_add_f32_e32 v73, 1.0, v73
	v_add_f32_e32 v78, 1.0, v78
	v_add_f32_e32 v74, 1.0, v74
	v_add_f32_e32 v79, 1.0, v79
	v_add_f32_e32 v75, 1.0, v75
	v_rcp_f32_e32 v76, v76
	v_rcp_f32_e32 v72, v72
	v_rcp_f32_e32 v77, v77
	v_rcp_f32_e32 v73, v73
	v_rcp_f32_e32 v78, v78
	v_rcp_f32_e32 v74, v74
	v_rcp_f32_e32 v79, v79
	v_rcp_f32_e32 v75, v75
	v_lshlrev_b32_e32 v87, 16, v80
	v_and_b32_e32 v80, 0xffff0000, v80
	v_lshlrev_b32_e32 v88, 16, v81
	v_and_b32_e32 v81, 0xffff0000, v81
	v_lshlrev_b32_e32 v89, 16, v82
	v_and_b32_e32 v82, 0xffff0000, v82
	v_lshlrev_b32_e32 v90, 16, v83
	v_and_b32_e32 v83, 0xffff0000, v83
	v_mul_f32_e32 v76, v76, v87
	v_mul_f32_e32 v87, v72, v89
	v_mul_f32_e32 v72, v77, v80
	v_mul_f32_e32 v77, v73, v82
	v_mul_f32_e32 v73, v78, v88
	v_mul_f32_e32 v78, v74, v90
	v_mul_f32_e32 v74, v79, v81
	v_mul_f32_e32 v75, v75, v83
	v_cvt_pk_bf16_f32 v72, v76, v72
	v_cvt_pk_bf16_f32 v73, v73, v74
	v_cvt_pk_bf16_f32 v74, v87, v77
	v_cvt_pk_bf16_f32 v75, v78, v75
	global_store_dwordx4 v[84:85], v[72:75], off
	v_mul_f32_e32 v68, v68, v86
	v_mul_f32_e32 v64, v64, v86
	v_mul_f32_e32 v69, v69, v86
	v_mul_f32_e32 v65, v65, v86
	v_mul_f32_e32 v70, v70, v86
	v_mul_f32_e32 v66, v66, v86
	v_mul_f32_e32 v71, v71, v86
	v_mul_f32_e32 v67, v67, v86
	v_exp_f32_e32 v68, v68
	v_exp_f32_e32 v64, v64
	v_exp_f32_e32 v69, v69
	v_exp_f32_e32 v65, v65
	v_exp_f32_e32 v70, v70
	v_exp_f32_e32 v66, v66
	v_exp_f32_e32 v71, v71
	v_exp_f32_e32 v67, v67
	v_add_f32_e32 v68, 1.0, v68
; __device__ __forceinline__ float bf_lo(unsigned w) { return __uint_as_float(w << 16); }
; __device__ __forceinline__ float bf_hi(unsigned w) { return __uint_as_float(w & 0xffff0000u); }
; __device__ __forceinline__ float fast_rcp(float x) { return __builtin_amdgcn_rcpf(x); }
; __device__ __forceinline__ float fast_exp2(float x) { return __builtin_amdgcn_exp2f(x); }
; __device__ __forceinline__ u32x4 pack8(f32x4 v0, f32x4 v1) { u32x4 w; w.x = cvt_pk_bf16(v0[0], v0[1]); w.y = cvt_pk_bf16(v0[2], v0[3]); w.z = cvt_pk_bf16(v1[0], v1[1]); w.w = cvt_pk_bf16(v1[2], v1[3]); return w; }
;     __device__ __forceinline__ void operator()(const f32x4 (&acc)[2][2][4][2], const Unit& u, int wr, int wc, int fr, int fq) const {
;     ...
;             for (int m = 0; m < 4; ++m) { const size_t ro = (size_t)(row0 + ai * HALF + m * 16) * DM + col0; const float nr = -LOG2E * rs[row0 + ai * HALF + m * 16];
; #pragma unroll
;                 for (int bj = 0; bj < 2; ++bj) {
;                     const u32x4 pw = *(const u32x4*)(PP + ro + bj * HALF);
;                     const float pv[8] = {bf_lo(pw.x), bf_hi(pw.x), bf_lo(pw.y), bf_hi(pw.y), bf_lo(pw.z), bf_hi(pw.z), bf_lo(pw.w), bf_hi(pw.w)};
;                     f32x4 t0, t1;
; #pragma unroll
;                     for (int j = 0; j < 4; ++j) {
;                         t0[j] = fast_rcp(1.0f + fast_exp2(acc[ai][bj][m][0][j] * nr)) * pv[j];
;                         t1[j] = fast_rcp(1.0f + fast_exp2(acc[ai][bj][m][1][j] * nr)) * pv[4 + j]; }
;                     *(u32x4*)(O + ro + bj * HALF) = pack8(t0, t1); } }
	v_add_f32_e32 v64, 1.0, v64
	v_add_f32_e32 v69, 1.0, v69
	v_add_f32_e32 v65, 1.0, v65
	v_add_f32_e32 v70, 1.0, v70
	v_add_f32_e32 v66, 1.0, v66
	v_add_f32_e32 v71, 1.0, v71
	v_add_f32_e32 v67, 1.0, v67
	v_rcp_f32_e32 v68, v68
	v_rcp_f32_e32 v64, v64
	v_rcp_f32_e32 v69, v69
	v_rcp_f32_e32 v65, v65
	v_rcp_f32_e32 v70, v70
	v_rcp_f32_e32 v66, v66
	v_rcp_f32_e32 v71, v71
	v_rcp_f32_e32 v67, v67
	v_lshl_add_u64 v[76:77], v[142:143], 0, s[2:3]
	v_lshl_add_u64 v[78:79], s[20:21], 0, v[76:77]
	v_lshlrev_b32_e32 v80, 16, v224
	v_and_b32_e32 v72, 0xffff0000, v224
	v_lshlrev_b32_e32 v81, 16, v225
	v_and_b32_e32 v73, 0xffff0000, v225
	v_lshlrev_b32_e32 v82, 16, v226
	v_and_b32_e32 v74, 0xffff0000, v226
	v_lshlrev_b32_e32 v83, 16, v227
	v_and_b32_e32 v75, 0xffff0000, v227
	v_mul_f32_e32 v68, v68, v80
	v_mul_f32_e32 v80, v64, v82
	v_mul_f32_e32 v64, v69, v72
	v_mul_f32_e32 v69, v65, v74
	v_mul_f32_e32 v65, v70, v81
	v_mul_f32_e32 v70, v66, v83
	v_mul_f32_e32 v66, v71, v73
	v_mul_f32_e32 v67, v67, v75
	v_cvt_pk_bf16_f32 v64, v68, v64
	v_cvt_pk_bf16_f32 v65, v65, v66
	v_cvt_pk_bf16_f32 v66, v80, v69
	v_cvt_pk_bf16_f32 v67, v70, v67
	global_store_dwordx4 v[84:85], v[64:67], off offset:256
	global_load_dword v70, v[140:141], off offset:512
	s_nop 0
	global_load_dwordx4 v[64:67], v[78:79], off
	global_load_dwordx4 v[220:223], v[78:79], off offset:256
	v_lshl_add_u64 v[68:69], s[24:25], 0, v[76:77]
	s_waitcnt vmcnt(0)
	v_mul_f32_e32 v70, 0xbfb8aa3b, v70
	v_mul_f32_e32 v60, v60, v70
	v_mul_f32_e32 v56, v56, v70
	v_mul_f32_e32 v61, v61, v70
	v_mul_f32_e32 v57, v57, v70
	v_mul_f32_e32 v62, v62, v70
	v_mul_f32_e32 v58, v58, v70
	v_mul_f32_e32 v63, v63, v70
	v_mul_f32_e32 v59, v59, v70
	v_exp_f32_e32 v60, v60
	v_exp_f32_e32 v56, v56
	v_exp_f32_e32 v61, v61
	v_exp_f32_e32 v57, v57
	v_exp_f32_e32 v62, v62
	v_exp_f32_e32 v58, v58
	v_exp_f32_e32 v63, v63
	v_exp_f32_e32 v59, v59
	v_add_f32_e32 v60, 1.0, v60
	v_add_f32_e32 v56, 1.0, v56
	v_add_f32_e32 v61, 1.0, v61
	v_add_f32_e32 v57, 1.0, v57
	v_add_f32_e32 v62, 1.0, v62
	v_add_f32_e32 v58, 1.0, v58
	v_add_f32_e32 v63, 1.0, v63
	v_add_f32_e32 v59, 1.0, v59
	v_rcp_f32_e32 v60, v60
	v_rcp_f32_e32 v56, v56
	v_rcp_f32_e32 v61, v61
	v_rcp_f32_e32 v57, v57
	v_rcp_f32_e32 v62, v62
	v_rcp_f32_e32 v58, v58
	v_rcp_f32_e32 v63, v63
	v_rcp_f32_e32 v59, v59
	v_lshlrev_b32_e32 v71, 16, v64
	v_and_b32_e32 v64, 0xffff0000, v64
	v_lshlrev_b32_e32 v72, 16, v65
	v_and_b32_e32 v65, 0xffff0000, v65
	v_lshlrev_b32_e32 v73, 16, v66
	v_and_b32_e32 v66, 0xffff0000, v66
	v_lshlrev_b32_e32 v74, 16, v67
	v_and_b32_e32 v67, 0xffff0000, v67
	v_mul_f32_e32 v60, v60, v71
	v_mul_f32_e32 v71, v56, v73
	v_mul_f32_e32 v56, v61, v64
	v_mul_f32_e32 v61, v57, v66
	v_mul_f32_e32 v57, v62, v72
	v_mul_f32_e32 v62, v58, v74
	v_mul_f32_e32 v58, v63, v65
	v_mul_f32_e32 v59, v59, v67
	v_cvt_pk_bf16_f32 v56, v60, v56
	v_cvt_pk_bf16_f32 v57, v57, v58
	v_cvt_pk_bf16_f32 v58, v71, v61
	v_cvt_pk_bf16_f32 v59, v62, v59
	global_store_dwordx4 v[68:69], v[56:59], off
	v_mul_f32_e32 v52, v52, v70
	v_mul_f32_e32 v48, v48, v70
	v_mul_f32_e32 v53, v53, v70
	v_mul_f32_e32 v49, v49, v70
	v_mul_f32_e32 v54, v54, v70
	v_mul_f32_e32 v50, v50, v70
	v_mul_f32_e32 v55, v55, v70
	v_mul_f32_e32 v51, v51, v70
	v_exp_f32_e32 v52, v52
	v_exp_f32_e32 v48, v48
	v_exp_f32_e32 v53, v53
	v_exp_f32_e32 v49, v49
	v_exp_f32_e32 v54, v54
	v_exp_f32_e32 v50, v50
	v_exp_f32_e32 v55, v55
	v_exp_f32_e32 v51, v51
	v_add_f32_e32 v52, 1.0, v52
	v_add_f32_e32 v48, 1.0, v48
	v_add_f32_e32 v53, 1.0, v53
	v_add_f32_e32 v49, 1.0, v49
	v_add_f32_e32 v54, 1.0, v54
	v_add_f32_e32 v50, 1.0, v50
	v_add_f32_e32 v55, 1.0, v55
	v_add_f32_e32 v51, 1.0, v51
	v_rcp_f32_e32 v52, v52
	v_rcp_f32_e32 v48, v48
	v_rcp_f32_e32 v53, v53
	v_rcp_f32_e32 v49, v49
	v_rcp_f32_e32 v54, v54
	v_rcp_f32_e32 v50, v50
	v_rcp_f32_e32 v55, v55
	v_rcp_f32_e32 v51, v51
	v_lshl_add_u64 v[60:61], v[142:143], 0, s[6:7]
	v_lshl_add_u64 v[62:63], s[20:21], 0, v[60:61]
	v_lshlrev_b32_e32 v64, 16, v220
	v_and_b32_e32 v56, 0xffff0000, v220
	v_lshlrev_b32_e32 v65, 16, v221
	v_and_b32_e32 v57, 0xffff0000, v221
	v_lshlrev_b32_e32 v66, 16, v222
	v_and_b32_e32 v58, 0xffff0000, v222
	v_lshlrev_b32_e32 v67, 16, v223
	v_and_b32_e32 v59, 0xffff0000, v223
	v_mul_f32_e32 v52, v52, v64
	v_mul_f32_e32 v64, v48, v66
	v_mul_f32_e32 v48, v53, v56
	v_mul_f32_e32 v53, v49, v58
	v_mul_f32_e32 v49, v54, v65
	v_mul_f32_e32 v54, v50, v67
	v_mul_f32_e32 v50, v55, v57
	v_mul_f32_e32 v51, v51, v59
	v_cvt_pk_bf16_f32 v48, v52, v48
	v_cvt_pk_bf16_f32 v49, v49, v50
	v_cvt_pk_bf16_f32 v50, v64, v53
	v_cvt_pk_bf16_f32 v51, v54, v51
	global_store_dwordx4 v[68:69], v[48:51], off offset:256
	global_load_dword v54, v[140:141], off offset:576
	s_nop 0
	global_load_dwordx4 v[48:51], v[62:63], off
	global_load_dwordx4 v[224:227], v[62:63], off offset:256
	v_lshl_add_u64 v[52:53], s[24:25], 0, v[60:61]
	s_waitcnt vmcnt(0)
; __device__ __forceinline__ float bf_lo(unsigned w) { return __uint_as_float(w << 16); }
; __device__ __forceinline__ float bf_hi(unsigned w) { return __uint_as_float(w & 0xffff0000u); }
; __device__ __forceinline__ float fast_rcp(float x) { return __builtin_amdgcn_rcpf(x); }
; __device__ __forceinline__ float fast_exp2(float x) { return __builtin_amdgcn_exp2f(x); }
; __device__ __forceinline__ u32x4 pack8(f32x4 v0, f32x4 v1) { u32x4 w; w.x = cvt_pk_bf16(v0[0], v0[1]); w.y = cvt_pk_bf16(v0[2], v0[3]); w.z = cvt_pk_bf16(v1[0], v1[1]); w.w = cvt_pk_bf16(v1[2], v1[3]); return w; }
;     __device__ __forceinline__ void operator()(const f32x4 (&acc)[2][2][4][2], const Unit& u, int wr, int wc, int fr, int fq) const {
;     ...
;             for (int m = 0; m < 4; ++m) { const size_t ro = (size_t)(row0 + ai * HALF + m * 16) * DM + col0; const float nr = -LOG2E * rs[row0 + ai * HALF + m * 16];
; #pragma unroll
;                 for (int bj = 0; bj < 2; ++bj) {
;                     const u32x4 pw = *(const u32x4*)(PP + ro + bj * HALF);
;                     const float pv[8] = {bf_lo(pw.x), bf_hi(pw.x), bf_lo(pw.y), bf_hi(pw.y), bf_lo(pw.z), bf_hi(pw.z), bf_lo(pw.w), bf_hi(pw.w)};
;                     f32x4 t0, t1;
; #pragma unroll
;                     for (int j = 0; j < 4; ++j) {
;                         t0[j] = fast_rcp(1.0f + fast_exp2(acc[ai][bj][m][0][j] * nr)) * pv[j];
;                         t1[j] = fast_rcp(1.0f + fast_exp2(acc[ai][bj][m][1][j] * nr)) * pv[4 + j]; }
;                     *(u32x4*)(O + ro + bj * HALF) = pack8(t0, t1); } }
	v_mul_f32_e32 v54, 0xbfb8aa3b, v54
	v_mul_f32_e32 v44, v44, v54
	v_mul_f32_e32 v40, v40, v54
	v_mul_f32_e32 v45, v45, v54
	v_mul_f32_e32 v41, v41, v54
	v_mul_f32_e32 v46, v46, v54
	v_mul_f32_e32 v42, v42, v54
	v_mul_f32_e32 v47, v47, v54
	v_mul_f32_e32 v43, v43, v54
	v_exp_f32_e32 v44, v44
	v_exp_f32_e32 v40, v40
	v_exp_f32_e32 v45, v45
	v_exp_f32_e32 v41, v41
	v_exp_f32_e32 v46, v46
	v_exp_f32_e32 v42, v42
	v_exp_f32_e32 v47, v47
	v_exp_f32_e32 v43, v43
	v_add_f32_e32 v44, 1.0, v44
	v_add_f32_e32 v40, 1.0, v40
	v_add_f32_e32 v45, 1.0, v45
	v_add_f32_e32 v41, 1.0, v41
	v_add_f32_e32 v46, 1.0, v46
	v_add_f32_e32 v42, 1.0, v42
	v_add_f32_e32 v47, 1.0, v47
	v_add_f32_e32 v43, 1.0, v43
	v_rcp_f32_e32 v44, v44
	v_rcp_f32_e32 v40, v40
	v_rcp_f32_e32 v45, v45
	v_rcp_f32_e32 v41, v41
	v_rcp_f32_e32 v46, v46
	v_rcp_f32_e32 v42, v42
	v_rcp_f32_e32 v47, v47
	v_rcp_f32_e32 v43, v43
	v_lshlrev_b32_e32 v55, 16, v48
	v_and_b32_e32 v48, 0xffff0000, v48
	v_lshlrev_b32_e32 v56, 16, v49
	v_and_b32_e32 v49, 0xffff0000, v49
	v_lshlrev_b32_e32 v57, 16, v50
	v_and_b32_e32 v50, 0xffff0000, v50
	v_lshlrev_b32_e32 v58, 16, v51
	v_and_b32_e32 v51, 0xffff0000, v51
	v_mul_f32_e32 v44, v44, v55
	v_mul_f32_e32 v55, v40, v57
	v_mul_f32_e32 v40, v45, v48
	v_mul_f32_e32 v45, v41, v50
	v_mul_f32_e32 v41, v46, v56
	v_mul_f32_e32 v46, v42, v58
	v_mul_f32_e32 v42, v47, v49
	v_mul_f32_e32 v43, v43, v51
	v_cvt_pk_bf16_f32 v40, v44, v40
	v_cvt_pk_bf16_f32 v41, v41, v42
	v_cvt_pk_bf16_f32 v42, v55, v45
	v_cvt_pk_bf16_f32 v43, v46, v43
	global_store_dwordx4 v[52:53], v[40:43], off
	v_mul_f32_e32 v36, v36, v54
	v_mul_f32_e32 v32, v32, v54
	v_mul_f32_e32 v37, v37, v54
	v_mul_f32_e32 v33, v33, v54
	v_mul_f32_e32 v38, v38, v54
	v_mul_f32_e32 v34, v34, v54
	v_mul_f32_e32 v39, v39, v54
	v_mul_f32_e32 v35, v35, v54
	v_exp_f32_e32 v36, v36
	v_exp_f32_e32 v32, v32
	v_exp_f32_e32 v37, v37
	v_exp_f32_e32 v33, v33
	v_exp_f32_e32 v38, v38
	v_exp_f32_e32 v34, v34
	v_exp_f32_e32 v39, v39
	v_exp_f32_e32 v35, v35
	v_add_f32_e32 v36, 1.0, v36
	v_add_f32_e32 v32, 1.0, v32
	v_add_f32_e32 v37, 1.0, v37
	v_add_f32_e32 v33, 1.0, v33
	v_add_f32_e32 v38, 1.0, v38
	v_add_f32_e32 v34, 1.0, v34
	v_add_f32_e32 v39, 1.0, v39
	v_add_f32_e32 v35, 1.0, v35
	v_rcp_f32_e32 v36, v36
	v_rcp_f32_e32 v32, v32
	v_rcp_f32_e32 v37, v37
	v_rcp_f32_e32 v33, v33
	v_rcp_f32_e32 v38, v38
	v_rcp_f32_e32 v34, v34
	v_rcp_f32_e32 v39, v39
	v_rcp_f32_e32 v35, v35
	v_lshl_add_u64 v[44:45], v[142:143], 0, s[8:9]
	v_lshl_add_u64 v[46:47], s[20:21], 0, v[44:45]
	v_lshlrev_b32_e32 v48, 16, v224
	v_and_b32_e32 v40, 0xffff0000, v224
	v_lshlrev_b32_e32 v49, 16, v225
	v_and_b32_e32 v41, 0xffff0000, v225
	v_lshlrev_b32_e32 v50, 16, v226
	v_and_b32_e32 v42, 0xffff0000, v226
	v_lshlrev_b32_e32 v51, 16, v227
	v_and_b32_e32 v43, 0xffff0000, v227
	v_mul_f32_e32 v36, v36, v48
	v_mul_f32_e32 v48, v32, v50
	v_mul_f32_e32 v32, v37, v40
	v_mul_f32_e32 v37, v33, v42
	v_mul_f32_e32 v33, v38, v49
	v_mul_f32_e32 v38, v34, v51
	v_mul_f32_e32 v34, v39, v41
	v_mul_f32_e32 v35, v35, v43
	v_cvt_pk_bf16_f32 v32, v36, v32
	v_cvt_pk_bf16_f32 v33, v33, v34
	v_cvt_pk_bf16_f32 v34, v48, v37
	v_cvt_pk_bf16_f32 v35, v38, v35
	global_store_dwordx4 v[52:53], v[32:35], off offset:256
	global_load_dword v38, v[140:141], off offset:640
	s_nop 0
	global_load_dwordx4 v[32:35], v[46:47], off
	global_load_dwordx4 v[220:223], v[46:47], off offset:256
	v_lshl_add_u64 v[36:37], s[24:25], 0, v[44:45]
	s_waitcnt vmcnt(0)
; __device__ __forceinline__ float bf_lo(unsigned w) { return __uint_as_float(w << 16); }
; __device__ __forceinline__ float bf_hi(unsigned w) { return __uint_as_float(w & 0xffff0000u); }
; __device__ __forceinline__ float fast_rcp(float x) { return __builtin_amdgcn_rcpf(x); }
; __device__ __forceinline__ float fast_exp2(float x) { return __builtin_amdgcn_exp2f(x); }
; #define PG8_WAIT_V(n) asm volatile("s_waitcnt vmcnt(" #n ")" ::: "memory")
; #define PG8_BAR __builtin_amdgcn_s_barrier()
; __device__ __forceinline__ u32x4 pack8(f32x4 v0, f32x4 v1) { u32x4 w; w.x = cvt_pk_bf16(v0[0], v0[1]); w.y = cvt_pk_bf16(v0[2], v0[3]); w.z = cvt_pk_bf16(v1[0], v1[1]); w.w = cvt_pk_bf16(v1[2], v1[3]); return w; }
; template <class Epi>
; __device__ __forceinline__ void gemm_phase(LAS unsigned char* lds, const Gemm g, const StaticOrder& S, const Epi& E) {
;     ...
;         if (!has_next) break;
; #pragma unroll
;         for (int a = 0; a < 2; ++a)
; #pragma unroll
;             for (int b = 0; b < 2; ++b)
; #pragma unroll
;                 for (int m = 0; m < 4; ++m)
; #pragma unroll
;                     for (int n = 0; n < 2; ++n) acc[a][b][m][n] = (f32x4){0.f, 0.f, 0.f, 0.f};
;         cur = nxt; cA = nA; cB = nB; ++ui;
;     }
;     PG8_WAIT_V(0);
;     if (wr == 0) PG8_BAR;
;     PG8_BAR;
;     __device__ __forceinline__ void operator()(const f32x4 (&acc)[2][2][4][2], const Unit& u, int wr, int wc, int fr, int fq) const {
;     ...
;             for (int m = 0; m < 4; ++m) { const size_t ro = (size_t)(row0 + ai * HALF + m * 16) * DM + col0; const float nr = -LOG2E * rs[row0 + ai * HALF + m * 16];
; #pragma unroll
;                 for (int bj = 0; bj < 2; ++bj) {
;                     const u32x4 pw = *(const u32x4*)(PP + ro + bj * HALF);
;                     const float pv[8] = {bf_lo(pw.x), bf_hi(pw.x), bf_lo(pw.y), bf_hi(pw.y), bf_lo(pw.z), bf_hi(pw.z), bf_lo(pw.w), bf_hi(pw.w)};
;                     f32x4 t0, t1;
; #pragma unroll
;                     for (int j = 0; j < 4; ++j) {
;                         t0[j] = fast_rcp(1.0f + fast_exp2(acc[ai][bj][m][0][j] * nr)) * pv[j];
;                         t1[j] = fast_rcp(1.0f + fast_exp2(acc[ai][bj][m][1][j] * nr)) * pv[4 + j]; }
;                     *(u32x4*)(O + ro + bj * HALF) = pack8(t0, t1); } }
	v_mul_f32_e32 v38, 0xbfb8aa3b, v38
	v_mul_f32_e32 v28, v28, v38
	v_mul_f32_e32 v24, v24, v38
	v_mul_f32_e32 v29, v29, v38
	v_mul_f32_e32 v25, v25, v38
	v_mul_f32_e32 v30, v30, v38
	v_mul_f32_e32 v26, v26, v38
	v_mul_f32_e32 v31, v31, v38
	v_mul_f32_e32 v27, v27, v38
	v_exp_f32_e32 v28, v28
	v_exp_f32_e32 v24, v24
	v_exp_f32_e32 v29, v29
	v_exp_f32_e32 v25, v25
	v_exp_f32_e32 v30, v30
	v_exp_f32_e32 v26, v26
	v_exp_f32_e32 v31, v31
	v_exp_f32_e32 v27, v27
	v_add_f32_e32 v28, 1.0, v28
	v_add_f32_e32 v24, 1.0, v24
	v_add_f32_e32 v29, 1.0, v29
	v_add_f32_e32 v25, 1.0, v25
	v_add_f32_e32 v30, 1.0, v30
	v_add_f32_e32 v26, 1.0, v26
	v_add_f32_e32 v31, 1.0, v31
	v_add_f32_e32 v27, 1.0, v27
	v_rcp_f32_e32 v28, v28
	v_rcp_f32_e32 v24, v24
	v_rcp_f32_e32 v29, v29
	v_rcp_f32_e32 v25, v25
	v_rcp_f32_e32 v30, v30
	v_rcp_f32_e32 v26, v26
	v_rcp_f32_e32 v31, v31
	v_rcp_f32_e32 v27, v27
	v_lshlrev_b32_e32 v39, 16, v32
	v_and_b32_e32 v32, 0xffff0000, v32
	v_lshlrev_b32_e32 v40, 16, v33
	v_and_b32_e32 v33, 0xffff0000, v33
	v_lshlrev_b32_e32 v41, 16, v34
	v_and_b32_e32 v34, 0xffff0000, v34
	v_lshlrev_b32_e32 v42, 16, v35
	v_and_b32_e32 v35, 0xffff0000, v35
	v_mul_f32_e32 v28, v28, v39
	v_mul_f32_e32 v39, v24, v41
	v_mul_f32_e32 v24, v29, v32
	v_mul_f32_e32 v29, v25, v34
	v_mul_f32_e32 v25, v30, v40
	v_mul_f32_e32 v30, v26, v42
	v_mul_f32_e32 v26, v31, v33
	v_mul_f32_e32 v27, v27, v35
	v_cvt_pk_bf16_f32 v24, v28, v24
	v_cvt_pk_bf16_f32 v25, v25, v26
	v_cvt_pk_bf16_f32 v26, v39, v29
	v_cvt_pk_bf16_f32 v27, v30, v27
	global_store_dwordx4 v[36:37], v[24:27], off
	v_mul_f32_e32 v20, v20, v38
	v_mul_f32_e32 v16, v16, v38
	v_mul_f32_e32 v21, v21, v38
	v_mul_f32_e32 v17, v17, v38
	v_mul_f32_e32 v22, v22, v38
	v_mul_f32_e32 v18, v18, v38
	v_mul_f32_e32 v23, v23, v38
	v_mul_f32_e32 v19, v19, v38
	v_exp_f32_e32 v20, v20
	v_exp_f32_e32 v16, v16
	v_exp_f32_e32 v21, v21
	v_exp_f32_e32 v17, v17
	v_exp_f32_e32 v22, v22
	v_exp_f32_e32 v18, v18
	v_exp_f32_e32 v23, v23
	v_exp_f32_e32 v19, v19
	v_add_f32_e32 v20, 1.0, v20
	v_add_f32_e32 v16, 1.0, v16
	v_add_f32_e32 v21, 1.0, v21
	v_add_f32_e32 v17, 1.0, v17
	v_add_f32_e32 v22, 1.0, v22
	v_add_f32_e32 v18, 1.0, v18
	v_add_f32_e32 v23, 1.0, v23
	v_add_f32_e32 v19, 1.0, v19
	v_rcp_f32_e32 v20, v20
	v_rcp_f32_e32 v16, v16
	v_rcp_f32_e32 v21, v21
	v_rcp_f32_e32 v17, v17
	v_rcp_f32_e32 v22, v22
	v_rcp_f32_e32 v18, v18
	v_rcp_f32_e32 v23, v23
	v_rcp_f32_e32 v19, v19
	v_lshl_add_u64 v[28:29], v[142:143], 0, s[30:31]
	v_lshl_add_u64 v[30:31], s[20:21], 0, v[28:29]
	v_lshlrev_b32_e32 v32, 16, v220
	v_and_b32_e32 v24, 0xffff0000, v220
	v_lshlrev_b32_e32 v33, 16, v221
	v_and_b32_e32 v25, 0xffff0000, v221
	v_lshlrev_b32_e32 v34, 16, v222
	v_and_b32_e32 v26, 0xffff0000, v222
	v_lshlrev_b32_e32 v35, 16, v223
	v_and_b32_e32 v27, 0xffff0000, v223
	v_mul_f32_e32 v20, v20, v32
	v_mul_f32_e32 v32, v16, v34
	v_mul_f32_e32 v16, v21, v24
	v_mul_f32_e32 v21, v17, v26
	v_mul_f32_e32 v17, v22, v33
	v_mul_f32_e32 v22, v18, v35
	v_mul_f32_e32 v18, v23, v25
	v_mul_f32_e32 v19, v19, v27
	v_cvt_pk_bf16_f32 v16, v20, v16
	v_cvt_pk_bf16_f32 v17, v17, v18
	v_cvt_pk_bf16_f32 v18, v32, v21
	v_cvt_pk_bf16_f32 v19, v22, v19
	global_store_dwordx4 v[36:37], v[16:19], off offset:256
	global_load_dword v22, v[140:141], off offset:704
	s_nop 0
	global_load_dwordx4 v[16:19], v[30:31], off
	global_load_dwordx4 v[224:227], v[30:31], off offset:256
	v_lshl_add_u64 v[20:21], s[24:25], 0, v[28:29]
	s_waitcnt vmcnt(0)
	v_mul_f32_e32 v22, 0xbfb8aa3b, v22
	v_mul_f32_e32 v12, v12, v22
	v_mul_f32_e32 v8, v8, v22
	v_mul_f32_e32 v13, v13, v22
	v_mul_f32_e32 v9, v9, v22
	v_mul_f32_e32 v14, v14, v22
	v_mul_f32_e32 v10, v10, v22
	v_mul_f32_e32 v15, v15, v22
	v_mul_f32_e32 v11, v11, v22
	v_exp_f32_e32 v12, v12
	v_exp_f32_e32 v8, v8
	v_exp_f32_e32 v13, v13
	v_exp_f32_e32 v9, v9
	v_exp_f32_e32 v14, v14
	v_exp_f32_e32 v10, v10
	v_exp_f32_e32 v15, v15
	v_exp_f32_e32 v11, v11
	v_add_f32_e32 v12, 1.0, v12
	v_add_f32_e32 v8, 1.0, v8
	v_add_f32_e32 v13, 1.0, v13
	v_add_f32_e32 v9, 1.0, v9
	v_add_f32_e32 v14, 1.0, v14
	v_add_f32_e32 v10, 1.0, v10
	v_add_f32_e32 v15, 1.0, v15
	v_add_f32_e32 v11, 1.0, v11
	v_rcp_f32_e32 v12, v12
	v_rcp_f32_e32 v8, v8
	v_rcp_f32_e32 v13, v13
	v_rcp_f32_e32 v9, v9
	v_rcp_f32_e32 v14, v14
	v_rcp_f32_e32 v10, v10
	v_rcp_f32_e32 v15, v15
	v_rcp_f32_e32 v11, v11
	v_lshlrev_b32_e32 v23, 16, v16
	v_and_b32_e32 v16, 0xffff0000, v16
	v_lshlrev_b32_e32 v24, 16, v17
	v_and_b32_e32 v17, 0xffff0000, v17
	v_lshlrev_b32_e32 v25, 16, v18
	v_and_b32_e32 v18, 0xffff0000, v18
	v_lshlrev_b32_e32 v26, 16, v19
	v_and_b32_e32 v19, 0xffff0000, v19
	v_mul_f32_e32 v12, v12, v23
	v_mul_f32_e32 v23, v8, v25
	v_mul_f32_e32 v8, v13, v16
	v_mul_f32_e32 v13, v9, v18
	v_mul_f32_e32 v9, v14, v24
	v_mul_f32_e32 v14, v10, v26
	v_mul_f32_e32 v10, v15, v17
	v_mul_f32_e32 v11, v11, v19
	v_cvt_pk_bf16_f32 v8, v12, v8
	v_cvt_pk_bf16_f32 v9, v9, v10
	v_cvt_pk_bf16_f32 v10, v23, v13
	v_cvt_pk_bf16_f32 v11, v14, v11
	global_store_dwordx4 v[20:21], v[8:11], off
	v_mul_f32_e32 v4, v4, v22
	v_mul_f32_e32 v0, v0, v22
	v_mul_f32_e32 v5, v5, v22
	v_mul_f32_e32 v1, v1, v22
	v_mul_f32_e32 v6, v6, v22
	v_mul_f32_e32 v2, v2, v22
	v_mul_f32_e32 v7, v7, v22
	v_mul_f32_e32 v3, v3, v22
	v_exp_f32_e32 v4, v4
	v_exp_f32_e32 v0, v0
	v_exp_f32_e32 v5, v5
	v_exp_f32_e32 v1, v1
	v_exp_f32_e32 v6, v6
	v_exp_f32_e32 v2, v2
	v_exp_f32_e32 v7, v7
	v_exp_f32_e32 v3, v3
	v_add_f32_e32 v4, 1.0, v4
	v_add_f32_e32 v0, 1.0, v0
	v_add_f32_e32 v5, 1.0, v5
	v_add_f32_e32 v1, 1.0, v1
	v_add_f32_e32 v6, 1.0, v6
	v_add_f32_e32 v2, 1.0, v2
	v_add_f32_e32 v7, 1.0, v7
	v_add_f32_e32 v3, 1.0, v3
	v_rcp_f32_e32 v4, v4
	v_rcp_f32_e32 v0, v0
	v_rcp_f32_e32 v5, v5
	v_rcp_f32_e32 v1, v1
	v_rcp_f32_e32 v6, v6
	v_rcp_f32_e32 v2, v2
	v_rcp_f32_e32 v7, v7
	v_rcp_f32_e32 v3, v3
	v_lshlrev_b32_e32 v12, 16, v224
	v_and_b32_e32 v8, 0xffff0000, v224
	v_lshlrev_b32_e32 v13, 16, v225
	v_and_b32_e32 v9, 0xffff0000, v225
	v_lshlrev_b32_e32 v14, 16, v226
	v_and_b32_e32 v10, 0xffff0000, v226
	v_lshlrev_b32_e32 v15, 16, v227
	v_and_b32_e32 v11, 0xffff0000, v227
	v_mul_f32_e32 v4, v4, v12
	v_mul_f32_e32 v12, v0, v14
	v_mul_f32_e32 v0, v5, v8
	v_mul_f32_e32 v5, v1, v10
	v_mul_f32_e32 v1, v6, v13
	v_mul_f32_e32 v6, v2, v15
	v_mul_f32_e32 v2, v7, v9
	v_mul_f32_e32 v3, v3, v11
	v_cvt_pk_bf16_f32 v0, v4, v0
	v_cvt_pk_bf16_f32 v1, v1, v2
	v_cvt_pk_bf16_f32 v2, v12, v5
	v_cvt_pk_bf16_f32 v3, v6, v3
	global_store_dwordx4 v[20:21], v[0:3], off offset:256
	s_cbranch_vccz .LBB0_996
	s_waitcnt vmcnt(0)
	s_cmpk_gt_u32 s10, 0xff
	s_cbranch_scc1 .LBB0_1003
	s_barrier
